# code placement: the 12 GEMM K-loop heads pinned to 64-byte boundaries (pad after the peel's unconditional branch, never executed)
# speedup vs baseline: 1.0156x; 1.0156x over previous
.Lpeel_327:
	ds_read_b128 v[128:131], v177
	ds_read_b128 v[132:135], v177 offset:1024
	ds_read_b128 v[136:139], v177 offset:2048
	ds_read_b128 v[140:143], v177 offset:3072
	ds_read_b128 v[160:163], v178
	ds_read_b128 v[164:167], v178 offset:1024
	ds_read_b128 v[168:171], v178 offset:2048
	ds_read_b128 v[180:183], v178 offset:3072
	s_add_i32 s87, s40, 2
	s_add_u32 s41, s38, 0xfffc0080
	s_addc_u32 s42, s39, -1
	s_cmp_eq_u32 s57, s40
	s_cselect_b32 s40, s84, s85
	s_cselect_b32 s43, s81, s42
	s_cselect_b32 s42, s82, s41
	s_cselect_b32 s41, s83, s86
	s_add_i32 m0, s48, 0xc000
	ds_read_b128 v[184:187], v179
	ds_read_b128 v[188:191], v179 offset:1024
	ds_read_b128 v[192:195], v179 offset:2048
	ds_read_b128 v[196:199], v179 offset:3072
	ds_read_b128 v[202:205], v179 offset:4096
	ds_read_b128 v[206:209], v179 offset:5120
	ds_read_b128 v[210:213], v179 offset:6144
	ds_read_b128 v[214:217], v179 offset:7168
	global_load_lds_dwordx4 v152, s[38:39]
	s_add_i32 m0, s48, 0xe000
	s_nop 0
	global_load_lds_dwordx4 v154, s[38:39]
	s_waitcnt vmcnt(8)
	s_waitcnt lgkmcnt(0)
	s_setprio 1
	s_barrier
	v_mfma_f32_16x16x32_bf16 v[124:127], v[128:131], v[184:187], 0
	v_mfma_f32_16x16x32_bf16 v[120:123], v[136:139], v[184:187], 0
	v_mfma_f32_16x16x32_bf16 v[108:111], v[128:131], v[192:195], 0
	v_mfma_f32_16x16x32_bf16 v[104:107], v[136:139], v[192:195], 0
	v_mfma_f32_16x16x32_bf16 v[92:95], v[128:131], v[202:205], 0
	v_mfma_f32_16x16x32_bf16 v[88:91], v[136:139], v[202:205], 0
	v_mfma_f32_16x16x32_bf16 v[76:79], v[128:131], v[210:213], 0
	v_mfma_f32_16x16x32_bf16 v[72:75], v[136:139], v[210:213], 0
	v_mfma_f32_16x16x32_bf16 v[124:127], v[132:135], v[188:191], v[124:127]
	v_mfma_f32_16x16x32_bf16 v[120:123], v[140:143], v[188:191], v[120:123]
	v_mfma_f32_16x16x32_bf16 v[108:111], v[132:135], v[196:199], v[108:111]
	v_mfma_f32_16x16x32_bf16 v[104:107], v[140:143], v[196:199], v[104:107]
	v_mfma_f32_16x16x32_bf16 v[92:95], v[132:135], v[206:209], v[92:95]
	v_mfma_f32_16x16x32_bf16 v[88:91], v[140:143], v[206:209], v[88:91]
	v_mfma_f32_16x16x32_bf16 v[76:79], v[132:135], v[214:217], v[76:79]
	v_mfma_f32_16x16x32_bf16 v[72:75], v[140:143], v[214:217], v[72:75]
	v_mfma_f32_16x16x32_bf16 v[116:119], v[160:163], v[184:187], 0
	v_mfma_f32_16x16x32_bf16 v[112:115], v[168:171], v[184:187], 0
	v_mfma_f32_16x16x32_bf16 v[100:103], v[160:163], v[192:195], 0
	v_mfma_f32_16x16x32_bf16 v[96:99], v[168:171], v[192:195], 0
	v_mfma_f32_16x16x32_bf16 v[84:87], v[160:163], v[202:205], 0
	v_mfma_f32_16x16x32_bf16 v[80:83], v[168:171], v[202:205], 0
	v_mfma_f32_16x16x32_bf16 v[68:71], v[160:163], v[210:213], 0
	v_mfma_f32_16x16x32_bf16 v[64:67], v[168:171], v[210:213], 0
	v_mfma_f32_16x16x32_bf16 v[116:119], v[164:167], v[188:191], v[116:119]
	v_mfma_f32_16x16x32_bf16 v[112:115], v[180:183], v[188:191], v[112:115]
	v_mfma_f32_16x16x32_bf16 v[100:103], v[164:167], v[196:199], v[100:103]
	v_mfma_f32_16x16x32_bf16 v[96:99], v[180:183], v[196:199], v[96:99]
	v_mfma_f32_16x16x32_bf16 v[84:87], v[164:167], v[206:209], v[84:87]
	v_mfma_f32_16x16x32_bf16 v[80:83], v[180:183], v[206:209], v[80:83]
	v_mfma_f32_16x16x32_bf16 v[68:71], v[164:167], v[214:217], v[68:71]
	v_mfma_f32_16x16x32_bf16 v[64:67], v[180:183], v[214:217], v[64:67]
	s_barrier
	s_setprio 0
	s_add_i32 s88, s58, s33
	v_lshl_add_u64 v[172:173], s[40:41], 0, v[148:149]
	s_mov_b32 m0, s88
	ds_read_b128 v[184:187], v179 offset:16384
	ds_read_b128 v[188:191], v179 offset:17408
	ds_read_b128 v[192:195], v179 offset:18432
	ds_read_b128 v[196:199], v179 offset:19456
	ds_read_b128 v[202:205], v179 offset:20480
	ds_read_b128 v[206:209], v179 offset:21504
	ds_read_b128 v[210:213], v179 offset:22528
	ds_read_b128 v[214:217], v179 offset:23552
	global_load_lds_dwordx4 v[172:173], off
	s_add_i32 m0, s88, 0x2000
	s_add_u32 s88, s40, 0x40000
	v_lshl_add_u64 v[218:219], s[40:41], 0, v[144:145]
	s_addc_u32 s89, s41, 0
	s_add_i32 s90, s64, s33
	global_load_lds_dwordx4 v[218:219], off
	s_mov_b32 m0, s90
	v_lshl_add_u64 v[222:223], s[42:43], 0, v[146:147]
	global_load_lds_dwordx4 v148, s[88:89]
	s_add_i32 m0, s90, 0x2000
	s_nop 0
	global_load_lds_dwordx4 v144, s[88:89]
	v_lshl_add_u64 v[220:221], s[42:43], 0, v[150:151]
	s_mov_b32 m0, s48
	s_nop 0
	global_load_lds_dwordx4 v[220:221], off
	s_mov_b32 m0, s49
	s_nop 0
	global_load_lds_dwordx4 v[222:223], off
	s_waitcnt vmcnt(8)
	s_waitcnt lgkmcnt(0)
	s_setprio 1
	s_barrier
	v_mfma_f32_16x16x32_bf16 v[60:63], v[128:131], v[184:187], 0
	v_mfma_f32_16x16x32_bf16 v[56:59], v[136:139], v[184:187], 0
	v_mfma_f32_16x16x32_bf16 v[44:47], v[128:131], v[192:195], 0
	v_mfma_f32_16x16x32_bf16 v[40:43], v[136:139], v[192:195], 0
	v_mfma_f32_16x16x32_bf16 v[28:31], v[128:131], v[202:205], 0
	v_mfma_f32_16x16x32_bf16 v[24:27], v[136:139], v[202:205], 0
	v_mfma_f32_16x16x32_bf16 v[12:15], v[128:131], v[210:213], 0
	v_mfma_f32_16x16x32_bf16 v[8:11], v[136:139], v[210:213], 0
	v_mfma_f32_16x16x32_bf16 v[60:63], v[132:135], v[188:191], v[60:63]
	v_mfma_f32_16x16x32_bf16 v[56:59], v[140:143], v[188:191], v[56:59]
	v_mfma_f32_16x16x32_bf16 v[44:47], v[132:135], v[196:199], v[44:47]
	v_mfma_f32_16x16x32_bf16 v[40:43], v[140:143], v[196:199], v[40:43]
	v_mfma_f32_16x16x32_bf16 v[28:31], v[132:135], v[206:209], v[28:31]
	v_mfma_f32_16x16x32_bf16 v[24:27], v[140:143], v[206:209], v[24:27]
	v_mfma_f32_16x16x32_bf16 v[12:15], v[132:135], v[214:217], v[12:15]
	v_mfma_f32_16x16x32_bf16 v[8:11], v[140:143], v[214:217], v[8:11]
	v_mfma_f32_16x16x32_bf16 v[52:55], v[160:163], v[184:187], 0
	v_mfma_f32_16x16x32_bf16 v[48:51], v[168:171], v[184:187], 0
	v_mfma_f32_16x16x32_bf16 v[36:39], v[160:163], v[192:195], 0
	v_mfma_f32_16x16x32_bf16 v[32:35], v[168:171], v[192:195], 0
	v_mfma_f32_16x16x32_bf16 v[20:23], v[160:163], v[202:205], 0
	v_mfma_f32_16x16x32_bf16 v[16:19], v[168:171], v[202:205], 0
	v_mfma_f32_16x16x32_bf16 v[4:7], v[160:163], v[210:213], 0
	v_mfma_f32_16x16x32_bf16 v[0:3], v[168:171], v[210:213], 0
	v_mfma_f32_16x16x32_bf16 v[52:55], v[164:167], v[188:191], v[52:55]
	v_mfma_f32_16x16x32_bf16 v[48:51], v[180:183], v[188:191], v[48:51]
	v_mfma_f32_16x16x32_bf16 v[36:39], v[164:167], v[196:199], v[36:39]
	v_mfma_f32_16x16x32_bf16 v[32:35], v[180:183], v[196:199], v[32:35]
	v_mfma_f32_16x16x32_bf16 v[20:23], v[164:167], v[206:209], v[20:23]
	v_mfma_f32_16x16x32_bf16 v[16:19], v[180:183], v[206:209], v[16:19]
	v_mfma_f32_16x16x32_bf16 v[4:7], v[164:167], v[214:217], v[4:7]
	v_mfma_f32_16x16x32_bf16 v[0:3], v[180:183], v[214:217], v[0:3]
	s_barrier
	s_setprio 0
	s_add_i32 s88, 0, 0x18000
	s_add_i32 s89, 0, 0x1c000
	v_add_u32_e32 v140, s88, v175
	v_add_u32_e32 v180, s89, v175
	ds_read_b128 v[128:131], v140
	ds_read_b128 v[132:135], v140 offset:1024
	ds_read_b128 v[136:139], v140 offset:2048
	ds_read_b128 v[140:143], v140 offset:3072
	ds_read_b128 v[160:163], v180
	ds_read_b128 v[164:167], v180 offset:1024
	ds_read_b128 v[168:171], v180 offset:2048
	ds_read_b128 v[180:183], v180 offset:3072
	s_add_u32 s42, s42, 0x40000
	s_addc_u32 s43, s43, 0
	s_mov_b32 m0, s50
	ds_read_b128 v[184:187], v179 offset:32768
	ds_read_b128 v[188:191], v179 offset:33792
	ds_read_b128 v[192:195], v179 offset:34816
	ds_read_b128 v[196:199], v179 offset:35840
	ds_read_b128 v[202:205], v179 offset:36864
	ds_read_b128 v[206:209], v179 offset:37888
	ds_read_b128 v[210:213], v179 offset:38912
	ds_read_b128 v[214:217], v179 offset:39936
	global_load_lds_dwordx4 v150, s[42:43]
	s_mov_b32 m0, s51
	s_nop 0
	global_load_lds_dwordx4 v146, s[42:43]
	s_waitcnt vmcnt(8)
	s_waitcnt lgkmcnt(0)
	s_setprio 1
	s_barrier
	v_mfma_f32_16x16x32_bf16 v[124:127], v[128:131], v[184:187], v[124:127]
	v_mfma_f32_16x16x32_bf16 v[120:123], v[136:139], v[184:187], v[120:123]
	v_mfma_f32_16x16x32_bf16 v[108:111], v[128:131], v[192:195], v[108:111]
	v_mfma_f32_16x16x32_bf16 v[104:107], v[136:139], v[192:195], v[104:107]
	v_mfma_f32_16x16x32_bf16 v[92:95], v[128:131], v[202:205], v[92:95]
	v_mfma_f32_16x16x32_bf16 v[88:91], v[136:139], v[202:205], v[88:91]
	v_mfma_f32_16x16x32_bf16 v[76:79], v[128:131], v[210:213], v[76:79]
	v_mfma_f32_16x16x32_bf16 v[72:75], v[136:139], v[210:213], v[72:75]
	v_mfma_f32_16x16x32_bf16 v[124:127], v[132:135], v[188:191], v[124:127]
	v_mfma_f32_16x16x32_bf16 v[120:123], v[140:143], v[188:191], v[120:123]
	v_mfma_f32_16x16x32_bf16 v[108:111], v[132:135], v[196:199], v[108:111]
	v_mfma_f32_16x16x32_bf16 v[104:107], v[140:143], v[196:199], v[104:107]
	v_mfma_f32_16x16x32_bf16 v[92:95], v[132:135], v[206:209], v[92:95]
	v_mfma_f32_16x16x32_bf16 v[88:91], v[140:143], v[206:209], v[88:91]
	v_mfma_f32_16x16x32_bf16 v[76:79], v[132:135], v[214:217], v[76:79]
	v_mfma_f32_16x16x32_bf16 v[72:75], v[140:143], v[214:217], v[72:75]
	v_mfma_f32_16x16x32_bf16 v[116:119], v[160:163], v[184:187], v[116:119]
	v_mfma_f32_16x16x32_bf16 v[112:115], v[168:171], v[184:187], v[112:115]
	v_mfma_f32_16x16x32_bf16 v[100:103], v[160:163], v[192:195], v[100:103]
	v_mfma_f32_16x16x32_bf16 v[96:99], v[168:171], v[192:195], v[96:99]
	v_mfma_f32_16x16x32_bf16 v[84:87], v[160:163], v[202:205], v[84:87]
	v_mfma_f32_16x16x32_bf16 v[80:83], v[168:171], v[202:205], v[80:83]
	v_mfma_f32_16x16x32_bf16 v[68:71], v[160:163], v[210:213], v[68:71]
	v_mfma_f32_16x16x32_bf16 v[64:67], v[168:171], v[210:213], v[64:67]
	v_mfma_f32_16x16x32_bf16 v[116:119], v[164:167], v[188:191], v[116:119]
	v_mfma_f32_16x16x32_bf16 v[112:115], v[180:183], v[188:191], v[112:115]
	v_mfma_f32_16x16x32_bf16 v[100:103], v[164:167], v[196:199], v[100:103]
	v_mfma_f32_16x16x32_bf16 v[96:99], v[180:183], v[196:199], v[96:99]
	v_mfma_f32_16x16x32_bf16 v[84:87], v[164:167], v[206:209], v[84:87]
	v_mfma_f32_16x16x32_bf16 v[80:83], v[180:183], v[206:209], v[80:83]
	v_mfma_f32_16x16x32_bf16 v[68:71], v[164:167], v[214:217], v[68:71]
	v_mfma_f32_16x16x32_bf16 v[64:67], v[180:183], v[214:217], v[64:67]
	s_barrier
	s_setprio 0
	s_add_i32 s42, s88, s33
	v_lshl_add_u64 v[172:173], v[172:173], 0, s[10:11]
	s_mov_b32 m0, s42
	ds_read_b128 v[184:187], v179 offset:49152
	ds_read_b128 v[188:191], v179 offset:50176
	ds_read_b128 v[192:195], v179 offset:51200
	ds_read_b128 v[196:199], v179 offset:52224
	ds_read_b128 v[202:205], v179 offset:53248
	ds_read_b128 v[206:209], v179 offset:54272
	ds_read_b128 v[210:213], v179 offset:55296
	ds_read_b128 v[214:217], v179 offset:56320
	global_load_lds_dwordx4 v[172:173], off
	s_add_i32 m0, s42, 0x2000
	s_add_u32 s40, s40, 0x40080
	v_lshl_add_u64 v[172:173], v[218:219], 0, s[10:11]
	s_addc_u32 s41, s41, 0
	s_add_i32 s42, s89, s33
	global_load_lds_dwordx4 v[172:173], off
	s_mov_b32 m0, s42
	s_nop 0
	global_load_lds_dwordx4 v148, s[40:41]
	s_add_i32 m0, s42, 0x2000
	s_nop 0
	global_load_lds_dwordx4 v144, s[40:41]
	v_lshl_add_u64 v[172:173], v[220:221], 0, s[10:11]
	s_mov_b32 m0, s55
	s_nop 0
	global_load_lds_dwordx4 v[172:173], off
	v_lshl_add_u64 v[172:173], v[222:223], 0, s[10:11]
	s_mov_b32 m0, s56
	s_nop 0
	global_load_lds_dwordx4 v[172:173], off
	s_waitcnt vmcnt(8)
	s_waitcnt lgkmcnt(0)
	s_setprio 1
	s_barrier
	v_mfma_f32_16x16x32_bf16 v[60:63], v[128:131], v[184:187], v[60:63]
	v_mfma_f32_16x16x32_bf16 v[56:59], v[136:139], v[184:187], v[56:59]
	v_mfma_f32_16x16x32_bf16 v[44:47], v[128:131], v[192:195], v[44:47]
	v_mfma_f32_16x16x32_bf16 v[40:43], v[136:139], v[192:195], v[40:43]
	v_mfma_f32_16x16x32_bf16 v[28:31], v[128:131], v[202:205], v[28:31]
	v_mfma_f32_16x16x32_bf16 v[24:27], v[136:139], v[202:205], v[24:27]
	v_mfma_f32_16x16x32_bf16 v[12:15], v[128:131], v[210:213], v[12:15]
	v_mfma_f32_16x16x32_bf16 v[8:11], v[136:139], v[210:213], v[8:11]
	v_mfma_f32_16x16x32_bf16 v[60:63], v[132:135], v[188:191], v[60:63]
	v_mfma_f32_16x16x32_bf16 v[56:59], v[140:143], v[188:191], v[56:59]
	v_mfma_f32_16x16x32_bf16 v[44:47], v[132:135], v[196:199], v[44:47]
	v_mfma_f32_16x16x32_bf16 v[40:43], v[140:143], v[196:199], v[40:43]
	v_mfma_f32_16x16x32_bf16 v[28:31], v[132:135], v[206:209], v[28:31]
	v_mfma_f32_16x16x32_bf16 v[24:27], v[140:143], v[206:209], v[24:27]
	v_mfma_f32_16x16x32_bf16 v[12:15], v[132:135], v[214:217], v[12:15]
	v_mfma_f32_16x16x32_bf16 v[8:11], v[140:143], v[214:217], v[8:11]
	v_mfma_f32_16x16x32_bf16 v[52:55], v[160:163], v[184:187], v[52:55]
	v_mfma_f32_16x16x32_bf16 v[48:51], v[168:171], v[184:187], v[48:51]
	v_mfma_f32_16x16x32_bf16 v[36:39], v[160:163], v[192:195], v[36:39]
	v_mfma_f32_16x16x32_bf16 v[32:35], v[168:171], v[192:195], v[32:35]
	v_mfma_f32_16x16x32_bf16 v[20:23], v[160:163], v[202:205], v[20:23]
	v_mfma_f32_16x16x32_bf16 v[16:19], v[168:171], v[202:205], v[16:19]
	v_mfma_f32_16x16x32_bf16 v[4:7], v[160:163], v[210:213], v[4:7]
	v_mfma_f32_16x16x32_bf16 v[0:3], v[168:171], v[210:213], v[0:3]
	v_mfma_f32_16x16x32_bf16 v[52:55], v[164:167], v[188:191], v[52:55]
	v_mfma_f32_16x16x32_bf16 v[48:51], v[180:183], v[188:191], v[48:51]
	v_mfma_f32_16x16x32_bf16 v[36:39], v[164:167], v[196:199], v[36:39]
	v_mfma_f32_16x16x32_bf16 v[32:35], v[180:183], v[196:199], v[32:35]
	v_mfma_f32_16x16x32_bf16 v[20:23], v[164:167], v[206:209], v[20:23]
	v_mfma_f32_16x16x32_bf16 v[16:19], v[180:183], v[206:209], v[16:19]
	v_mfma_f32_16x16x32_bf16 v[4:7], v[164:167], v[214:217], v[4:7]
	v_mfma_f32_16x16x32_bf16 v[0:3], v[180:183], v[214:217], v[0:3]
	s_barrier
	s_setprio 0
	s_add_u32 s38, s38, 0x100
	s_addc_u32 s39, s39, 0
	s_add_u32 s85, s85, 0x100
	s_addc_u32 s86, s86, 0
	s_cmp_ge_i32 s87, s26
	s_mov_b32 s40, s87
	s_cbranch_scc0 .LBB7_327
	s_branch .Lpeelx_327
	.p2align	6

.Lswi_nobar:
.Lpeel_357:
	s_add_i32 s86, s42, 2
	s_add_u32 s29, s16, 0xfffc0080
	s_addc_u32 s37, s17, -1
	s_add_i32 s74, 0, 0x10000
	s_cmp_eq_u32 s20, s42
	s_cselect_b32 s73, s9, s37
	s_cselect_b32 s72, s13, s29
	v_add_u32_e32 v170, s74, v179
	s_cselect_b32 s43, s28, s57
	s_cselect_b32 s42, s39, s56
	s_add_i32 s29, 0, 0x14000
	ds_read_b128 v[130:133], v170
	ds_read_b128 v[180:183], v170 offset:1024
	ds_read_b128 v[184:187], v170 offset:2048
	ds_read_b128 v[188:191], v170 offset:3072
	v_add_u32_e32 v170, s29, v179
	ds_read_b128 v[192:195], v170
	ds_read_b128 v[196:199], v170 offset:1024
	ds_read_b128 v[204:207], v170 offset:2048
	ds_read_b128 v[208:211], v170 offset:3072
	s_add_i32 m0, s4, 0xc000
	ds_read_b128 v[212:215], v143
	ds_read_b128 v[216:219], v143 offset:1024
	ds_read_b128 v[220:223], v143 offset:2048
	ds_read_b128 v[224:227], v143 offset:3072
	ds_read_b128 v[228:231], v143 offset:4096
	ds_read_b128 v[232:235], v143 offset:5120
	ds_read_b128 v[236:239], v143 offset:6144
	ds_read_b128 v[240:243], v143 offset:7168
	global_load_lds_dwordx4 v174, s[16:17]
	s_add_i32 m0, s4, 0xe000
	s_nop 0
	global_load_lds_dwordx4 v176, s[16:17]
	s_waitcnt vmcnt(8)
	s_waitcnt lgkmcnt(0)
	s_setprio 1
	s_barrier
	v_mfma_f32_16x16x32_bf16 v[126:129], v[130:133], v[212:215], 0
	v_mfma_f32_16x16x32_bf16 v[118:121], v[184:187], v[212:215], 0
	v_mfma_f32_16x16x32_bf16 v[110:113], v[130:133], v[220:223], 0
	v_mfma_f32_16x16x32_bf16 v[102:105], v[184:187], v[220:223], 0
	v_mfma_f32_16x16x32_bf16 v[94:97], v[130:133], v[228:231], 0
	v_mfma_f32_16x16x32_bf16 v[86:89], v[184:187], v[228:231], 0
	v_mfma_f32_16x16x32_bf16 v[78:81], v[130:133], v[236:239], 0
	v_mfma_f32_16x16x32_bf16 v[70:73], v[184:187], v[236:239], 0
	v_mfma_f32_16x16x32_bf16 v[126:129], v[180:183], v[216:219], v[126:129]
	v_mfma_f32_16x16x32_bf16 v[118:121], v[188:191], v[216:219], v[118:121]
	v_mfma_f32_16x16x32_bf16 v[110:113], v[180:183], v[224:227], v[110:113]
	v_mfma_f32_16x16x32_bf16 v[102:105], v[188:191], v[224:227], v[102:105]
	v_mfma_f32_16x16x32_bf16 v[94:97], v[180:183], v[232:235], v[94:97]
	v_mfma_f32_16x16x32_bf16 v[86:89], v[188:191], v[232:235], v[86:89]
	v_mfma_f32_16x16x32_bf16 v[78:81], v[180:183], v[240:243], v[78:81]
	v_mfma_f32_16x16x32_bf16 v[70:73], v[188:191], v[240:243], v[70:73]
	v_mfma_f32_16x16x32_bf16 v[122:125], v[192:195], v[212:215], 0
	v_mfma_f32_16x16x32_bf16 v[114:117], v[204:207], v[212:215], 0
	v_mfma_f32_16x16x32_bf16 v[106:109], v[192:195], v[220:223], 0
	v_mfma_f32_16x16x32_bf16 v[98:101], v[204:207], v[220:223], 0
	v_mfma_f32_16x16x32_bf16 v[90:93], v[192:195], v[228:231], 0
	v_mfma_f32_16x16x32_bf16 v[82:85], v[204:207], v[228:231], 0
	v_mfma_f32_16x16x32_bf16 v[74:77], v[192:195], v[236:239], 0
	v_mfma_f32_16x16x32_bf16 v[66:69], v[204:207], v[236:239], 0
	v_mfma_f32_16x16x32_bf16 v[122:125], v[196:199], v[216:219], v[122:125]
	v_mfma_f32_16x16x32_bf16 v[114:117], v[208:211], v[216:219], v[114:117]
	v_mfma_f32_16x16x32_bf16 v[106:109], v[196:199], v[224:227], v[106:109]
	v_mfma_f32_16x16x32_bf16 v[98:101], v[208:211], v[224:227], v[98:101]
	v_mfma_f32_16x16x32_bf16 v[90:93], v[196:199], v[232:235], v[90:93]
	v_mfma_f32_16x16x32_bf16 v[82:85], v[208:211], v[232:235], v[82:85]
	v_mfma_f32_16x16x32_bf16 v[74:77], v[196:199], v[240:243], v[74:77]
	v_mfma_f32_16x16x32_bf16 v[66:69], v[208:211], v[240:243], v[66:69]
	s_barrier
	s_setprio 0
	s_add_i32 s37, s74, s84
	v_lshl_add_u64 v[244:245], s[42:43], 0, v[138:139]
	s_mov_b32 m0, s37
	ds_read_b128 v[212:215], v143 offset:16384
	ds_read_b128 v[216:219], v143 offset:17408
	ds_read_b128 v[220:223], v143 offset:18432
	ds_read_b128 v[224:227], v143 offset:19456
	ds_read_b128 v[228:231], v143 offset:20480
	ds_read_b128 v[232:235], v143 offset:21504
	ds_read_b128 v[236:239], v143 offset:22528
	ds_read_b128 v[240:243], v143 offset:23552
	global_load_lds_dwordx4 v[244:245], off
	s_add_i32 m0, s37, 0x2000
	s_add_u32 s74, s42, 0x40000
	v_lshl_add_u64 v[246:247], s[42:43], 0, v[134:135]
	s_addc_u32 s75, s43, 0
	s_add_i32 s29, s29, s84
	global_load_lds_dwordx4 v[246:247], off
	s_mov_b32 m0, s29
	v_lshl_add_u64 v[170:171], s[72:73], 0, v[136:137]
	global_load_lds_dwordx4 v138, s[74:75]
	s_add_i32 m0, s29, 0x2000
	s_nop 0
	global_load_lds_dwordx4 v134, s[74:75]
	v_lshl_add_u64 v[248:249], s[72:73], 0, v[140:141]
	s_mov_b32 m0, s4
	s_nop 0
	global_load_lds_dwordx4 v[248:249], off
	s_mov_b32 m0, s5
	s_nop 0
	global_load_lds_dwordx4 v[170:171], off
	s_lshl_b32 s101, s38, 14
	s_add_i32 s101, s101, s84
	s_add_u32 s100, s66, s101
	s_addc_u32 s101, s67, 0
	v_lshlrev_b32_e32 v172, 4, v163
	v_add_u32_e32 v173, 0x2000, v172
	s_add_i32 m0, s84, 0x20000
	s_nop 0
	global_load_lds_dwordx4 v172, s[100:101]
	s_add_i32 m0, s84, 0x22000
	s_nop 0
	global_load_lds_dwordx4 v173, s[100:101]
	s_waitcnt vmcnt(8)
	s_waitcnt lgkmcnt(0)
	s_setprio 1
	s_barrier
	v_mfma_f32_16x16x32_bf16 v[62:65], v[130:133], v[212:215], 0
	v_mfma_f32_16x16x32_bf16 v[54:57], v[184:187], v[212:215], 0
	v_mfma_f32_16x16x32_bf16 v[46:49], v[130:133], v[220:223], 0
	v_mfma_f32_16x16x32_bf16 v[38:41], v[184:187], v[220:223], 0
	v_mfma_f32_16x16x32_bf16 v[30:33], v[130:133], v[228:231], 0
	v_mfma_f32_16x16x32_bf16 v[22:25], v[184:187], v[228:231], 0
	v_mfma_f32_16x16x32_bf16 v[14:17], v[130:133], v[236:239], 0
	v_mfma_f32_16x16x32_bf16 v[6:9], v[184:187], v[236:239], 0
	v_mfma_f32_16x16x32_bf16 v[62:65], v[180:183], v[216:219], v[62:65]
	v_mfma_f32_16x16x32_bf16 v[54:57], v[188:191], v[216:219], v[54:57]
	v_mfma_f32_16x16x32_bf16 v[46:49], v[180:183], v[224:227], v[46:49]
	v_mfma_f32_16x16x32_bf16 v[38:41], v[188:191], v[224:227], v[38:41]
	v_mfma_f32_16x16x32_bf16 v[30:33], v[180:183], v[232:235], v[30:33]
	v_mfma_f32_16x16x32_bf16 v[22:25], v[188:191], v[232:235], v[22:25]
	v_mfma_f32_16x16x32_bf16 v[14:17], v[180:183], v[240:243], v[14:17]
	v_mfma_f32_16x16x32_bf16 v[6:9], v[188:191], v[240:243], v[6:9]
	v_mfma_f32_16x16x32_bf16 v[58:61], v[192:195], v[212:215], 0
	v_mfma_f32_16x16x32_bf16 v[50:53], v[204:207], v[212:215], 0
	v_mfma_f32_16x16x32_bf16 v[42:45], v[192:195], v[220:223], 0
	v_mfma_f32_16x16x32_bf16 v[34:37], v[204:207], v[220:223], 0
	v_mfma_f32_16x16x32_bf16 v[26:29], v[192:195], v[228:231], 0
	v_mfma_f32_16x16x32_bf16 v[18:21], v[204:207], v[228:231], 0
	v_mfma_f32_16x16x32_bf16 v[10:13], v[192:195], v[236:239], 0
	v_mfma_f32_16x16x32_bf16 v[2:5], v[204:207], v[236:239], 0
	v_mfma_f32_16x16x32_bf16 v[58:61], v[196:199], v[216:219], v[58:61]
	v_mfma_f32_16x16x32_bf16 v[50:53], v[208:211], v[216:219], v[50:53]
	v_mfma_f32_16x16x32_bf16 v[42:45], v[196:199], v[224:227], v[42:45]
	v_mfma_f32_16x16x32_bf16 v[34:37], v[208:211], v[224:227], v[34:37]
	v_mfma_f32_16x16x32_bf16 v[26:29], v[196:199], v[232:235], v[26:29]
	v_mfma_f32_16x16x32_bf16 v[18:21], v[208:211], v[232:235], v[18:21]
	v_mfma_f32_16x16x32_bf16 v[10:13], v[196:199], v[240:243], v[10:13]
	v_mfma_f32_16x16x32_bf16 v[2:5], v[208:211], v[240:243], v[2:5]
	s_barrier
	s_setprio 0
	s_add_i32 s29, 0, 0x18000
	v_add_u32_e32 v172, s29, v179
	s_add_i32 s37, 0, 0x1c000
	ds_read_b128 v[130:133], v172
	ds_read_b128 v[180:183], v172 offset:1024
	ds_read_b128 v[184:187], v172 offset:2048
	ds_read_b128 v[188:191], v172 offset:3072
	v_add_u32_e32 v172, s37, v179
	ds_read_b128 v[192:195], v172
	ds_read_b128 v[196:199], v172 offset:1024
	ds_read_b128 v[204:207], v172 offset:2048
	ds_read_b128 v[208:211], v172 offset:3072
	s_add_u32 s72, s72, 0x40000
	s_addc_u32 s73, s73, 0
	s_mov_b32 m0, s93
	ds_read_b128 v[212:215], v143 offset:32768
	ds_read_b128 v[216:219], v143 offset:33792
	ds_read_b128 v[220:223], v143 offset:34816
	ds_read_b128 v[224:227], v143 offset:35840
	ds_read_b128 v[228:231], v143 offset:36864
	ds_read_b128 v[232:235], v143 offset:37888
	ds_read_b128 v[236:239], v143 offset:38912
	ds_read_b128 v[240:243], v143 offset:39936
	global_load_lds_dwordx4 v140, s[72:73]
	s_mov_b32 m0, s33
	s_nop 0
	global_load_lds_dwordx4 v136, s[72:73]
	s_waitcnt vmcnt(8)
	s_waitcnt lgkmcnt(0)
	s_setprio 1
	s_barrier
	v_mfma_f32_16x16x32_bf16 v[126:129], v[130:133], v[212:215], v[126:129]
	v_mfma_f32_16x16x32_bf16 v[118:121], v[184:187], v[212:215], v[118:121]
	v_mfma_f32_16x16x32_bf16 v[110:113], v[130:133], v[220:223], v[110:113]
	v_mfma_f32_16x16x32_bf16 v[102:105], v[184:187], v[220:223], v[102:105]
	v_mfma_f32_16x16x32_bf16 v[94:97], v[130:133], v[228:231], v[94:97]
	v_mfma_f32_16x16x32_bf16 v[86:89], v[184:187], v[228:231], v[86:89]
	v_mfma_f32_16x16x32_bf16 v[78:81], v[130:133], v[236:239], v[78:81]
	v_mfma_f32_16x16x32_bf16 v[70:73], v[184:187], v[236:239], v[70:73]
	v_mfma_f32_16x16x32_bf16 v[126:129], v[180:183], v[216:219], v[126:129]
	v_mfma_f32_16x16x32_bf16 v[118:121], v[188:191], v[216:219], v[118:121]
	v_mfma_f32_16x16x32_bf16 v[110:113], v[180:183], v[224:227], v[110:113]
	v_mfma_f32_16x16x32_bf16 v[102:105], v[188:191], v[224:227], v[102:105]
	v_mfma_f32_16x16x32_bf16 v[94:97], v[180:183], v[232:235], v[94:97]
	v_mfma_f32_16x16x32_bf16 v[86:89], v[188:191], v[232:235], v[86:89]
	v_mfma_f32_16x16x32_bf16 v[78:81], v[180:183], v[240:243], v[78:81]
	v_mfma_f32_16x16x32_bf16 v[70:73], v[188:191], v[240:243], v[70:73]
	v_mfma_f32_16x16x32_bf16 v[122:125], v[192:195], v[212:215], v[122:125]
	v_mfma_f32_16x16x32_bf16 v[114:117], v[204:207], v[212:215], v[114:117]
	v_mfma_f32_16x16x32_bf16 v[106:109], v[192:195], v[220:223], v[106:109]
	v_mfma_f32_16x16x32_bf16 v[98:101], v[204:207], v[220:223], v[98:101]
	v_mfma_f32_16x16x32_bf16 v[90:93], v[192:195], v[228:231], v[90:93]
	v_mfma_f32_16x16x32_bf16 v[82:85], v[204:207], v[228:231], v[82:85]
	v_mfma_f32_16x16x32_bf16 v[74:77], v[192:195], v[236:239], v[74:77]
	v_mfma_f32_16x16x32_bf16 v[66:69], v[204:207], v[236:239], v[66:69]
	v_mfma_f32_16x16x32_bf16 v[122:125], v[196:199], v[216:219], v[122:125]
	v_mfma_f32_16x16x32_bf16 v[114:117], v[208:211], v[216:219], v[114:117]
	v_mfma_f32_16x16x32_bf16 v[106:109], v[196:199], v[224:227], v[106:109]
	v_mfma_f32_16x16x32_bf16 v[98:101], v[208:211], v[224:227], v[98:101]
	v_mfma_f32_16x16x32_bf16 v[90:93], v[196:199], v[232:235], v[90:93]
	v_mfma_f32_16x16x32_bf16 v[82:85], v[208:211], v[232:235], v[82:85]
	v_mfma_f32_16x16x32_bf16 v[74:77], v[196:199], v[240:243], v[74:77]
	v_mfma_f32_16x16x32_bf16 v[66:69], v[208:211], v[240:243], v[66:69]
	s_barrier
	s_setprio 0
	s_add_i32 s29, s29, s84
	v_lshl_add_u64 v[172:173], v[244:245], 0, s[24:25]
	s_mov_b32 m0, s29
	ds_read_b128 v[212:215], v143 offset:49152
	ds_read_b128 v[216:219], v143 offset:50176
	ds_read_b128 v[220:223], v143 offset:51200
	ds_read_b128 v[224:227], v143 offset:52224
	ds_read_b128 v[228:231], v143 offset:53248
	ds_read_b128 v[232:235], v143 offset:54272
	ds_read_b128 v[236:239], v143 offset:55296
	ds_read_b128 v[240:243], v143 offset:56320
	global_load_lds_dwordx4 v[172:173], off
	s_add_i32 m0, s29, 0x2000
	s_add_u32 s42, s42, 0x40080
	v_lshl_add_u64 v[172:173], v[246:247], 0, s[24:25]
	s_addc_u32 s43, s43, 0
	s_add_i32 s29, s37, s84
	global_load_lds_dwordx4 v[172:173], off
	s_mov_b32 m0, s29
	v_lshl_add_u64 v[170:171], v[170:171], 0, s[24:25]
	global_load_lds_dwordx4 v138, s[42:43]
	s_add_i32 m0, s29, 0x2000
	s_nop 0
	global_load_lds_dwordx4 v134, s[42:43]
	v_lshl_add_u64 v[172:173], v[248:249], 0, s[24:25]
	s_mov_b32 m0, s97
	s_nop 0
	global_load_lds_dwordx4 v[172:173], off
	s_mov_b32 m0, s3
	s_nop 0
	global_load_lds_dwordx4 v[170:171], off
	s_waitcnt vmcnt(8)
	s_waitcnt lgkmcnt(0)
	s_setprio 1
	s_barrier
	v_mfma_f32_16x16x32_bf16 v[62:65], v[130:133], v[212:215], v[62:65]
	v_mfma_f32_16x16x32_bf16 v[54:57], v[184:187], v[212:215], v[54:57]
	v_mfma_f32_16x16x32_bf16 v[46:49], v[130:133], v[220:223], v[46:49]
	v_mfma_f32_16x16x32_bf16 v[38:41], v[184:187], v[220:223], v[38:41]
	v_mfma_f32_16x16x32_bf16 v[30:33], v[130:133], v[228:231], v[30:33]
	v_mfma_f32_16x16x32_bf16 v[22:25], v[184:187], v[228:231], v[22:25]
	v_mfma_f32_16x16x32_bf16 v[14:17], v[130:133], v[236:239], v[14:17]
	v_mfma_f32_16x16x32_bf16 v[6:9], v[184:187], v[236:239], v[6:9]
	v_mfma_f32_16x16x32_bf16 v[62:65], v[180:183], v[216:219], v[62:65]
	v_mfma_f32_16x16x32_bf16 v[54:57], v[188:191], v[216:219], v[54:57]
	v_mfma_f32_16x16x32_bf16 v[46:49], v[180:183], v[224:227], v[46:49]
	v_mfma_f32_16x16x32_bf16 v[38:41], v[188:191], v[224:227], v[38:41]
	v_mfma_f32_16x16x32_bf16 v[30:33], v[180:183], v[232:235], v[30:33]
	v_mfma_f32_16x16x32_bf16 v[22:25], v[188:191], v[232:235], v[22:25]
	v_mfma_f32_16x16x32_bf16 v[14:17], v[180:183], v[240:243], v[14:17]
	v_mfma_f32_16x16x32_bf16 v[6:9], v[188:191], v[240:243], v[6:9]
	v_mfma_f32_16x16x32_bf16 v[58:61], v[192:195], v[212:215], v[58:61]
	v_mfma_f32_16x16x32_bf16 v[50:53], v[204:207], v[212:215], v[50:53]
	v_mfma_f32_16x16x32_bf16 v[42:45], v[192:195], v[220:223], v[42:45]
	v_mfma_f32_16x16x32_bf16 v[34:37], v[204:207], v[220:223], v[34:37]
	v_mfma_f32_16x16x32_bf16 v[26:29], v[192:195], v[228:231], v[26:29]
	v_mfma_f32_16x16x32_bf16 v[18:21], v[204:207], v[228:231], v[18:21]
	v_mfma_f32_16x16x32_bf16 v[10:13], v[192:195], v[236:239], v[10:13]
	v_mfma_f32_16x16x32_bf16 v[2:5], v[204:207], v[236:239], v[2:5]
	v_mfma_f32_16x16x32_bf16 v[58:61], v[196:199], v[216:219], v[58:61]
	v_mfma_f32_16x16x32_bf16 v[50:53], v[208:211], v[216:219], v[50:53]
	v_mfma_f32_16x16x32_bf16 v[42:45], v[196:199], v[224:227], v[42:45]
	v_mfma_f32_16x16x32_bf16 v[34:37], v[208:211], v[224:227], v[34:37]
	v_mfma_f32_16x16x32_bf16 v[26:29], v[196:199], v[232:235], v[26:29]
	v_mfma_f32_16x16x32_bf16 v[18:21], v[208:211], v[232:235], v[18:21]
	v_mfma_f32_16x16x32_bf16 v[10:13], v[196:199], v[240:243], v[10:13]
	v_mfma_f32_16x16x32_bf16 v[2:5], v[208:211], v[240:243], v[2:5]
	s_barrier
	s_setprio 0
	s_lshl_b32 s100, s84, 1
	v_lshl_add_u32 v204, v163, 5, s100
	v_add_u32_e32 v204, 0x20000, v204
	ds_read_b128 v[208:211], v204
	ds_read_b128 v[212:215], v204 offset:16
	s_waitcnt lgkmcnt(0)
	v_add_f32_e32 v208, v208, v209
	v_add_f32_e32 v210, v210, v211
	v_add_f32_e32 v212, v212, v213
	v_add_f32_e32 v214, v214, v215
	v_add_f32_e32 v208, v208, v210
	v_add_f32_e32 v212, v212, v214
	v_add_f32_e32 v208, v208, v212
	v_mov_b32_e32 v209, 0x358637bd
	s_nop 0
	v_add_f32_dpp v208, v208, v208 quad_perm:[1,0,3,2] row_mask:0xf bank_mask:0xf
	v_fmamk_f32 v208, v208, 0x3a800000, v209
	v_rsq_f32_e32 v209, v208
	s_nop 0
	v_mul_f32_e32 v209, 0xbfb8aa3b, v209
	ds_write_b64 v204, v[208:209]
	s_add_u32 s16, s16, 0x100
	s_addc_u32 s17, s17, 0
	s_add_u32 s56, s56, 0x100
	s_addc_u32 s57, s57, 0
	s_cmp_ge_i32 s86, s23
	s_mov_b32 s42, s86
	s_cbranch_scc0 .LBB7_357
	s_branch .Lpeelx_357
	.p2align	6

.Lpeel_434:
	s_add_i32 s75, s72, 2
	s_add_u32 s76, s16, 0x4000
	s_addc_u32 s73, s17, 0
	s_cmp_eq_u32 s3, s72
	s_cselect_b32 s72, s86, s76
	s_cselect_b32 s73, s20, s73
	s_cselect_b32 s84, s37, s29
	s_cselect_b32 s85, s87, s74
	s_add_u32 vcc_lo, s72, 0x8000
	s_addc_u32 vcc_hi, s73, 0
	s_add_i32 s76, 0, 0x10000
	v_add_u32_e32 v0, s76, v205
	s_add_i32 s91, 0, 0x14000
	ds_read_b128 v[132:135], v0
	ds_read_b128 v[136:139], v0 offset:1024
	ds_read_b128 v[140:143], v0 offset:2048
	ds_read_b128 v[144:147], v0 offset:3072
	v_add_u32_e32 v0, s91, v205
	ds_read_b128 v[148:151], v0
	ds_read_b128 v[152:155], v0 offset:1024
	ds_read_b128 v[156:159], v0 offset:2048
	ds_read_b128 v[184:187], v0 offset:3072
	s_waitcnt lgkmcnt(0)
	s_add_i32 m0, s23, 0xc000
	ds_read_b128 v[188:191], v207
	ds_read_b128 v[192:195], v207 offset:1024
	ds_read_b128 v[196:199], v207 offset:2048
	ds_read_b128 v[208:211], v207 offset:3072
	ds_read_b128 v[212:215], v207 offset:4096
	ds_read_b128 v[216:219], v207 offset:5120
	ds_read_b128 v[220:223], v207 offset:6144
	ds_read_b128 v[224:227], v207 offset:7168
	global_load_lds_dwordx4 v180, s[16:17]
	s_add_i32 m0, s23, 0xe000
	s_nop 0
	global_load_lds_dwordx4 v182, s[16:17]
	s_waitcnt vmcnt(8)
	s_waitcnt lgkmcnt(0)
	s_setprio 1
	s_barrier
	v_mfma_f32_16x16x32_bf16 v[128:131], v[132:135], v[188:191], 0
	v_mfma_f32_16x16x32_bf16 v[124:127], v[140:143], v[188:191], 0
	v_mfma_f32_16x16x32_bf16 v[120:123], v[132:135], v[196:199], 0
	v_mfma_f32_16x16x32_bf16 v[116:119], v[140:143], v[196:199], 0
	v_mfma_f32_16x16x32_bf16 v[112:115], v[132:135], v[212:215], 0
	v_mfma_f32_16x16x32_bf16 v[108:111], v[140:143], v[212:215], 0
	v_mfma_f32_16x16x32_bf16 v[104:107], v[132:135], v[220:223], 0
	v_mfma_f32_16x16x32_bf16 v[100:103], v[140:143], v[220:223], 0
	v_mfma_f32_16x16x32_bf16 v[128:131], v[136:139], v[192:195], v[128:131]
	v_mfma_f32_16x16x32_bf16 v[124:127], v[144:147], v[192:195], v[124:127]
	v_mfma_f32_16x16x32_bf16 v[120:123], v[136:139], v[208:211], v[120:123]
	v_mfma_f32_16x16x32_bf16 v[116:119], v[144:147], v[208:211], v[116:119]
	v_mfma_f32_16x16x32_bf16 v[112:115], v[136:139], v[216:219], v[112:115]
	v_mfma_f32_16x16x32_bf16 v[108:111], v[144:147], v[216:219], v[108:111]
	v_mfma_f32_16x16x32_bf16 v[104:107], v[136:139], v[224:227], v[104:107]
	v_mfma_f32_16x16x32_bf16 v[100:103], v[144:147], v[224:227], v[100:103]
	v_mfma_f32_16x16x32_bf16 v[96:99], v[148:151], v[188:191], 0
	v_mfma_f32_16x16x32_bf16 v[92:95], v[156:159], v[188:191], 0
	v_mfma_f32_16x16x32_bf16 v[88:91], v[148:151], v[196:199], 0
	v_mfma_f32_16x16x32_bf16 v[84:87], v[156:159], v[196:199], 0
	v_mfma_f32_16x16x32_bf16 v[80:83], v[148:151], v[212:215], 0
	v_mfma_f32_16x16x32_bf16 v[76:79], v[156:159], v[212:215], 0
	v_mfma_f32_16x16x32_bf16 v[72:75], v[148:151], v[220:223], 0
	v_mfma_f32_16x16x32_bf16 v[64:67], v[156:159], v[220:223], 0
	v_mfma_f32_16x16x32_bf16 v[96:99], v[152:155], v[192:195], v[96:99]
	v_mfma_f32_16x16x32_bf16 v[92:95], v[184:187], v[192:195], v[92:95]
	v_mfma_f32_16x16x32_bf16 v[88:91], v[152:155], v[208:211], v[88:91]
	v_mfma_f32_16x16x32_bf16 v[84:87], v[184:187], v[208:211], v[84:87]
	v_mfma_f32_16x16x32_bf16 v[80:83], v[152:155], v[216:219], v[80:83]
	v_mfma_f32_16x16x32_bf16 v[76:79], v[184:187], v[216:219], v[76:79]
	v_mfma_f32_16x16x32_bf16 v[72:75], v[152:155], v[224:227], v[72:75]
	v_mfma_f32_16x16x32_bf16 v[64:67], v[184:187], v[224:227], v[64:67]
	s_barrier
	s_setprio 0
	s_add_i32 s76, s76, s4
	s_mov_b32 m0, s76
	ds_read_b128 v[188:191], v207 offset:16384
	ds_read_b128 v[192:195], v207 offset:17408
	ds_read_b128 v[196:199], v207 offset:18432
	ds_read_b128 v[208:211], v207 offset:19456
	ds_read_b128 v[212:215], v207 offset:20480
	ds_read_b128 v[216:219], v207 offset:21504
	ds_read_b128 v[220:223], v207 offset:22528
	ds_read_b128 v[224:227], v207 offset:23552
	global_load_lds_dwordx4 v176, s[84:85]
	s_add_i32 m0, s76, 0x2000
	s_add_u32 s76, s84, 0x4000
	s_addc_u32 s77, s85, 0
	s_add_i32 s91, s91, s4
	global_load_lds_dwordx4 v160, s[84:85]
	s_mov_b32 m0, s91
	s_nop 0
	global_load_lds_dwordx4 v176, s[76:77]
	s_add_i32 m0, s91, 0x2000
	s_nop 0
	global_load_lds_dwordx4 v160, s[76:77]
	s_mov_b32 m0, s23
	s_nop 0
	global_load_lds_dwordx4 v178, s[72:73]
	s_mov_b32 m0, s31
	s_nop 0
	global_load_lds_dwordx4 v174, s[72:73]
	s_waitcnt vmcnt(8)
	s_waitcnt lgkmcnt(0)
	s_setprio 1
	s_barrier
	v_mfma_f32_16x16x32_bf16 v[68:71], v[132:135], v[188:191], 0
	v_mfma_f32_16x16x32_bf16 v[60:63], v[140:143], v[188:191], 0
	v_mfma_f32_16x16x32_bf16 v[56:59], v[132:135], v[196:199], 0
	v_mfma_f32_16x16x32_bf16 v[52:55], v[140:143], v[196:199], 0
	v_mfma_f32_16x16x32_bf16 v[48:51], v[132:135], v[212:215], 0
	v_mfma_f32_16x16x32_bf16 v[44:47], v[140:143], v[212:215], 0
	v_mfma_f32_16x16x32_bf16 v[40:43], v[132:135], v[220:223], 0
	v_mfma_f32_16x16x32_bf16 v[36:39], v[140:143], v[220:223], 0
	v_mfma_f32_16x16x32_bf16 v[68:71], v[136:139], v[192:195], v[68:71]
	v_mfma_f32_16x16x32_bf16 v[60:63], v[144:147], v[192:195], v[60:63]
	v_mfma_f32_16x16x32_bf16 v[56:59], v[136:139], v[208:211], v[56:59]
	v_mfma_f32_16x16x32_bf16 v[52:55], v[144:147], v[208:211], v[52:55]
	v_mfma_f32_16x16x32_bf16 v[48:51], v[136:139], v[216:219], v[48:51]
	v_mfma_f32_16x16x32_bf16 v[44:47], v[144:147], v[216:219], v[44:47]
	v_mfma_f32_16x16x32_bf16 v[40:43], v[136:139], v[224:227], v[40:43]
	v_mfma_f32_16x16x32_bf16 v[36:39], v[144:147], v[224:227], v[36:39]
	v_mfma_f32_16x16x32_bf16 v[32:35], v[148:151], v[188:191], 0
	v_mfma_f32_16x16x32_bf16 v[28:31], v[156:159], v[188:191], 0
	v_mfma_f32_16x16x32_bf16 v[24:27], v[148:151], v[196:199], 0
	v_mfma_f32_16x16x32_bf16 v[20:23], v[156:159], v[196:199], 0
	v_mfma_f32_16x16x32_bf16 v[16:19], v[148:151], v[212:215], 0
	v_mfma_f32_16x16x32_bf16 v[12:15], v[156:159], v[212:215], 0
	v_mfma_f32_16x16x32_bf16 v[8:11], v[148:151], v[220:223], 0
	v_mfma_f32_16x16x32_bf16 v[2:5], v[156:159], v[220:223], 0
	v_mfma_f32_16x16x32_bf16 v[32:35], v[152:155], v[192:195], v[32:35]
	v_mfma_f32_16x16x32_bf16 v[28:31], v[184:187], v[192:195], v[28:31]
	v_mfma_f32_16x16x32_bf16 v[24:27], v[152:155], v[208:211], v[24:27]
	v_mfma_f32_16x16x32_bf16 v[20:23], v[184:187], v[208:211], v[20:23]
	v_mfma_f32_16x16x32_bf16 v[16:19], v[152:155], v[216:219], v[16:19]
	v_mfma_f32_16x16x32_bf16 v[12:15], v[184:187], v[216:219], v[12:15]
	v_mfma_f32_16x16x32_bf16 v[8:11], v[152:155], v[224:227], v[8:11]
	v_mfma_f32_16x16x32_bf16 v[2:5], v[184:187], v[224:227], v[2:5]
	s_barrier
	s_setprio 0
	s_add_i32 s76, 0, 0x18000
	v_add_u32_e32 v0, s76, v205
	s_add_i32 s77, 0, 0x1c000
	ds_read_b128 v[132:135], v0
	ds_read_b128 v[136:139], v0 offset:1024
	ds_read_b128 v[140:143], v0 offset:2048
	ds_read_b128 v[144:147], v0 offset:3072
	v_add_u32_e32 v0, s77, v205
	ds_read_b128 v[148:151], v0
	ds_read_b128 v[152:155], v0 offset:1024
	ds_read_b128 v[156:159], v0 offset:2048
	ds_read_b128 v[184:187], v0 offset:3072
	s_add_u32 s72, s72, 0x4000
	s_addc_u32 s73, s73, 0
	s_mov_b32 m0, s33
	ds_read_b128 v[188:191], v207 offset:32768
	ds_read_b128 v[192:195], v207 offset:33792
	ds_read_b128 v[196:199], v207 offset:34816
	ds_read_b128 v[208:211], v207 offset:35840
	ds_read_b128 v[212:215], v207 offset:36864
	ds_read_b128 v[216:219], v207 offset:37888
	ds_read_b128 v[220:223], v207 offset:38912
	ds_read_b128 v[224:227], v207 offset:39936
	global_load_lds_dwordx4 v178, s[72:73]
	s_mov_b32 m0, s93
	s_nop 0
	global_load_lds_dwordx4 v174, s[72:73]
	s_waitcnt vmcnt(8)
	s_waitcnt lgkmcnt(0)
	s_setprio 1
	s_barrier
	v_mfma_f32_16x16x32_bf16 v[128:131], v[132:135], v[188:191], v[128:131]
	v_mfma_f32_16x16x32_bf16 v[124:127], v[140:143], v[188:191], v[124:127]
	v_mfma_f32_16x16x32_bf16 v[120:123], v[132:135], v[196:199], v[120:123]
	v_mfma_f32_16x16x32_bf16 v[116:119], v[140:143], v[196:199], v[116:119]
	v_mfma_f32_16x16x32_bf16 v[112:115], v[132:135], v[212:215], v[112:115]
	v_mfma_f32_16x16x32_bf16 v[108:111], v[140:143], v[212:215], v[108:111]
	v_mfma_f32_16x16x32_bf16 v[104:107], v[132:135], v[220:223], v[104:107]
	v_mfma_f32_16x16x32_bf16 v[100:103], v[140:143], v[220:223], v[100:103]
	v_mfma_f32_16x16x32_bf16 v[128:131], v[136:139], v[192:195], v[128:131]
	v_mfma_f32_16x16x32_bf16 v[124:127], v[144:147], v[192:195], v[124:127]
	v_mfma_f32_16x16x32_bf16 v[120:123], v[136:139], v[208:211], v[120:123]
	v_mfma_f32_16x16x32_bf16 v[116:119], v[144:147], v[208:211], v[116:119]
	v_mfma_f32_16x16x32_bf16 v[112:115], v[136:139], v[216:219], v[112:115]
	v_mfma_f32_16x16x32_bf16 v[108:111], v[144:147], v[216:219], v[108:111]
	v_mfma_f32_16x16x32_bf16 v[104:107], v[136:139], v[224:227], v[104:107]
	v_mfma_f32_16x16x32_bf16 v[100:103], v[144:147], v[224:227], v[100:103]
	v_mfma_f32_16x16x32_bf16 v[96:99], v[148:151], v[188:191], v[96:99]
	v_mfma_f32_16x16x32_bf16 v[92:95], v[156:159], v[188:191], v[92:95]
	v_mfma_f32_16x16x32_bf16 v[88:91], v[148:151], v[196:199], v[88:91]
	v_mfma_f32_16x16x32_bf16 v[84:87], v[156:159], v[196:199], v[84:87]
	v_mfma_f32_16x16x32_bf16 v[80:83], v[148:151], v[212:215], v[80:83]
	v_mfma_f32_16x16x32_bf16 v[76:79], v[156:159], v[212:215], v[76:79]
	v_mfma_f32_16x16x32_bf16 v[72:75], v[148:151], v[220:223], v[72:75]
	v_mfma_f32_16x16x32_bf16 v[64:67], v[156:159], v[220:223], v[64:67]
	v_mfma_f32_16x16x32_bf16 v[96:99], v[152:155], v[192:195], v[96:99]
	v_mfma_f32_16x16x32_bf16 v[92:95], v[184:187], v[192:195], v[92:95]
	v_mfma_f32_16x16x32_bf16 v[88:91], v[152:155], v[208:211], v[88:91]
	v_mfma_f32_16x16x32_bf16 v[84:87], v[184:187], v[208:211], v[84:87]
	v_mfma_f32_16x16x32_bf16 v[80:83], v[152:155], v[216:219], v[80:83]
	v_mfma_f32_16x16x32_bf16 v[76:79], v[184:187], v[216:219], v[76:79]
	v_mfma_f32_16x16x32_bf16 v[72:75], v[152:155], v[224:227], v[72:75]
	v_mfma_f32_16x16x32_bf16 v[64:67], v[184:187], v[224:227], v[64:67]
	s_barrier
	s_setprio 0
	s_add_u32 s72, s84, 0x8000
	s_addc_u32 s73, s85, 0
	s_add_i32 s76, s76, s4
	s_mov_b32 m0, s76
	ds_read_b128 v[188:191], v207 offset:49152
	ds_read_b128 v[192:195], v207 offset:50176
	ds_read_b128 v[196:199], v207 offset:51200
	ds_read_b128 v[208:211], v207 offset:52224
	ds_read_b128 v[212:215], v207 offset:53248
	ds_read_b128 v[216:219], v207 offset:54272
	ds_read_b128 v[220:223], v207 offset:55296
	ds_read_b128 v[224:227], v207 offset:56320
	global_load_lds_dwordx4 v176, s[72:73]
	s_add_i32 m0, s76, 0x2000
	v_lshl_add_u64 v[6:7], s[72:73], 0, v[160:161]
	s_add_u32 s72, s84, 0xc000
	s_addc_u32 s73, s85, 0
	s_add_i32 s76, s77, s4
	global_load_lds_dwordx4 v[6:7], off
	s_mov_b32 m0, s76
	s_nop 0
	global_load_lds_dwordx4 v176, s[72:73]
	s_add_i32 m0, s76, 0x2000
	s_nop 0
	global_load_lds_dwordx4 v160, s[72:73]
	s_mov_b32 m0, s97
	s_nop 0
	global_load_lds_dwordx4 v178, vcc
	s_mov_b32 m0, s38
	s_nop 0
	global_load_lds_dwordx4 v174, vcc
	s_waitcnt vmcnt(8)
	s_waitcnt lgkmcnt(0)
	s_setprio 1
	s_barrier
	v_mfma_f32_16x16x32_bf16 v[68:71], v[132:135], v[188:191], v[68:71]
	v_mfma_f32_16x16x32_bf16 v[60:63], v[140:143], v[188:191], v[60:63]
	v_mfma_f32_16x16x32_bf16 v[56:59], v[132:135], v[196:199], v[56:59]
	v_mfma_f32_16x16x32_bf16 v[52:55], v[140:143], v[196:199], v[52:55]
	v_mfma_f32_16x16x32_bf16 v[48:51], v[132:135], v[212:215], v[48:51]
	v_mfma_f32_16x16x32_bf16 v[44:47], v[140:143], v[212:215], v[44:47]
	v_mfma_f32_16x16x32_bf16 v[40:43], v[132:135], v[220:223], v[40:43]
	v_mfma_f32_16x16x32_bf16 v[36:39], v[140:143], v[220:223], v[36:39]
	v_mfma_f32_16x16x32_bf16 v[68:71], v[136:139], v[192:195], v[68:71]
	v_mfma_f32_16x16x32_bf16 v[60:63], v[144:147], v[192:195], v[60:63]
	v_mfma_f32_16x16x32_bf16 v[56:59], v[136:139], v[208:211], v[56:59]
	v_mfma_f32_16x16x32_bf16 v[52:55], v[144:147], v[208:211], v[52:55]
	v_mfma_f32_16x16x32_bf16 v[48:51], v[136:139], v[216:219], v[48:51]
	v_mfma_f32_16x16x32_bf16 v[44:47], v[144:147], v[216:219], v[44:47]
	v_mfma_f32_16x16x32_bf16 v[40:43], v[136:139], v[224:227], v[40:43]
	v_mfma_f32_16x16x32_bf16 v[36:39], v[144:147], v[224:227], v[36:39]
	v_mfma_f32_16x16x32_bf16 v[32:35], v[148:151], v[188:191], v[32:35]
	v_mfma_f32_16x16x32_bf16 v[28:31], v[156:159], v[188:191], v[28:31]
	v_mfma_f32_16x16x32_bf16 v[24:27], v[148:151], v[196:199], v[24:27]
	v_mfma_f32_16x16x32_bf16 v[20:23], v[156:159], v[196:199], v[20:23]
	v_mfma_f32_16x16x32_bf16 v[16:19], v[148:151], v[212:215], v[16:19]
	v_mfma_f32_16x16x32_bf16 v[12:15], v[156:159], v[212:215], v[12:15]
	v_mfma_f32_16x16x32_bf16 v[6:9], v[148:151], v[220:223], v[8:11]
	v_mfma_f32_16x16x32_bf16 v[2:5], v[156:159], v[220:223], v[2:5]
	v_mfma_f32_16x16x32_bf16 v[32:35], v[152:155], v[192:195], v[32:35]
	v_mfma_f32_16x16x32_bf16 v[28:31], v[184:187], v[192:195], v[28:31]
	v_mfma_f32_16x16x32_bf16 v[24:27], v[152:155], v[208:211], v[24:27]
	v_mfma_f32_16x16x32_bf16 v[20:23], v[184:187], v[208:211], v[20:23]
	v_mfma_f32_16x16x32_bf16 v[16:19], v[152:155], v[216:219], v[16:19]
	v_mfma_f32_16x16x32_bf16 v[12:15], v[184:187], v[216:219], v[12:15]
	v_mfma_f32_16x16x32_bf16 v[8:11], v[152:155], v[224:227], v[6:9]
	v_mfma_f32_16x16x32_bf16 v[4:7], v[184:187], v[224:227], v[2:5]
	s_barrier
	s_setprio 0
	s_add_u32 s29, s29, 0x10000
	s_addc_u32 s74, s74, 0
	s_add_u32 s16, s16, 0x10000
	s_addc_u32 s17, s17, 0
	s_cmp_ge_i32 s75, s39
	s_mov_b32 s72, s75
	s_cbranch_scc0 .LBB7_434
	s_branch .Lpeelx_434
	.p2align	6

.Lpeel_523:
	s_add_i32 s56, s42, 2
	s_add_u32 s29, s16, 0xfffc0080
	s_addc_u32 s37, s17, -1
	s_add_i32 s57, 0, 0x10000
	s_cmp_eq_u32 s84, s42
	s_cselect_b32 s45, s13, s37
	s_cselect_b32 s44, s15, s29
	v_add_u32_e32 v0, s57, v195
	s_cselect_b32 s43, s38, s49
	s_cselect_b32 s42, s39, s48
	s_add_i32 s29, 0, 0x14000
	ds_read_b128 v[130:133], v0
	ds_read_b128 v[150:153], v0 offset:1024
	ds_read_b128 v[154:157], v0 offset:2048
	ds_read_b128 v[158:161], v0 offset:3072
	v_add_u32_e32 v0, s29, v195
	ds_read_b128 v[174:177], v0
	ds_read_b128 v[178:181], v0 offset:1024
	ds_read_b128 v[182:185], v0 offset:2048
	ds_read_b128 v[186:189], v0 offset:3072
	s_add_i32 m0, s5, 0xc000
	ds_read_b128 v[190:193], v196
	ds_read_b128 v[204:207], v196 offset:1024
	ds_read_b128 v[208:211], v196 offset:2048
	ds_read_b128 v[212:215], v196 offset:3072
	ds_read_b128 v[216:219], v196 offset:4096
	ds_read_b128 v[220:223], v196 offset:5120
	ds_read_b128 v[224:227], v196 offset:6144
	ds_read_b128 v[228:231], v196 offset:7168
	global_load_lds_dwordx4 v146, s[16:17]
	s_add_i32 m0, s5, 0xe000
	s_nop 0
	global_load_lds_dwordx4 v148, s[16:17]
	s_waitcnt vmcnt(8)
	s_waitcnt lgkmcnt(0)
	s_setprio 1
	s_barrier
	v_mfma_f32_16x16x32_bf16 v[126:129], v[130:133], v[190:193], 0
	v_mfma_f32_16x16x32_bf16 v[122:125], v[154:157], v[190:193], 0
	v_mfma_f32_16x16x32_bf16 v[110:113], v[130:133], v[208:211], 0
	v_mfma_f32_16x16x32_bf16 v[106:109], v[154:157], v[208:211], 0
	v_mfma_f32_16x16x32_bf16 v[94:97], v[130:133], v[216:219], 0
	v_mfma_f32_16x16x32_bf16 v[90:93], v[154:157], v[216:219], 0
	v_mfma_f32_16x16x32_bf16 v[78:81], v[130:133], v[224:227], 0
	v_mfma_f32_16x16x32_bf16 v[74:77], v[154:157], v[224:227], 0
	v_mfma_f32_16x16x32_bf16 v[126:129], v[150:153], v[204:207], v[126:129]
	v_mfma_f32_16x16x32_bf16 v[122:125], v[158:161], v[204:207], v[122:125]
	v_mfma_f32_16x16x32_bf16 v[110:113], v[150:153], v[212:215], v[110:113]
	v_mfma_f32_16x16x32_bf16 v[106:109], v[158:161], v[212:215], v[106:109]
	v_mfma_f32_16x16x32_bf16 v[94:97], v[150:153], v[220:223], v[94:97]
	v_mfma_f32_16x16x32_bf16 v[90:93], v[158:161], v[220:223], v[90:93]
	v_mfma_f32_16x16x32_bf16 v[78:81], v[150:153], v[228:231], v[78:81]
	v_mfma_f32_16x16x32_bf16 v[74:77], v[158:161], v[228:231], v[74:77]
	v_mfma_f32_16x16x32_bf16 v[118:121], v[174:177], v[190:193], 0
	v_mfma_f32_16x16x32_bf16 v[114:117], v[182:185], v[190:193], 0
	v_mfma_f32_16x16x32_bf16 v[102:105], v[174:177], v[208:211], 0
	v_mfma_f32_16x16x32_bf16 v[98:101], v[182:185], v[208:211], 0
	v_mfma_f32_16x16x32_bf16 v[86:89], v[174:177], v[216:219], 0
	v_mfma_f32_16x16x32_bf16 v[82:85], v[182:185], v[216:219], 0
	v_mfma_f32_16x16x32_bf16 v[70:73], v[174:177], v[224:227], 0
	v_mfma_f32_16x16x32_bf16 v[66:69], v[182:185], v[224:227], 0
	v_mfma_f32_16x16x32_bf16 v[118:121], v[178:181], v[204:207], v[118:121]
	v_mfma_f32_16x16x32_bf16 v[114:117], v[186:189], v[204:207], v[114:117]
	v_mfma_f32_16x16x32_bf16 v[102:105], v[178:181], v[212:215], v[102:105]
	v_mfma_f32_16x16x32_bf16 v[98:101], v[186:189], v[212:215], v[98:101]
	v_mfma_f32_16x16x32_bf16 v[86:89], v[178:181], v[220:223], v[86:89]
	v_mfma_f32_16x16x32_bf16 v[82:85], v[186:189], v[220:223], v[82:85]
	v_mfma_f32_16x16x32_bf16 v[70:73], v[178:181], v[228:231], v[70:73]
	v_mfma_f32_16x16x32_bf16 v[66:69], v[186:189], v[228:231], v[66:69]
	s_barrier
	s_setprio 0
	s_add_i32 s37, s57, s4
	v_lshl_add_u64 v[170:171], s[42:43], 0, v[138:139]
	s_mov_b32 m0, s37
	ds_read_b128 v[190:193], v196 offset:16384
	ds_read_b128 v[204:207], v196 offset:17408
	ds_read_b128 v[208:211], v196 offset:18432
	ds_read_b128 v[212:215], v196 offset:19456
	ds_read_b128 v[216:219], v196 offset:20480
	ds_read_b128 v[220:223], v196 offset:21504
	ds_read_b128 v[224:227], v196 offset:22528
	ds_read_b128 v[228:231], v196 offset:23552
	global_load_lds_dwordx4 v[170:171], off
	s_add_i32 m0, s37, 0x2000
	s_add_u32 s74, s42, 0x40000
	v_lshl_add_u64 v[172:173], s[42:43], 0, v[134:135]
	s_addc_u32 s75, s43, 0
	s_add_i32 s29, s29, s4
	global_load_lds_dwordx4 v[172:173], off
	s_mov_b32 m0, s29
	v_lshl_add_u64 v[232:233], s[44:45], 0, v[136:137]
	global_load_lds_dwordx4 v138, s[74:75]
	s_add_i32 m0, s29, 0x2000
	s_nop 0
	global_load_lds_dwordx4 v134, s[74:75]
	v_lshl_add_u64 v[198:199], s[44:45], 0, v[140:141]
	s_mov_b32 m0, s5
	s_nop 0
	global_load_lds_dwordx4 v[198:199], off
	s_mov_b32 m0, s20
	s_nop 0
	global_load_lds_dwordx4 v[232:233], off
	s_lshl_b32 s101, s28, 14
	s_add_i32 s101, s101, s5
	s_add_u32 s100, s66, s101
	s_addc_u32 s101, s67, 0
	v_lshlrev_b32_e32 v2, 4, v163
	v_add_u32_e32 v3, 0x2000, v2
	s_add_i32 m0, s5, 0x20000
	s_nop 0
	global_load_lds_dwordx4 v2, s[100:101]
	s_add_i32 m0, s5, 0x22000
	s_nop 0
	global_load_lds_dwordx4 v3, s[100:101]
	s_waitcnt vmcnt(8)
	s_waitcnt lgkmcnt(0)
	s_setprio 1
	s_barrier
	v_mfma_f32_16x16x32_bf16 v[62:65], v[130:133], v[190:193], 0
	v_mfma_f32_16x16x32_bf16 v[58:61], v[154:157], v[190:193], 0
	v_mfma_f32_16x16x32_bf16 v[46:49], v[130:133], v[208:211], 0
	v_mfma_f32_16x16x32_bf16 v[42:45], v[154:157], v[208:211], 0
	v_mfma_f32_16x16x32_bf16 v[30:33], v[130:133], v[216:219], 0
	v_mfma_f32_16x16x32_bf16 v[26:29], v[154:157], v[216:219], 0
	v_mfma_f32_16x16x32_bf16 v[14:17], v[130:133], v[224:227], 0
	v_mfma_f32_16x16x32_bf16 v[10:13], v[154:157], v[224:227], 0
	v_mfma_f32_16x16x32_bf16 v[62:65], v[150:153], v[204:207], v[62:65]
	v_mfma_f32_16x16x32_bf16 v[58:61], v[158:161], v[204:207], v[58:61]
	v_mfma_f32_16x16x32_bf16 v[46:49], v[150:153], v[212:215], v[46:49]
	v_mfma_f32_16x16x32_bf16 v[42:45], v[158:161], v[212:215], v[42:45]
	v_mfma_f32_16x16x32_bf16 v[30:33], v[150:153], v[220:223], v[30:33]
	v_mfma_f32_16x16x32_bf16 v[26:29], v[158:161], v[220:223], v[26:29]
	v_mfma_f32_16x16x32_bf16 v[14:17], v[150:153], v[228:231], v[14:17]
	v_mfma_f32_16x16x32_bf16 v[10:13], v[158:161], v[228:231], v[10:13]
	v_mfma_f32_16x16x32_bf16 v[54:57], v[174:177], v[190:193], 0
	v_mfma_f32_16x16x32_bf16 v[50:53], v[182:185], v[190:193], 0
	v_mfma_f32_16x16x32_bf16 v[38:41], v[174:177], v[208:211], 0
	v_mfma_f32_16x16x32_bf16 v[34:37], v[182:185], v[208:211], 0
	v_mfma_f32_16x16x32_bf16 v[22:25], v[174:177], v[216:219], 0
	v_mfma_f32_16x16x32_bf16 v[18:21], v[182:185], v[216:219], 0
	v_mfma_f32_16x16x32_bf16 v[6:9], v[174:177], v[224:227], 0
	v_mfma_f32_16x16x32_bf16 v[2:5], v[182:185], v[224:227], 0
	v_mfma_f32_16x16x32_bf16 v[54:57], v[178:181], v[204:207], v[54:57]
	v_mfma_f32_16x16x32_bf16 v[50:53], v[186:189], v[204:207], v[50:53]
	v_mfma_f32_16x16x32_bf16 v[38:41], v[178:181], v[212:215], v[38:41]
	v_mfma_f32_16x16x32_bf16 v[34:37], v[186:189], v[212:215], v[34:37]
	v_mfma_f32_16x16x32_bf16 v[22:25], v[178:181], v[220:223], v[22:25]
	v_mfma_f32_16x16x32_bf16 v[18:21], v[186:189], v[220:223], v[18:21]
	v_mfma_f32_16x16x32_bf16 v[6:9], v[178:181], v[228:231], v[6:9]
	v_mfma_f32_16x16x32_bf16 v[2:5], v[186:189], v[228:231], v[2:5]
	s_barrier
	s_setprio 0
	s_add_i32 s29, 0, 0x18000
	v_add_u32_e32 v0, s29, v195
	s_add_i32 s37, 0, 0x1c000
	ds_read_b128 v[130:133], v0
	ds_read_b128 v[150:153], v0 offset:1024
	ds_read_b128 v[154:157], v0 offset:2048
	ds_read_b128 v[158:161], v0 offset:3072
	v_add_u32_e32 v0, s37, v195
	ds_read_b128 v[174:177], v0
	ds_read_b128 v[178:181], v0 offset:1024
	ds_read_b128 v[182:185], v0 offset:2048
	ds_read_b128 v[186:189], v0 offset:3072
	s_add_u32 s44, s44, 0x40000
	s_addc_u32 s45, s45, 0
	s_mov_b32 m0, s22
	ds_read_b128 v[190:193], v196 offset:32768
	ds_read_b128 v[204:207], v196 offset:33792
	ds_read_b128 v[208:211], v196 offset:34816
	ds_read_b128 v[212:215], v196 offset:35840
	ds_read_b128 v[216:219], v196 offset:36864
	ds_read_b128 v[220:223], v196 offset:37888
	ds_read_b128 v[224:227], v196 offset:38912
	ds_read_b128 v[228:231], v196 offset:39936
	global_load_lds_dwordx4 v140, s[44:45]
	s_mov_b32 m0, s23
	s_nop 0
	global_load_lds_dwordx4 v136, s[44:45]
	s_waitcnt vmcnt(8)
	s_waitcnt lgkmcnt(0)
	s_setprio 1
	s_barrier
	v_mfma_f32_16x16x32_bf16 v[126:129], v[130:133], v[190:193], v[126:129]
	v_mfma_f32_16x16x32_bf16 v[122:125], v[154:157], v[190:193], v[122:125]
	v_mfma_f32_16x16x32_bf16 v[110:113], v[130:133], v[208:211], v[110:113]
	v_mfma_f32_16x16x32_bf16 v[106:109], v[154:157], v[208:211], v[106:109]
	v_mfma_f32_16x16x32_bf16 v[94:97], v[130:133], v[216:219], v[94:97]
	v_mfma_f32_16x16x32_bf16 v[90:93], v[154:157], v[216:219], v[90:93]
	v_mfma_f32_16x16x32_bf16 v[78:81], v[130:133], v[224:227], v[78:81]
	v_mfma_f32_16x16x32_bf16 v[74:77], v[154:157], v[224:227], v[74:77]
	v_mfma_f32_16x16x32_bf16 v[126:129], v[150:153], v[204:207], v[126:129]
	v_mfma_f32_16x16x32_bf16 v[122:125], v[158:161], v[204:207], v[122:125]
	v_mfma_f32_16x16x32_bf16 v[110:113], v[150:153], v[212:215], v[110:113]
	v_mfma_f32_16x16x32_bf16 v[106:109], v[158:161], v[212:215], v[106:109]
	v_mfma_f32_16x16x32_bf16 v[94:97], v[150:153], v[220:223], v[94:97]
	v_mfma_f32_16x16x32_bf16 v[90:93], v[158:161], v[220:223], v[90:93]
	v_mfma_f32_16x16x32_bf16 v[78:81], v[150:153], v[228:231], v[78:81]
	v_mfma_f32_16x16x32_bf16 v[74:77], v[158:161], v[228:231], v[74:77]
	v_mfma_f32_16x16x32_bf16 v[118:121], v[174:177], v[190:193], v[118:121]
	v_mfma_f32_16x16x32_bf16 v[114:117], v[182:185], v[190:193], v[114:117]
	v_mfma_f32_16x16x32_bf16 v[102:105], v[174:177], v[208:211], v[102:105]
	v_mfma_f32_16x16x32_bf16 v[98:101], v[182:185], v[208:211], v[98:101]
	v_mfma_f32_16x16x32_bf16 v[86:89], v[174:177], v[216:219], v[86:89]
	v_mfma_f32_16x16x32_bf16 v[82:85], v[182:185], v[216:219], v[82:85]
	v_mfma_f32_16x16x32_bf16 v[70:73], v[174:177], v[224:227], v[70:73]
	v_mfma_f32_16x16x32_bf16 v[66:69], v[182:185], v[224:227], v[66:69]
	v_mfma_f32_16x16x32_bf16 v[118:121], v[178:181], v[204:207], v[118:121]
	v_mfma_f32_16x16x32_bf16 v[114:117], v[186:189], v[204:207], v[114:117]
	v_mfma_f32_16x16x32_bf16 v[102:105], v[178:181], v[212:215], v[102:105]
	v_mfma_f32_16x16x32_bf16 v[98:101], v[186:189], v[212:215], v[98:101]
	v_mfma_f32_16x16x32_bf16 v[86:89], v[178:181], v[220:223], v[86:89]
	v_mfma_f32_16x16x32_bf16 v[82:85], v[186:189], v[220:223], v[82:85]
	v_mfma_f32_16x16x32_bf16 v[70:73], v[178:181], v[228:231], v[70:73]
	v_mfma_f32_16x16x32_bf16 v[66:69], v[186:189], v[228:231], v[66:69]
	s_barrier
	s_setprio 0
	s_add_i32 s29, s29, s4
	v_lshl_add_u64 v[170:171], v[170:171], 0, s[24:25]
	s_mov_b32 m0, s29
	ds_read_b128 v[190:193], v196 offset:49152
	ds_read_b128 v[204:207], v196 offset:50176
	ds_read_b128 v[208:211], v196 offset:51200
	ds_read_b128 v[212:215], v196 offset:52224
	ds_read_b128 v[216:219], v196 offset:53248
	ds_read_b128 v[220:223], v196 offset:54272
	ds_read_b128 v[224:227], v196 offset:55296
	ds_read_b128 v[228:231], v196 offset:56320
	global_load_lds_dwordx4 v[170:171], off
	s_add_i32 m0, s29, 0x2000
	s_add_u32 s42, s42, 0x40080
	v_lshl_add_u64 v[170:171], v[172:173], 0, s[24:25]
	s_addc_u32 s43, s43, 0
	s_add_i32 s29, s37, s4
	global_load_lds_dwordx4 v[170:171], off
	s_mov_b32 m0, s29
	s_nop 0
	global_load_lds_dwordx4 v138, s[42:43]
	s_add_i32 m0, s29, 0x2000
	s_nop 0
	global_load_lds_dwordx4 v134, s[42:43]
	v_lshl_add_u64 v[170:171], v[198:199], 0, s[24:25]
	s_mov_b32 m0, s33
	s_nop 0
	global_load_lds_dwordx4 v[170:171], off
	v_lshl_add_u64 v[170:171], v[232:233], 0, s[24:25]
	s_mov_b32 m0, s72
	s_nop 0
	global_load_lds_dwordx4 v[170:171], off
	s_waitcnt vmcnt(8)
	s_waitcnt lgkmcnt(0)
	s_setprio 1
	s_barrier
	v_mfma_f32_16x16x32_bf16 v[62:65], v[130:133], v[190:193], v[62:65]
	v_mfma_f32_16x16x32_bf16 v[58:61], v[154:157], v[190:193], v[58:61]
	v_mfma_f32_16x16x32_bf16 v[46:49], v[130:133], v[208:211], v[46:49]
	v_mfma_f32_16x16x32_bf16 v[42:45], v[154:157], v[208:211], v[42:45]
	v_mfma_f32_16x16x32_bf16 v[30:33], v[130:133], v[216:219], v[30:33]
	v_mfma_f32_16x16x32_bf16 v[26:29], v[154:157], v[216:219], v[26:29]
	v_mfma_f32_16x16x32_bf16 v[14:17], v[130:133], v[224:227], v[14:17]
	v_mfma_f32_16x16x32_bf16 v[10:13], v[154:157], v[224:227], v[10:13]
	v_mfma_f32_16x16x32_bf16 v[62:65], v[150:153], v[204:207], v[62:65]
	v_mfma_f32_16x16x32_bf16 v[58:61], v[158:161], v[204:207], v[58:61]
	v_mfma_f32_16x16x32_bf16 v[46:49], v[150:153], v[212:215], v[46:49]
	v_mfma_f32_16x16x32_bf16 v[42:45], v[158:161], v[212:215], v[42:45]
	v_mfma_f32_16x16x32_bf16 v[30:33], v[150:153], v[220:223], v[30:33]
	v_mfma_f32_16x16x32_bf16 v[26:29], v[158:161], v[220:223], v[26:29]
	v_mfma_f32_16x16x32_bf16 v[14:17], v[150:153], v[228:231], v[14:17]
	v_mfma_f32_16x16x32_bf16 v[10:13], v[158:161], v[228:231], v[10:13]
	v_mfma_f32_16x16x32_bf16 v[54:57], v[174:177], v[190:193], v[54:57]
	v_mfma_f32_16x16x32_bf16 v[50:53], v[182:185], v[190:193], v[50:53]
	v_mfma_f32_16x16x32_bf16 v[38:41], v[174:177], v[208:211], v[38:41]
	v_mfma_f32_16x16x32_bf16 v[34:37], v[182:185], v[208:211], v[34:37]
	v_mfma_f32_16x16x32_bf16 v[22:25], v[174:177], v[216:219], v[22:25]
	v_mfma_f32_16x16x32_bf16 v[18:21], v[182:185], v[216:219], v[18:21]
	v_mfma_f32_16x16x32_bf16 v[6:9], v[174:177], v[224:227], v[6:9]
	v_mfma_f32_16x16x32_bf16 v[2:5], v[182:185], v[224:227], v[2:5]
	v_mfma_f32_16x16x32_bf16 v[54:57], v[178:181], v[204:207], v[54:57]
	v_mfma_f32_16x16x32_bf16 v[50:53], v[186:189], v[204:207], v[50:53]
	v_mfma_f32_16x16x32_bf16 v[38:41], v[178:181], v[212:215], v[38:41]
	v_mfma_f32_16x16x32_bf16 v[34:37], v[186:189], v[212:215], v[34:37]
	v_mfma_f32_16x16x32_bf16 v[22:25], v[178:181], v[220:223], v[22:25]
	v_mfma_f32_16x16x32_bf16 v[18:21], v[186:189], v[220:223], v[18:21]
	v_mfma_f32_16x16x32_bf16 v[6:9], v[178:181], v[228:231], v[6:9]
	v_mfma_f32_16x16x32_bf16 v[2:5], v[186:189], v[228:231], v[2:5]
	s_barrier
	s_setprio 0
	s_add_u32 s16, s16, 0x100
	s_addc_u32 s17, s17, 0
	s_add_u32 s48, s48, 0x100
	s_addc_u32 s49, s49, 0
	s_cmp_ge_i32 s56, s3
	s_mov_b32 s42, s56
	s_cbranch_scc0 .LBB7_523
	s_branch .Lpeelx_523
	.p2align	6

.Lpeel_676:
	s_add_i32 s29, s37, 2
	s_add_u32 s44, s42, 0x100
	s_addc_u32 s45, s43, 0
	s_add_i32 s74, 0, 0x10000
	v_add_u32_e32 v81, s74, v79
	ds_read_b128 v[82:85], v81
	ds_read_b128 v[86:89], v81 offset:1024
	ds_read_b128 v[90:93], v81 offset:2048
	ds_read_b128 v[94:97], v81 offset:3072
	s_cmp_eq_u32 s53, s37
	s_cselect_b32 s51, s56, s45
	s_cselect_b32 s50, s57, s44
	s_cselect_b32 s49, s72, s85
	s_cselect_b32 s48, s73, s84
	v_lshl_add_u64 v[130:131], s[42:43], 0, v[74:75]
	s_add_i32 m0, s5, 0xc000
	ds_read_b128 v[98:101], v80
	ds_read_b128 v[102:105], v80 offset:1024
	ds_read_b128 v[106:109], v80 offset:2048
	ds_read_b128 v[110:113], v80 offset:3072
	ds_read_b128 v[114:117], v80 offset:4096
	ds_read_b128 v[118:121], v80 offset:5120
	ds_read_b128 v[122:125], v80 offset:6144
	ds_read_b128 v[126:129], v80 offset:7168
	global_load_lds_dwordx4 v[130:131], off
	v_lshl_add_u64 v[130:131], s[42:43], 0, v[76:77]
	s_add_i32 m0, s5, 0xe000
	s_nop 0
	global_load_lds_dwordx4 v[130:131], off
	s_waitcnt vmcnt(8)
	s_waitcnt lgkmcnt(0)
	s_setprio 1
	s_barrier
	v_mfma_f32_16x16x32_bf16 v[62:65], v[82:85], v[98:101], 0
	v_mfma_f32_16x16x32_bf16 v[58:61], v[90:93], v[98:101], 0
	v_mfma_f32_16x16x32_bf16 v[54:57], v[82:85], v[106:109], 0
	v_mfma_f32_16x16x32_bf16 v[50:53], v[90:93], v[106:109], 0
	v_mfma_f32_16x16x32_bf16 v[46:49], v[82:85], v[114:117], 0
	v_mfma_f32_16x16x32_bf16 v[42:45], v[90:93], v[114:117], 0
	v_mfma_f32_16x16x32_bf16 v[38:41], v[82:85], v[122:125], 0
	v_mfma_f32_16x16x32_bf16 v[34:37], v[90:93], v[122:125], 0
	v_mfma_f32_16x16x32_bf16 v[62:65], v[86:89], v[102:105], v[62:65]
	v_mfma_f32_16x16x32_bf16 v[58:61], v[94:97], v[102:105], v[58:61]
	v_mfma_f32_16x16x32_bf16 v[54:57], v[86:89], v[110:113], v[54:57]
	v_mfma_f32_16x16x32_bf16 v[50:53], v[94:97], v[110:113], v[50:53]
	v_mfma_f32_16x16x32_bf16 v[46:49], v[86:89], v[118:121], v[46:49]
	v_mfma_f32_16x16x32_bf16 v[42:45], v[94:97], v[118:121], v[42:45]
	v_mfma_f32_16x16x32_bf16 v[38:41], v[86:89], v[126:129], v[38:41]
	v_mfma_f32_16x16x32_bf16 v[34:37], v[94:97], v[126:129], v[34:37]
	s_barrier
	s_setprio 0
	s_add_i32 s37, s74, s4
	v_lshl_add_u64 v[130:131], s[48:49], 0, v[70:71]
	s_mov_b32 m0, s37
	ds_read_b128 v[98:101], v80 offset:16384
	ds_read_b128 v[102:105], v80 offset:17408
	ds_read_b128 v[106:109], v80 offset:18432
	ds_read_b128 v[110:113], v80 offset:19456
	ds_read_b128 v[114:117], v80 offset:20480
	ds_read_b128 v[118:121], v80 offset:21504
	ds_read_b128 v[122:125], v80 offset:22528
	ds_read_b128 v[126:129], v80 offset:23552
	global_load_lds_dwordx4 v[130:131], off
	s_add_i32 m0, s37, 0x2000
	s_add_u32 s42, s48, 0x20000
	v_lshl_add_u64 v[132:133], s[48:49], 0, v[66:67]
	s_addc_u32 s43, s49, 0
	global_load_lds_dwordx4 v[132:133], off
	v_lshl_add_u64 v[134:135], s[42:43], 0, v[70:71]
	s_mov_b32 m0, s10
	v_lshl_add_u64 v[136:137], s[50:51], 0, v[68:69]
	global_load_lds_dwordx4 v[134:135], off
	v_lshl_add_u64 v[134:135], s[42:43], 0, v[66:67]
	s_mov_b32 m0, s20
	s_nop 0
	global_load_lds_dwordx4 v[134:135], off
	v_lshl_add_u64 v[134:135], s[50:51], 0, v[0:1]
	s_mov_b32 m0, s5
	s_nop 0
	global_load_lds_dwordx4 v[134:135], off
	s_mov_b32 m0, s22
	s_nop 0
	global_load_lds_dwordx4 v[136:137], off
	s_waitcnt vmcnt(8)
	s_waitcnt lgkmcnt(0)
	s_setprio 1
	s_barrier
	v_mfma_f32_16x16x32_bf16 v[30:33], v[82:85], v[98:101], 0
	v_mfma_f32_16x16x32_bf16 v[26:29], v[90:93], v[98:101], 0
	v_mfma_f32_16x16x32_bf16 v[22:25], v[82:85], v[106:109], 0
	v_mfma_f32_16x16x32_bf16 v[18:21], v[90:93], v[106:109], 0
	v_mfma_f32_16x16x32_bf16 v[14:17], v[82:85], v[114:117], 0
	v_mfma_f32_16x16x32_bf16 v[10:13], v[90:93], v[114:117], 0
	v_mfma_f32_16x16x32_bf16 v[6:9], v[82:85], v[122:125], 0
	v_mfma_f32_16x16x32_bf16 v[2:5], v[90:93], v[122:125], 0
	v_mfma_f32_16x16x32_bf16 v[30:33], v[86:89], v[102:105], v[30:33]
	v_mfma_f32_16x16x32_bf16 v[26:29], v[94:97], v[102:105], v[26:29]
	v_mfma_f32_16x16x32_bf16 v[22:25], v[86:89], v[110:113], v[22:25]
	v_mfma_f32_16x16x32_bf16 v[18:21], v[94:97], v[110:113], v[18:21]
	v_mfma_f32_16x16x32_bf16 v[14:17], v[86:89], v[118:121], v[14:17]
	v_mfma_f32_16x16x32_bf16 v[10:13], v[94:97], v[118:121], v[10:13]
	v_mfma_f32_16x16x32_bf16 v[6:9], v[86:89], v[126:129], v[6:9]
	v_mfma_f32_16x16x32_bf16 v[2:5], v[94:97], v[126:129], v[2:5]
	s_barrier
	s_setprio 0
	s_add_i32 s37, 0, 0x18000
	v_add_u32_e32 v81, s37, v79
	ds_read_b128 v[82:85], v81
	ds_read_b128 v[86:89], v81 offset:1024
	ds_read_b128 v[90:93], v81 offset:2048
	ds_read_b128 v[94:97], v81 offset:3072
	s_add_u32 s42, s50, 0x28000
	s_addc_u32 s43, s51, 0
	s_mov_b32 m0, s23
	v_lshl_add_u64 v[138:139], s[42:43], 0, v[0:1]
	ds_read_b128 v[98:101], v80 offset:32768
	ds_read_b128 v[102:105], v80 offset:33792
	ds_read_b128 v[106:109], v80 offset:34816
	ds_read_b128 v[110:113], v80 offset:35840
	ds_read_b128 v[114:117], v80 offset:36864
	ds_read_b128 v[118:121], v80 offset:37888
	ds_read_b128 v[122:125], v80 offset:38912
	ds_read_b128 v[126:129], v80 offset:39936
	global_load_lds_dwordx4 v[138:139], off
	v_lshl_add_u64 v[138:139], s[42:43], 0, v[68:69]
	s_mov_b32 m0, s28
	s_nop 0
	global_load_lds_dwordx4 v[138:139], off
	s_waitcnt vmcnt(8)
	s_waitcnt lgkmcnt(0)
	s_setprio 1
	s_barrier
	v_mfma_f32_16x16x32_bf16 v[62:65], v[82:85], v[98:101], v[62:65]
	v_mfma_f32_16x16x32_bf16 v[58:61], v[90:93], v[98:101], v[58:61]
	v_mfma_f32_16x16x32_bf16 v[54:57], v[82:85], v[106:109], v[54:57]
	v_mfma_f32_16x16x32_bf16 v[50:53], v[90:93], v[106:109], v[50:53]
	v_mfma_f32_16x16x32_bf16 v[46:49], v[82:85], v[114:117], v[46:49]
	v_mfma_f32_16x16x32_bf16 v[42:45], v[90:93], v[114:117], v[42:45]
	v_mfma_f32_16x16x32_bf16 v[38:41], v[82:85], v[122:125], v[38:41]
	v_mfma_f32_16x16x32_bf16 v[34:37], v[90:93], v[122:125], v[34:37]
	v_mfma_f32_16x16x32_bf16 v[62:65], v[86:89], v[102:105], v[62:65]
	v_mfma_f32_16x16x32_bf16 v[58:61], v[94:97], v[102:105], v[58:61]
	v_mfma_f32_16x16x32_bf16 v[54:57], v[86:89], v[110:113], v[54:57]
	v_mfma_f32_16x16x32_bf16 v[50:53], v[94:97], v[110:113], v[50:53]
	v_mfma_f32_16x16x32_bf16 v[46:49], v[86:89], v[118:121], v[46:49]
	v_mfma_f32_16x16x32_bf16 v[42:45], v[94:97], v[118:121], v[42:45]
	v_mfma_f32_16x16x32_bf16 v[38:41], v[86:89], v[126:129], v[38:41]
	v_mfma_f32_16x16x32_bf16 v[34:37], v[94:97], v[126:129], v[34:37]
	s_barrier
	s_setprio 0
	s_add_i32 s37, s37, s4
	v_lshl_add_u64 v[130:131], v[130:131], 0, s[24:25]
	s_mov_b32 m0, s37
	ds_read_b128 v[98:101], v80 offset:49152
	ds_read_b128 v[102:105], v80 offset:50176
	ds_read_b128 v[106:109], v80 offset:51200
	ds_read_b128 v[110:113], v80 offset:52224
	ds_read_b128 v[114:117], v80 offset:53248
	ds_read_b128 v[118:121], v80 offset:54272
	ds_read_b128 v[122:125], v80 offset:55296
	ds_read_b128 v[126:129], v80 offset:56320
	global_load_lds_dwordx4 v[130:131], off
	s_add_i32 m0, s37, 0x2000
	s_add_u32 s42, s48, 0x20080
	v_lshl_add_u64 v[130:131], v[132:133], 0, s[24:25]
	s_addc_u32 s43, s49, 0
	global_load_lds_dwordx4 v[130:131], off
	v_lshl_add_u64 v[130:131], s[42:43], 0, v[70:71]
	s_mov_b32 m0, s38
	s_nop 0
	global_load_lds_dwordx4 v[130:131], off
	v_lshl_add_u64 v[130:131], s[42:43], 0, v[66:67]
	s_mov_b32 m0, s39
	s_nop 0
	global_load_lds_dwordx4 v[130:131], off
	v_lshl_add_u64 v[130:131], v[134:135], 0, s[24:25]
	s_mov_b32 m0, s31
	s_nop 0
	global_load_lds_dwordx4 v[130:131], off
	v_lshl_add_u64 v[130:131], v[136:137], 0, s[24:25]
	s_mov_b32 m0, s33
	s_nop 0
	global_load_lds_dwordx4 v[130:131], off
	s_waitcnt vmcnt(8)
	s_waitcnt lgkmcnt(0)
	s_setprio 1
	s_barrier
	v_mfma_f32_16x16x32_bf16 v[30:33], v[82:85], v[98:101], v[30:33]
	v_mfma_f32_16x16x32_bf16 v[26:29], v[90:93], v[98:101], v[26:29]
	v_mfma_f32_16x16x32_bf16 v[22:25], v[82:85], v[106:109], v[22:25]
	v_mfma_f32_16x16x32_bf16 v[18:21], v[90:93], v[106:109], v[18:21]
	v_mfma_f32_16x16x32_bf16 v[14:17], v[82:85], v[114:117], v[14:17]
	v_mfma_f32_16x16x32_bf16 v[10:13], v[90:93], v[114:117], v[10:13]
	v_mfma_f32_16x16x32_bf16 v[6:9], v[82:85], v[122:125], v[6:9]
	v_mfma_f32_16x16x32_bf16 v[2:5], v[90:93], v[122:125], v[2:5]
	v_mfma_f32_16x16x32_bf16 v[30:33], v[86:89], v[102:105], v[30:33]
	v_mfma_f32_16x16x32_bf16 v[26:29], v[94:97], v[102:105], v[26:29]
	v_mfma_f32_16x16x32_bf16 v[22:25], v[86:89], v[110:113], v[22:25]
	v_mfma_f32_16x16x32_bf16 v[18:21], v[94:97], v[110:113], v[18:21]
	v_mfma_f32_16x16x32_bf16 v[14:17], v[86:89], v[118:121], v[14:17]
	v_mfma_f32_16x16x32_bf16 v[10:13], v[94:97], v[118:121], v[10:13]
	v_mfma_f32_16x16x32_bf16 v[6:9], v[86:89], v[126:129], v[6:9]
	v_mfma_f32_16x16x32_bf16 v[2:5], v[94:97], v[126:129], v[2:5]
	s_barrier
	s_setprio 0
	s_add_u32 s84, s84, 0x100
	s_addc_u32 s85, s85, 0
	s_cmp_ge_i32 s29, s3
	s_mov_b64 s[42:43], s[44:45]
	s_mov_b32 s37, s29
	s_cbranch_scc0 .LBB7_676
	s_branch .Lpeelx_676
	.p2align	6

.Lpeel_886:
	s_add_i32 s37, s44, 2
	s_add_u32 s42, s16, 0x100
	s_addc_u32 s43, s17, 0
	s_add_i32 s29, 0, 0x10000
	s_cmp_eq_u32 s57, s44
	s_cselect_b32 s49, s39, s43
	s_cselect_b32 s48, s54, s42
	s_cselect_b32 s45, s55, s73
	s_cselect_b32 s44, s56, s72
	s_add_i32 s74, 0, 0x14000
	v_add_u32_e32 v142, s29, v193
	v_add_u32_e32 v158, s74, v193
	ds_read_b128 v[74:77], v142
	ds_read_b128 v[78:81], v142 offset:1024
	ds_read_b128 v[138:141], v142 offset:2048
	ds_read_b128 v[142:145], v142 offset:3072
	ds_read_b128 v[146:149], v158
	ds_read_b128 v[150:153], v158 offset:1024
	ds_read_b128 v[154:157], v158 offset:2048
	ds_read_b128 v[158:161], v158 offset:3072
	v_lshl_add_u64 v[170:171], s[16:17], 0, v[184:185]
	s_add_i32 m0, s5, 0xc000
	ds_read_b128 v[188:191], v195
	ds_read_b128 v[196:199], v195 offset:1024
	ds_read_b128 v[204:207], v195 offset:2048
	ds_read_b128 v[208:211], v195 offset:3072
	ds_read_b128 v[212:215], v195 offset:4096
	ds_read_b128 v[216:219], v195 offset:5120
	ds_read_b128 v[220:223], v195 offset:6144
	ds_read_b128 v[224:227], v195 offset:7168
	global_load_lds_dwordx4 v[170:171], off
	v_lshl_add_u64 v[170:171], s[16:17], 0, v[186:187]
	s_add_i32 m0, s5, 0xe000
	s_nop 0
	global_load_lds_dwordx4 v[170:171], off
	s_waitcnt vmcnt(8)
	s_waitcnt lgkmcnt(0)
	s_setprio 1
	s_barrier
	v_mfma_f32_16x16x32_bf16 v[134:137], v[74:77], v[188:191], 0
	v_mfma_f32_16x16x32_bf16 v[130:133], v[138:141], v[188:191], 0
	v_mfma_f32_16x16x32_bf16 v[118:121], v[74:77], v[204:207], 0
	v_mfma_f32_16x16x32_bf16 v[114:117], v[138:141], v[204:207], 0
	v_mfma_f32_16x16x32_bf16 v[102:105], v[74:77], v[212:215], 0
	v_mfma_f32_16x16x32_bf16 v[98:101], v[138:141], v[212:215], 0
	v_mfma_f32_16x16x32_bf16 v[86:89], v[74:77], v[220:223], 0
	v_mfma_f32_16x16x32_bf16 v[82:85], v[138:141], v[220:223], 0
	v_mfma_f32_16x16x32_bf16 v[134:137], v[78:81], v[196:199], v[134:137]
	v_mfma_f32_16x16x32_bf16 v[130:133], v[142:145], v[196:199], v[130:133]
	v_mfma_f32_16x16x32_bf16 v[118:121], v[78:81], v[208:211], v[118:121]
	v_mfma_f32_16x16x32_bf16 v[114:117], v[142:145], v[208:211], v[114:117]
	v_mfma_f32_16x16x32_bf16 v[102:105], v[78:81], v[216:219], v[102:105]
	v_mfma_f32_16x16x32_bf16 v[98:101], v[142:145], v[216:219], v[98:101]
	v_mfma_f32_16x16x32_bf16 v[86:89], v[78:81], v[224:227], v[86:89]
	v_mfma_f32_16x16x32_bf16 v[82:85], v[142:145], v[224:227], v[82:85]
	v_mfma_f32_16x16x32_bf16 v[126:129], v[146:149], v[188:191], 0
	v_mfma_f32_16x16x32_bf16 v[122:125], v[154:157], v[188:191], 0
	v_mfma_f32_16x16x32_bf16 v[110:113], v[146:149], v[204:207], 0
	v_mfma_f32_16x16x32_bf16 v[106:109], v[154:157], v[204:207], 0
	v_mfma_f32_16x16x32_bf16 v[94:97], v[146:149], v[212:215], 0
	v_mfma_f32_16x16x32_bf16 v[90:93], v[154:157], v[212:215], 0
	v_mfma_f32_16x16x32_bf16 v[70:73], v[146:149], v[220:223], 0
	v_mfma_f32_16x16x32_bf16 v[66:69], v[154:157], v[220:223], 0
	v_mfma_f32_16x16x32_bf16 v[126:129], v[150:153], v[196:199], v[126:129]
	v_mfma_f32_16x16x32_bf16 v[122:125], v[158:161], v[196:199], v[122:125]
	v_mfma_f32_16x16x32_bf16 v[110:113], v[150:153], v[208:211], v[110:113]
	v_mfma_f32_16x16x32_bf16 v[106:109], v[158:161], v[208:211], v[106:109]
	v_mfma_f32_16x16x32_bf16 v[94:97], v[150:153], v[216:219], v[94:97]
	v_mfma_f32_16x16x32_bf16 v[90:93], v[158:161], v[216:219], v[90:93]
	v_mfma_f32_16x16x32_bf16 v[70:73], v[150:153], v[224:227], v[70:73]
	v_mfma_f32_16x16x32_bf16 v[66:69], v[158:161], v[224:227], v[66:69]
	s_barrier
	s_setprio 0
	s_add_i32 s16, s29, s4
	v_lshl_add_u64 v[170:171], s[44:45], 0, v[178:179]
	s_mov_b32 m0, s16
	ds_read_b128 v[188:191], v195 offset:16384
	ds_read_b128 v[196:199], v195 offset:17408
	ds_read_b128 v[204:207], v195 offset:18432
	ds_read_b128 v[208:211], v195 offset:19456
	ds_read_b128 v[212:215], v195 offset:20480
	ds_read_b128 v[216:219], v195 offset:21504
	ds_read_b128 v[220:223], v195 offset:22528
	ds_read_b128 v[224:227], v195 offset:23552
	global_load_lds_dwordx4 v[170:171], off
	s_add_i32 m0, s16, 0x2000
	s_add_u32 s16, s44, 0x28000
	v_lshl_add_u64 v[172:173], s[44:45], 0, v[174:175]
	s_addc_u32 s17, s45, 0
	s_add_i32 s29, s74, s4
	global_load_lds_dwordx4 v[172:173], off
	v_lshl_add_u64 v[228:229], s[16:17], 0, v[178:179]
	s_mov_b32 m0, s29
	v_lshl_add_u64 v[230:231], s[48:49], 0, v[176:177]
	global_load_lds_dwordx4 v[228:229], off
	v_lshl_add_u64 v[228:229], s[16:17], 0, v[174:175]
	s_add_i32 m0, s29, 0x2000
	s_nop 0
	global_load_lds_dwordx4 v[228:229], off
	v_lshl_add_u64 v[228:229], s[48:49], 0, v[180:181]
	s_mov_b32 m0, s5
	s_nop 0
	global_load_lds_dwordx4 v[228:229], off
	s_mov_b32 m0, s20
	s_nop 0
	global_load_lds_dwordx4 v[230:231], off
	s_waitcnt vmcnt(8)
	s_waitcnt lgkmcnt(0)
	s_setprio 1
	s_barrier
	v_mfma_f32_16x16x32_bf16 v[62:65], v[74:77], v[188:191], 0
	v_mfma_f32_16x16x32_bf16 v[58:61], v[138:141], v[188:191], 0
	v_mfma_f32_16x16x32_bf16 v[46:49], v[74:77], v[204:207], 0
	v_mfma_f32_16x16x32_bf16 v[42:45], v[138:141], v[204:207], 0
	v_mfma_f32_16x16x32_bf16 v[30:33], v[74:77], v[212:215], 0
	v_mfma_f32_16x16x32_bf16 v[26:29], v[138:141], v[212:215], 0
	v_mfma_f32_16x16x32_bf16 v[14:17], v[74:77], v[220:223], 0
	v_mfma_f32_16x16x32_bf16 v[10:13], v[138:141], v[220:223], 0
	v_mfma_f32_16x16x32_bf16 v[62:65], v[78:81], v[196:199], v[62:65]
	v_mfma_f32_16x16x32_bf16 v[58:61], v[142:145], v[196:199], v[58:61]
	v_mfma_f32_16x16x32_bf16 v[46:49], v[78:81], v[208:211], v[46:49]
	v_mfma_f32_16x16x32_bf16 v[42:45], v[142:145], v[208:211], v[42:45]
	v_mfma_f32_16x16x32_bf16 v[30:33], v[78:81], v[216:219], v[30:33]
	v_mfma_f32_16x16x32_bf16 v[26:29], v[142:145], v[216:219], v[26:29]
	v_mfma_f32_16x16x32_bf16 v[14:17], v[78:81], v[224:227], v[14:17]
	v_mfma_f32_16x16x32_bf16 v[10:13], v[142:145], v[224:227], v[10:13]
	v_mfma_f32_16x16x32_bf16 v[54:57], v[146:149], v[188:191], 0
	v_mfma_f32_16x16x32_bf16 v[50:53], v[154:157], v[188:191], 0
	v_mfma_f32_16x16x32_bf16 v[38:41], v[146:149], v[204:207], 0
	v_mfma_f32_16x16x32_bf16 v[34:37], v[154:157], v[204:207], 0
	v_mfma_f32_16x16x32_bf16 v[22:25], v[146:149], v[212:215], 0
	v_mfma_f32_16x16x32_bf16 v[18:21], v[154:157], v[212:215], 0
	v_mfma_f32_16x16x32_bf16 v[6:9], v[146:149], v[220:223], 0
	v_mfma_f32_16x16x32_bf16 v[2:5], v[154:157], v[220:223], 0
	v_mfma_f32_16x16x32_bf16 v[54:57], v[150:153], v[196:199], v[54:57]
	v_mfma_f32_16x16x32_bf16 v[50:53], v[158:161], v[196:199], v[50:53]
	v_mfma_f32_16x16x32_bf16 v[38:41], v[150:153], v[208:211], v[38:41]
	v_mfma_f32_16x16x32_bf16 v[34:37], v[158:161], v[208:211], v[34:37]
	v_mfma_f32_16x16x32_bf16 v[22:25], v[150:153], v[216:219], v[22:25]
	v_mfma_f32_16x16x32_bf16 v[18:21], v[158:161], v[216:219], v[18:21]
	v_mfma_f32_16x16x32_bf16 v[6:9], v[150:153], v[224:227], v[6:9]
	v_mfma_f32_16x16x32_bf16 v[2:5], v[158:161], v[224:227], v[2:5]
	s_barrier
	s_setprio 0
	s_add_i32 s29, 0, 0x18000
	s_add_i32 s74, 0, 0x1c000
	v_add_u32_e32 v142, s29, v193
	v_add_u32_e32 v158, s74, v193
	ds_read_b128 v[74:77], v142
	ds_read_b128 v[78:81], v142 offset:1024
	ds_read_b128 v[138:141], v142 offset:2048
	ds_read_b128 v[142:145], v142 offset:3072
	ds_read_b128 v[146:149], v158
	ds_read_b128 v[150:153], v158 offset:1024
	ds_read_b128 v[154:157], v158 offset:2048
	ds_read_b128 v[158:161], v158 offset:3072
	s_add_u32 s16, s48, 0x28000
	s_addc_u32 s17, s49, 0
	s_mov_b32 m0, s22
	v_lshl_add_u64 v[232:233], s[16:17], 0, v[180:181]
	ds_read_b128 v[188:191], v195 offset:32768
	ds_read_b128 v[196:199], v195 offset:33792
	ds_read_b128 v[204:207], v195 offset:34816
	ds_read_b128 v[208:211], v195 offset:35840
	ds_read_b128 v[212:215], v195 offset:36864
	ds_read_b128 v[216:219], v195 offset:37888
	ds_read_b128 v[220:223], v195 offset:38912
	ds_read_b128 v[224:227], v195 offset:39936
	global_load_lds_dwordx4 v[232:233], off
	v_lshl_add_u64 v[232:233], s[16:17], 0, v[176:177]
	s_mov_b32 m0, s23
	s_nop 0
	global_load_lds_dwordx4 v[232:233], off
	s_waitcnt vmcnt(8)
	s_waitcnt lgkmcnt(0)
	s_setprio 1
	s_barrier
	v_mfma_f32_16x16x32_bf16 v[134:137], v[74:77], v[188:191], v[134:137]
	v_mfma_f32_16x16x32_bf16 v[130:133], v[138:141], v[188:191], v[130:133]
	v_mfma_f32_16x16x32_bf16 v[118:121], v[74:77], v[204:207], v[118:121]
	v_mfma_f32_16x16x32_bf16 v[114:117], v[138:141], v[204:207], v[114:117]
	v_mfma_f32_16x16x32_bf16 v[102:105], v[74:77], v[212:215], v[102:105]
	v_mfma_f32_16x16x32_bf16 v[98:101], v[138:141], v[212:215], v[98:101]
	v_mfma_f32_16x16x32_bf16 v[86:89], v[74:77], v[220:223], v[86:89]
	v_mfma_f32_16x16x32_bf16 v[82:85], v[138:141], v[220:223], v[82:85]
	v_mfma_f32_16x16x32_bf16 v[134:137], v[78:81], v[196:199], v[134:137]
	v_mfma_f32_16x16x32_bf16 v[130:133], v[142:145], v[196:199], v[130:133]
	v_mfma_f32_16x16x32_bf16 v[118:121], v[78:81], v[208:211], v[118:121]
	v_mfma_f32_16x16x32_bf16 v[114:117], v[142:145], v[208:211], v[114:117]
	v_mfma_f32_16x16x32_bf16 v[102:105], v[78:81], v[216:219], v[102:105]
	v_mfma_f32_16x16x32_bf16 v[98:101], v[142:145], v[216:219], v[98:101]
	v_mfma_f32_16x16x32_bf16 v[86:89], v[78:81], v[224:227], v[86:89]
	v_mfma_f32_16x16x32_bf16 v[82:85], v[142:145], v[224:227], v[82:85]
	v_mfma_f32_16x16x32_bf16 v[126:129], v[146:149], v[188:191], v[126:129]
	v_mfma_f32_16x16x32_bf16 v[122:125], v[154:157], v[188:191], v[122:125]
	v_mfma_f32_16x16x32_bf16 v[110:113], v[146:149], v[204:207], v[110:113]
	v_mfma_f32_16x16x32_bf16 v[106:109], v[154:157], v[204:207], v[106:109]
	v_mfma_f32_16x16x32_bf16 v[94:97], v[146:149], v[212:215], v[94:97]
	v_mfma_f32_16x16x32_bf16 v[90:93], v[154:157], v[212:215], v[90:93]
	v_mfma_f32_16x16x32_bf16 v[70:73], v[146:149], v[220:223], v[70:73]
	v_mfma_f32_16x16x32_bf16 v[66:69], v[154:157], v[220:223], v[66:69]
	v_mfma_f32_16x16x32_bf16 v[126:129], v[150:153], v[196:199], v[126:129]
	v_mfma_f32_16x16x32_bf16 v[122:125], v[158:161], v[196:199], v[122:125]
	v_mfma_f32_16x16x32_bf16 v[110:113], v[150:153], v[208:211], v[110:113]
	v_mfma_f32_16x16x32_bf16 v[106:109], v[158:161], v[208:211], v[106:109]
	v_mfma_f32_16x16x32_bf16 v[94:97], v[150:153], v[216:219], v[94:97]
	v_mfma_f32_16x16x32_bf16 v[90:93], v[158:161], v[216:219], v[90:93]
	v_mfma_f32_16x16x32_bf16 v[70:73], v[150:153], v[224:227], v[70:73]
	v_mfma_f32_16x16x32_bf16 v[66:69], v[158:161], v[224:227], v[66:69]
	s_barrier
	s_setprio 0
	s_add_i32 s16, s29, s4
	v_lshl_add_u64 v[170:171], v[170:171], 0, s[24:25]
	s_mov_b32 m0, s16
	ds_read_b128 v[188:191], v195 offset:49152
	ds_read_b128 v[196:199], v195 offset:50176
	ds_read_b128 v[204:207], v195 offset:51200
	ds_read_b128 v[208:211], v195 offset:52224
	ds_read_b128 v[212:215], v195 offset:53248
	ds_read_b128 v[216:219], v195 offset:54272
	ds_read_b128 v[220:223], v195 offset:55296
	ds_read_b128 v[224:227], v195 offset:56320
	global_load_lds_dwordx4 v[170:171], off
	s_add_i32 m0, s16, 0x2000
	s_add_u32 s16, s44, 0x28080
	v_lshl_add_u64 v[170:171], v[172:173], 0, s[24:25]
	s_addc_u32 s17, s45, 0
	s_add_i32 s29, s74, s4
	global_load_lds_dwordx4 v[170:171], off
	v_lshl_add_u64 v[170:171], s[16:17], 0, v[178:179]
	s_mov_b32 m0, s29
	s_nop 0
	global_load_lds_dwordx4 v[170:171], off
	v_lshl_add_u64 v[170:171], s[16:17], 0, v[174:175]
	s_add_i32 m0, s29, 0x2000
	s_nop 0
	global_load_lds_dwordx4 v[170:171], off
	v_lshl_add_u64 v[170:171], v[228:229], 0, s[24:25]
	s_mov_b32 m0, s31
	s_nop 0
	global_load_lds_dwordx4 v[170:171], off
	v_lshl_add_u64 v[170:171], v[230:231], 0, s[24:25]
	s_mov_b32 m0, s33
	s_nop 0
	global_load_lds_dwordx4 v[170:171], off
	s_waitcnt vmcnt(8)
	s_waitcnt lgkmcnt(0)
	s_setprio 1
	s_barrier
	v_mfma_f32_16x16x32_bf16 v[62:65], v[74:77], v[188:191], v[62:65]
	v_mfma_f32_16x16x32_bf16 v[58:61], v[138:141], v[188:191], v[58:61]
	v_mfma_f32_16x16x32_bf16 v[46:49], v[74:77], v[204:207], v[46:49]
	v_mfma_f32_16x16x32_bf16 v[42:45], v[138:141], v[204:207], v[42:45]
	v_mfma_f32_16x16x32_bf16 v[30:33], v[74:77], v[212:215], v[30:33]
	v_mfma_f32_16x16x32_bf16 v[26:29], v[138:141], v[212:215], v[26:29]
	v_mfma_f32_16x16x32_bf16 v[14:17], v[74:77], v[220:223], v[14:17]
	v_mfma_f32_16x16x32_bf16 v[10:13], v[138:141], v[220:223], v[10:13]
	v_mfma_f32_16x16x32_bf16 v[62:65], v[78:81], v[196:199], v[62:65]
	v_mfma_f32_16x16x32_bf16 v[58:61], v[142:145], v[196:199], v[58:61]
	v_mfma_f32_16x16x32_bf16 v[46:49], v[78:81], v[208:211], v[46:49]
	v_mfma_f32_16x16x32_bf16 v[42:45], v[142:145], v[208:211], v[42:45]
	v_mfma_f32_16x16x32_bf16 v[30:33], v[78:81], v[216:219], v[30:33]
	v_mfma_f32_16x16x32_bf16 v[26:29], v[142:145], v[216:219], v[26:29]
	v_mfma_f32_16x16x32_bf16 v[14:17], v[78:81], v[224:227], v[14:17]
	v_mfma_f32_16x16x32_bf16 v[10:13], v[142:145], v[224:227], v[10:13]
	v_mfma_f32_16x16x32_bf16 v[54:57], v[146:149], v[188:191], v[54:57]
	v_mfma_f32_16x16x32_bf16 v[50:53], v[154:157], v[188:191], v[50:53]
	v_mfma_f32_16x16x32_bf16 v[38:41], v[146:149], v[204:207], v[38:41]
	v_mfma_f32_16x16x32_bf16 v[34:37], v[154:157], v[204:207], v[34:37]
	v_mfma_f32_16x16x32_bf16 v[22:25], v[146:149], v[212:215], v[22:25]
	v_mfma_f32_16x16x32_bf16 v[18:21], v[154:157], v[212:215], v[18:21]
	v_mfma_f32_16x16x32_bf16 v[6:9], v[146:149], v[220:223], v[6:9]
	v_mfma_f32_16x16x32_bf16 v[2:5], v[154:157], v[220:223], v[2:5]
	v_mfma_f32_16x16x32_bf16 v[54:57], v[150:153], v[196:199], v[54:57]
	v_mfma_f32_16x16x32_bf16 v[50:53], v[158:161], v[196:199], v[50:53]
	v_mfma_f32_16x16x32_bf16 v[38:41], v[150:153], v[208:211], v[38:41]
	v_mfma_f32_16x16x32_bf16 v[34:37], v[158:161], v[208:211], v[34:37]
	v_mfma_f32_16x16x32_bf16 v[22:25], v[150:153], v[216:219], v[22:25]
	v_mfma_f32_16x16x32_bf16 v[18:21], v[158:161], v[216:219], v[18:21]
	v_mfma_f32_16x16x32_bf16 v[6:9], v[150:153], v[224:227], v[6:9]
	v_mfma_f32_16x16x32_bf16 v[2:5], v[158:161], v[224:227], v[2:5]
	s_barrier
	s_setprio 0
	s_add_u32 s72, s72, 0x100
	s_addc_u32 s73, s73, 0
	s_cmp_ge_i32 s37, s38
	s_mov_b64 s[16:17], s[42:43]
	s_mov_b32 s44, s37
	s_cbranch_scc0 .LBB7_886
	s_branch .Lpeelx_886
	.p2align	6

.Lpeel_963:
	s_add_i32 s37, s48, 2
	s_add_u32 s42, s16, 0x100
	s_addc_u32 s43, s17, 0
	s_add_i32 s29, 0, 0x10000
	s_cmp_eq_u32 s53, s48
	s_cselect_b32 s51, s38, s43
	s_cselect_b32 s50, s39, s42
	s_cselect_b32 s49, s56, s73
	s_cselect_b32 s48, s57, s72
	s_add_i32 s74, 0, 0x14000
	v_add_u32_e32 v142, s29, v197
	v_add_u32_e32 v158, s74, v197
	ds_read_b128 v[130:133], v142
	ds_read_b128 v[134:137], v142 offset:1024
	ds_read_b128 v[138:141], v142 offset:2048
	ds_read_b128 v[142:145], v142 offset:3072
	ds_read_b128 v[146:149], v158
	ds_read_b128 v[150:153], v158 offset:1024
	ds_read_b128 v[154:157], v158 offset:2048
	ds_read_b128 v[158:161], v158 offset:3072
	v_lshl_add_u64 v[170:171], s[16:17], 0, v[180:181]
	s_add_i32 m0, s5, 0xc000
	ds_read_b128 v[184:187], v199
	ds_read_b128 v[188:191], v199 offset:1024
	ds_read_b128 v[192:195], v199 offset:2048
	ds_read_b128 v[204:207], v199 offset:3072
	ds_read_b128 v[208:211], v199 offset:4096
	ds_read_b128 v[212:215], v199 offset:5120
	ds_read_b128 v[216:219], v199 offset:6144
	ds_read_b128 v[220:223], v199 offset:7168
	global_load_lds_dwordx4 v[170:171], off
	v_lshl_add_u64 v[170:171], s[16:17], 0, v[182:183]
	s_add_i32 m0, s5, 0xe000
	s_nop 0
	global_load_lds_dwordx4 v[170:171], off
	s_waitcnt vmcnt(8)
	s_waitcnt lgkmcnt(0)
	s_setprio 1
	s_barrier
	v_mfma_f32_16x16x32_bf16 v[126:129], v[130:133], v[184:187], 0
	v_mfma_f32_16x16x32_bf16 v[122:125], v[138:141], v[184:187], 0
	v_mfma_f32_16x16x32_bf16 v[110:113], v[130:133], v[192:195], 0
	v_mfma_f32_16x16x32_bf16 v[106:109], v[138:141], v[192:195], 0
	v_mfma_f32_16x16x32_bf16 v[94:97], v[130:133], v[208:211], 0
	v_mfma_f32_16x16x32_bf16 v[90:93], v[138:141], v[208:211], 0
	v_mfma_f32_16x16x32_bf16 v[78:81], v[130:133], v[216:219], 0
	v_mfma_f32_16x16x32_bf16 v[74:77], v[138:141], v[216:219], 0
	v_mfma_f32_16x16x32_bf16 v[126:129], v[134:137], v[188:191], v[126:129]
	v_mfma_f32_16x16x32_bf16 v[122:125], v[142:145], v[188:191], v[122:125]
	v_mfma_f32_16x16x32_bf16 v[110:113], v[134:137], v[204:207], v[110:113]
	v_mfma_f32_16x16x32_bf16 v[106:109], v[142:145], v[204:207], v[106:109]
	v_mfma_f32_16x16x32_bf16 v[94:97], v[134:137], v[212:215], v[94:97]
	v_mfma_f32_16x16x32_bf16 v[90:93], v[142:145], v[212:215], v[90:93]
	v_mfma_f32_16x16x32_bf16 v[78:81], v[134:137], v[220:223], v[78:81]
	v_mfma_f32_16x16x32_bf16 v[74:77], v[142:145], v[220:223], v[74:77]
	v_mfma_f32_16x16x32_bf16 v[118:121], v[146:149], v[184:187], 0
	v_mfma_f32_16x16x32_bf16 v[114:117], v[154:157], v[184:187], 0
	v_mfma_f32_16x16x32_bf16 v[102:105], v[146:149], v[192:195], 0
	v_mfma_f32_16x16x32_bf16 v[98:101], v[154:157], v[192:195], 0
	v_mfma_f32_16x16x32_bf16 v[86:89], v[146:149], v[208:211], 0
	v_mfma_f32_16x16x32_bf16 v[82:85], v[154:157], v[208:211], 0
	v_mfma_f32_16x16x32_bf16 v[70:73], v[146:149], v[216:219], 0
	v_mfma_f32_16x16x32_bf16 v[66:69], v[154:157], v[216:219], 0
	v_mfma_f32_16x16x32_bf16 v[118:121], v[150:153], v[188:191], v[118:121]
	v_mfma_f32_16x16x32_bf16 v[114:117], v[158:161], v[188:191], v[114:117]
	v_mfma_f32_16x16x32_bf16 v[102:105], v[150:153], v[204:207], v[102:105]
	v_mfma_f32_16x16x32_bf16 v[98:101], v[158:161], v[204:207], v[98:101]
	v_mfma_f32_16x16x32_bf16 v[86:89], v[150:153], v[212:215], v[86:89]
	v_mfma_f32_16x16x32_bf16 v[82:85], v[158:161], v[212:215], v[82:85]
	v_mfma_f32_16x16x32_bf16 v[70:73], v[150:153], v[220:223], v[70:73]
	v_mfma_f32_16x16x32_bf16 v[66:69], v[158:161], v[220:223], v[66:69]
	s_barrier
	s_setprio 0
	s_add_i32 s16, s29, s4
	v_lshl_add_u64 v[170:171], s[48:49], 0, v[0:1]
	s_mov_b32 m0, s16
	ds_read_b128 v[184:187], v199 offset:16384
	ds_read_b128 v[188:191], v199 offset:17408
	ds_read_b128 v[192:195], v199 offset:18432
	ds_read_b128 v[204:207], v199 offset:19456
	ds_read_b128 v[208:211], v199 offset:20480
	ds_read_b128 v[212:215], v199 offset:21504
	ds_read_b128 v[216:219], v199 offset:22528
	ds_read_b128 v[220:223], v199 offset:23552
	global_load_lds_dwordx4 v[170:171], off
	s_add_i32 m0, s16, 0x2000
	s_add_u32 s16, s48, 0x18000
	v_lshl_add_u64 v[172:173], s[48:49], 0, v[174:175]
	s_addc_u32 s17, s49, 0
	s_add_i32 s29, s74, s4
	global_load_lds_dwordx4 v[172:173], off
	v_lshl_add_u64 v[224:225], s[16:17], 0, v[0:1]
	s_mov_b32 m0, s29
	v_lshl_add_u64 v[226:227], s[50:51], 0, v[176:177]
	global_load_lds_dwordx4 v[224:225], off
	v_lshl_add_u64 v[224:225], s[16:17], 0, v[174:175]
	s_add_i32 m0, s29, 0x2000
	s_nop 0
	global_load_lds_dwordx4 v[224:225], off
	v_lshl_add_u64 v[224:225], s[50:51], 0, v[178:179]
	s_mov_b32 m0, s5
	s_nop 0
	global_load_lds_dwordx4 v[224:225], off
	s_mov_b32 m0, s20
	s_nop 0
	global_load_lds_dwordx4 v[226:227], off
	s_waitcnt vmcnt(8)
	s_waitcnt lgkmcnt(0)
	s_setprio 1
	s_barrier
	v_mfma_f32_16x16x32_bf16 v[62:65], v[130:133], v[184:187], 0
	v_mfma_f32_16x16x32_bf16 v[58:61], v[138:141], v[184:187], 0
	v_mfma_f32_16x16x32_bf16 v[46:49], v[130:133], v[192:195], 0
	v_mfma_f32_16x16x32_bf16 v[42:45], v[138:141], v[192:195], 0
	v_mfma_f32_16x16x32_bf16 v[30:33], v[130:133], v[208:211], 0
	v_mfma_f32_16x16x32_bf16 v[26:29], v[138:141], v[208:211], 0
	v_mfma_f32_16x16x32_bf16 v[14:17], v[130:133], v[216:219], 0
	v_mfma_f32_16x16x32_bf16 v[10:13], v[138:141], v[216:219], 0
	v_mfma_f32_16x16x32_bf16 v[62:65], v[134:137], v[188:191], v[62:65]
	v_mfma_f32_16x16x32_bf16 v[58:61], v[142:145], v[188:191], v[58:61]
	v_mfma_f32_16x16x32_bf16 v[46:49], v[134:137], v[204:207], v[46:49]
	v_mfma_f32_16x16x32_bf16 v[42:45], v[142:145], v[204:207], v[42:45]
	v_mfma_f32_16x16x32_bf16 v[30:33], v[134:137], v[212:215], v[30:33]
	v_mfma_f32_16x16x32_bf16 v[26:29], v[142:145], v[212:215], v[26:29]
	v_mfma_f32_16x16x32_bf16 v[14:17], v[134:137], v[220:223], v[14:17]
	v_mfma_f32_16x16x32_bf16 v[10:13], v[142:145], v[220:223], v[10:13]
	v_mfma_f32_16x16x32_bf16 v[54:57], v[146:149], v[184:187], 0
	v_mfma_f32_16x16x32_bf16 v[50:53], v[154:157], v[184:187], 0
	v_mfma_f32_16x16x32_bf16 v[38:41], v[146:149], v[192:195], 0
	v_mfma_f32_16x16x32_bf16 v[34:37], v[154:157], v[192:195], 0
	v_mfma_f32_16x16x32_bf16 v[22:25], v[146:149], v[208:211], 0
	v_mfma_f32_16x16x32_bf16 v[18:21], v[154:157], v[208:211], 0
	v_mfma_f32_16x16x32_bf16 v[6:9], v[146:149], v[216:219], 0
	v_mfma_f32_16x16x32_bf16 v[2:5], v[154:157], v[216:219], 0
	v_mfma_f32_16x16x32_bf16 v[54:57], v[150:153], v[188:191], v[54:57]
	v_mfma_f32_16x16x32_bf16 v[50:53], v[158:161], v[188:191], v[50:53]
	v_mfma_f32_16x16x32_bf16 v[38:41], v[150:153], v[204:207], v[38:41]
	v_mfma_f32_16x16x32_bf16 v[34:37], v[158:161], v[204:207], v[34:37]
	v_mfma_f32_16x16x32_bf16 v[22:25], v[150:153], v[212:215], v[22:25]
	v_mfma_f32_16x16x32_bf16 v[18:21], v[158:161], v[212:215], v[18:21]
	v_mfma_f32_16x16x32_bf16 v[6:9], v[150:153], v[220:223], v[6:9]
	v_mfma_f32_16x16x32_bf16 v[2:5], v[158:161], v[220:223], v[2:5]
	s_barrier
	s_setprio 0
	s_add_i32 s29, 0, 0x18000
	s_add_i32 s74, 0, 0x1c000
	v_add_u32_e32 v142, s29, v197
	v_add_u32_e32 v158, s74, v197
	ds_read_b128 v[130:133], v142
	ds_read_b128 v[134:137], v142 offset:1024
	ds_read_b128 v[138:141], v142 offset:2048
	ds_read_b128 v[142:145], v142 offset:3072
	ds_read_b128 v[146:149], v158
	ds_read_b128 v[150:153], v158 offset:1024
	ds_read_b128 v[154:157], v158 offset:2048
	ds_read_b128 v[158:161], v158 offset:3072
	s_add_u32 s16, s50, 0x18000
	s_addc_u32 s17, s51, 0
	s_mov_b32 m0, s22
	v_lshl_add_u64 v[228:229], s[16:17], 0, v[178:179]
	ds_read_b128 v[184:187], v199 offset:32768
	ds_read_b128 v[188:191], v199 offset:33792
	ds_read_b128 v[192:195], v199 offset:34816
	ds_read_b128 v[204:207], v199 offset:35840
	ds_read_b128 v[208:211], v199 offset:36864
	ds_read_b128 v[212:215], v199 offset:37888
	ds_read_b128 v[216:219], v199 offset:38912
	ds_read_b128 v[220:223], v199 offset:39936
	global_load_lds_dwordx4 v[228:229], off
	v_lshl_add_u64 v[228:229], s[16:17], 0, v[176:177]
	s_mov_b32 m0, s23
	s_nop 0
	global_load_lds_dwordx4 v[228:229], off
	s_waitcnt vmcnt(8)
	s_waitcnt lgkmcnt(0)
	s_setprio 1
	s_barrier
	v_mfma_f32_16x16x32_bf16 v[126:129], v[130:133], v[184:187], v[126:129]
	v_mfma_f32_16x16x32_bf16 v[122:125], v[138:141], v[184:187], v[122:125]
	v_mfma_f32_16x16x32_bf16 v[110:113], v[130:133], v[192:195], v[110:113]
	v_mfma_f32_16x16x32_bf16 v[106:109], v[138:141], v[192:195], v[106:109]
	v_mfma_f32_16x16x32_bf16 v[94:97], v[130:133], v[208:211], v[94:97]
	v_mfma_f32_16x16x32_bf16 v[90:93], v[138:141], v[208:211], v[90:93]
	v_mfma_f32_16x16x32_bf16 v[78:81], v[130:133], v[216:219], v[78:81]
	v_mfma_f32_16x16x32_bf16 v[74:77], v[138:141], v[216:219], v[74:77]
	v_mfma_f32_16x16x32_bf16 v[126:129], v[134:137], v[188:191], v[126:129]
	v_mfma_f32_16x16x32_bf16 v[122:125], v[142:145], v[188:191], v[122:125]
	v_mfma_f32_16x16x32_bf16 v[110:113], v[134:137], v[204:207], v[110:113]
	v_mfma_f32_16x16x32_bf16 v[106:109], v[142:145], v[204:207], v[106:109]
	v_mfma_f32_16x16x32_bf16 v[94:97], v[134:137], v[212:215], v[94:97]
	v_mfma_f32_16x16x32_bf16 v[90:93], v[142:145], v[212:215], v[90:93]
	v_mfma_f32_16x16x32_bf16 v[78:81], v[134:137], v[220:223], v[78:81]
	v_mfma_f32_16x16x32_bf16 v[74:77], v[142:145], v[220:223], v[74:77]
	v_mfma_f32_16x16x32_bf16 v[118:121], v[146:149], v[184:187], v[118:121]
	v_mfma_f32_16x16x32_bf16 v[114:117], v[154:157], v[184:187], v[114:117]
	v_mfma_f32_16x16x32_bf16 v[102:105], v[146:149], v[192:195], v[102:105]
	v_mfma_f32_16x16x32_bf16 v[98:101], v[154:157], v[192:195], v[98:101]
	v_mfma_f32_16x16x32_bf16 v[86:89], v[146:149], v[208:211], v[86:89]
	v_mfma_f32_16x16x32_bf16 v[82:85], v[154:157], v[208:211], v[82:85]
	v_mfma_f32_16x16x32_bf16 v[70:73], v[146:149], v[216:219], v[70:73]
	v_mfma_f32_16x16x32_bf16 v[66:69], v[154:157], v[216:219], v[66:69]
	v_mfma_f32_16x16x32_bf16 v[118:121], v[150:153], v[188:191], v[118:121]
	v_mfma_f32_16x16x32_bf16 v[114:117], v[158:161], v[188:191], v[114:117]
	v_mfma_f32_16x16x32_bf16 v[102:105], v[150:153], v[204:207], v[102:105]
	v_mfma_f32_16x16x32_bf16 v[98:101], v[158:161], v[204:207], v[98:101]
	v_mfma_f32_16x16x32_bf16 v[86:89], v[150:153], v[212:215], v[86:89]
	v_mfma_f32_16x16x32_bf16 v[82:85], v[158:161], v[212:215], v[82:85]
	v_mfma_f32_16x16x32_bf16 v[70:73], v[150:153], v[220:223], v[70:73]
	v_mfma_f32_16x16x32_bf16 v[66:69], v[158:161], v[220:223], v[66:69]
	s_barrier
	s_setprio 0
	s_add_i32 s16, s29, s4
	v_lshl_add_u64 v[170:171], v[170:171], 0, s[24:25]
	s_mov_b32 m0, s16
	ds_read_b128 v[184:187], v199 offset:49152
	ds_read_b128 v[188:191], v199 offset:50176
	ds_read_b128 v[192:195], v199 offset:51200
	ds_read_b128 v[204:207], v199 offset:52224
	ds_read_b128 v[208:211], v199 offset:53248
	ds_read_b128 v[212:215], v199 offset:54272
	ds_read_b128 v[216:219], v199 offset:55296
	ds_read_b128 v[220:223], v199 offset:56320
	global_load_lds_dwordx4 v[170:171], off
	s_add_i32 m0, s16, 0x2000
	s_add_u32 s16, s48, 0x18080
	v_lshl_add_u64 v[170:171], v[172:173], 0, s[24:25]
	s_addc_u32 s17, s49, 0
	s_add_i32 s29, s74, s4
	global_load_lds_dwordx4 v[170:171], off
	v_lshl_add_u64 v[170:171], s[16:17], 0, v[0:1]
	s_mov_b32 m0, s29
	s_nop 0
	global_load_lds_dwordx4 v[170:171], off
	v_lshl_add_u64 v[170:171], s[16:17], 0, v[174:175]
	s_add_i32 m0, s29, 0x2000
	s_nop 0
	global_load_lds_dwordx4 v[170:171], off
	v_lshl_add_u64 v[170:171], v[224:225], 0, s[24:25]
	s_mov_b32 m0, s31
	s_nop 0
	global_load_lds_dwordx4 v[170:171], off
	v_lshl_add_u64 v[170:171], v[226:227], 0, s[24:25]
	s_mov_b32 m0, s33
	s_nop 0
	global_load_lds_dwordx4 v[170:171], off
	s_waitcnt vmcnt(8)
	s_waitcnt lgkmcnt(0)
	s_setprio 1
	s_barrier
	v_mfma_f32_16x16x32_bf16 v[62:65], v[130:133], v[184:187], v[62:65]
	v_mfma_f32_16x16x32_bf16 v[58:61], v[138:141], v[184:187], v[58:61]
	v_mfma_f32_16x16x32_bf16 v[46:49], v[130:133], v[192:195], v[46:49]
	v_mfma_f32_16x16x32_bf16 v[42:45], v[138:141], v[192:195], v[42:45]
	v_mfma_f32_16x16x32_bf16 v[30:33], v[130:133], v[208:211], v[30:33]
	v_mfma_f32_16x16x32_bf16 v[26:29], v[138:141], v[208:211], v[26:29]
	v_mfma_f32_16x16x32_bf16 v[14:17], v[130:133], v[216:219], v[14:17]
	v_mfma_f32_16x16x32_bf16 v[10:13], v[138:141], v[216:219], v[10:13]
	v_mfma_f32_16x16x32_bf16 v[62:65], v[134:137], v[188:191], v[62:65]
	v_mfma_f32_16x16x32_bf16 v[58:61], v[142:145], v[188:191], v[58:61]
	v_mfma_f32_16x16x32_bf16 v[46:49], v[134:137], v[204:207], v[46:49]
	v_mfma_f32_16x16x32_bf16 v[42:45], v[142:145], v[204:207], v[42:45]
	v_mfma_f32_16x16x32_bf16 v[30:33], v[134:137], v[212:215], v[30:33]
	v_mfma_f32_16x16x32_bf16 v[26:29], v[142:145], v[212:215], v[26:29]
	v_mfma_f32_16x16x32_bf16 v[14:17], v[134:137], v[220:223], v[14:17]
	v_mfma_f32_16x16x32_bf16 v[10:13], v[142:145], v[220:223], v[10:13]
	v_mfma_f32_16x16x32_bf16 v[54:57], v[146:149], v[184:187], v[54:57]
	v_mfma_f32_16x16x32_bf16 v[50:53], v[154:157], v[184:187], v[50:53]
	v_mfma_f32_16x16x32_bf16 v[38:41], v[146:149], v[192:195], v[38:41]
	v_mfma_f32_16x16x32_bf16 v[34:37], v[154:157], v[192:195], v[34:37]
	v_mfma_f32_16x16x32_bf16 v[22:25], v[146:149], v[208:211], v[22:25]
	v_mfma_f32_16x16x32_bf16 v[18:21], v[154:157], v[208:211], v[18:21]
	v_mfma_f32_16x16x32_bf16 v[6:9], v[146:149], v[216:219], v[6:9]
	v_mfma_f32_16x16x32_bf16 v[2:5], v[154:157], v[216:219], v[2:5]
	v_mfma_f32_16x16x32_bf16 v[54:57], v[150:153], v[188:191], v[54:57]
	v_mfma_f32_16x16x32_bf16 v[50:53], v[158:161], v[188:191], v[50:53]
	v_mfma_f32_16x16x32_bf16 v[38:41], v[150:153], v[204:207], v[38:41]
	v_mfma_f32_16x16x32_bf16 v[34:37], v[158:161], v[204:207], v[34:37]
	v_mfma_f32_16x16x32_bf16 v[22:25], v[150:153], v[212:215], v[22:25]
	v_mfma_f32_16x16x32_bf16 v[18:21], v[158:161], v[212:215], v[18:21]
	v_mfma_f32_16x16x32_bf16 v[6:9], v[150:153], v[220:223], v[6:9]
	v_mfma_f32_16x16x32_bf16 v[2:5], v[158:161], v[220:223], v[2:5]
	s_barrier
	s_setprio 0
	s_add_u32 s72, s72, 0x100
	s_addc_u32 s73, s73, 0
	s_cmp_ge_i32 s37, s3
	s_mov_b64 s[16:17], s[42:43]
	s_mov_b32 s48, s37
	s_cbranch_scc0 .LBB7_963
	s_branch .Lpeelx_963
	.p2align	6

.Lpeel_1104:
	s_add_i32 s74, s72, 2
	s_add_u32 s75, vcc_lo, 0xfffc0080
	s_addc_u32 s73, vcc_hi, -1
	s_add_i32 s76, 0, 0x10000
	s_cmp_eq_u32 s39, s72
	s_cselect_b32 s73, s19, s73
	s_cselect_b32 s72, s20, s75
	v_add_u32_e32 v0, s76, v205
	s_cselect_b32 s85, s28, s49
	s_cselect_b32 s84, s29, s37
	s_add_i32 s75, 0, 0x14000
	ds_read_b128 v[132:135], v0
	ds_read_b128 v[136:139], v0 offset:1024
	ds_read_b128 v[140:143], v0 offset:2048
	ds_read_b128 v[144:147], v0 offset:3072
	v_add_u32_e32 v0, s75, v205
	ds_read_b128 v[148:151], v0
	ds_read_b128 v[152:155], v0 offset:1024
	ds_read_b128 v[156:159], v0 offset:2048
	ds_read_b128 v[184:187], v0 offset:3072
	s_waitcnt lgkmcnt(0)
	s_add_i32 m0, s5, 0xc000
	ds_read_b128 v[188:191], v207
	ds_read_b128 v[192:195], v207 offset:1024
	ds_read_b128 v[196:199], v207 offset:2048
	ds_read_b128 v[208:211], v207 offset:3072
	ds_read_b128 v[212:215], v207 offset:4096
	ds_read_b128 v[216:219], v207 offset:5120
	ds_read_b128 v[220:223], v207 offset:6144
	ds_read_b128 v[224:227], v207 offset:7168
	global_load_lds_dwordx4 v180, vcc
	s_add_i32 m0, s5, 0xe000
	s_nop 0
	global_load_lds_dwordx4 v182, vcc
	s_waitcnt vmcnt(8)
	s_waitcnt lgkmcnt(0)
	s_setprio 1
	s_barrier
	v_mfma_f32_16x16x32_bf16 v[128:131], v[132:135], v[188:191], 0
	v_mfma_f32_16x16x32_bf16 v[124:127], v[140:143], v[188:191], 0
	v_mfma_f32_16x16x32_bf16 v[120:123], v[132:135], v[196:199], 0
	v_mfma_f32_16x16x32_bf16 v[116:119], v[140:143], v[196:199], 0
	v_mfma_f32_16x16x32_bf16 v[112:115], v[132:135], v[212:215], 0
	v_mfma_f32_16x16x32_bf16 v[108:111], v[140:143], v[212:215], 0
	v_mfma_f32_16x16x32_bf16 v[104:107], v[132:135], v[220:223], 0
	v_mfma_f32_16x16x32_bf16 v[100:103], v[140:143], v[220:223], 0
	v_mfma_f32_16x16x32_bf16 v[128:131], v[136:139], v[192:195], v[128:131]
	v_mfma_f32_16x16x32_bf16 v[124:127], v[144:147], v[192:195], v[124:127]
	v_mfma_f32_16x16x32_bf16 v[120:123], v[136:139], v[208:211], v[120:123]
	v_mfma_f32_16x16x32_bf16 v[116:119], v[144:147], v[208:211], v[116:119]
	v_mfma_f32_16x16x32_bf16 v[112:115], v[136:139], v[216:219], v[112:115]
	v_mfma_f32_16x16x32_bf16 v[108:111], v[144:147], v[216:219], v[108:111]
	v_mfma_f32_16x16x32_bf16 v[104:107], v[136:139], v[224:227], v[104:107]
	v_mfma_f32_16x16x32_bf16 v[100:103], v[144:147], v[224:227], v[100:103]
	v_mfma_f32_16x16x32_bf16 v[96:99], v[148:151], v[188:191], 0
	v_mfma_f32_16x16x32_bf16 v[92:95], v[156:159], v[188:191], 0
	v_mfma_f32_16x16x32_bf16 v[88:91], v[148:151], v[196:199], 0
	v_mfma_f32_16x16x32_bf16 v[84:87], v[156:159], v[196:199], 0
	v_mfma_f32_16x16x32_bf16 v[80:83], v[148:151], v[212:215], 0
	v_mfma_f32_16x16x32_bf16 v[76:79], v[156:159], v[212:215], 0
	v_mfma_f32_16x16x32_bf16 v[72:75], v[148:151], v[220:223], 0
	v_mfma_f32_16x16x32_bf16 v[68:71], v[156:159], v[220:223], 0
	v_mfma_f32_16x16x32_bf16 v[96:99], v[152:155], v[192:195], v[96:99]
	v_mfma_f32_16x16x32_bf16 v[92:95], v[184:187], v[192:195], v[92:95]
	v_mfma_f32_16x16x32_bf16 v[88:91], v[152:155], v[208:211], v[88:91]
	v_mfma_f32_16x16x32_bf16 v[84:87], v[184:187], v[208:211], v[84:87]
	v_mfma_f32_16x16x32_bf16 v[80:83], v[152:155], v[216:219], v[80:83]
	v_mfma_f32_16x16x32_bf16 v[76:79], v[184:187], v[216:219], v[76:79]
	v_mfma_f32_16x16x32_bf16 v[72:75], v[152:155], v[224:227], v[72:75]
	v_mfma_f32_16x16x32_bf16 v[68:71], v[184:187], v[224:227], v[68:71]
	s_barrier
	s_setprio 0
	s_add_i32 s76, s76, s4
	v_lshl_add_u64 v[170:171], s[84:85], 0, v[176:177]
	s_mov_b32 m0, s76
	ds_read_b128 v[188:191], v207 offset:16384
	ds_read_b128 v[192:195], v207 offset:17408
	ds_read_b128 v[196:199], v207 offset:18432
	ds_read_b128 v[208:211], v207 offset:19456
	ds_read_b128 v[212:215], v207 offset:20480
	ds_read_b128 v[216:219], v207 offset:21504
	ds_read_b128 v[220:223], v207 offset:22528
	ds_read_b128 v[224:227], v207 offset:23552
	global_load_lds_dwordx4 v[170:171], off
	s_add_i32 m0, s76, 0x2000
	s_add_u32 s76, s84, 0x40000
	v_lshl_add_u64 v[172:173], s[84:85], 0, v[160:161]
	s_addc_u32 s77, s85, 0
	s_add_i32 s75, s75, s4
	global_load_lds_dwordx4 v[172:173], off
	s_mov_b32 m0, s75
	v_lshl_add_u64 v[228:229], s[72:73], 0, v[178:179]
	global_load_lds_dwordx4 v176, s[76:77]
	s_add_i32 m0, s75, 0x2000
	v_lshl_add_u64 v[230:231], s[72:73], 0, v[174:175]
	global_load_lds_dwordx4 v160, s[76:77]
	s_mov_b32 m0, s5
	s_nop 0
	global_load_lds_dwordx4 v[228:229], off
	s_mov_b32 m0, s22
	s_nop 0
	global_load_lds_dwordx4 v[230:231], off
	s_waitcnt vmcnt(8)
	s_waitcnt lgkmcnt(0)
	s_setprio 1
	s_barrier
	v_mfma_f32_16x16x32_bf16 v[64:67], v[132:135], v[188:191], 0
	v_mfma_f32_16x16x32_bf16 v[60:63], v[140:143], v[188:191], 0
	v_mfma_f32_16x16x32_bf16 v[56:59], v[132:135], v[196:199], 0
	v_mfma_f32_16x16x32_bf16 v[52:55], v[140:143], v[196:199], 0
	v_mfma_f32_16x16x32_bf16 v[48:51], v[132:135], v[212:215], 0
	v_mfma_f32_16x16x32_bf16 v[44:47], v[140:143], v[212:215], 0
	v_mfma_f32_16x16x32_bf16 v[40:43], v[132:135], v[220:223], 0
	v_mfma_f32_16x16x32_bf16 v[36:39], v[140:143], v[220:223], 0
	v_mfma_f32_16x16x32_bf16 v[64:67], v[136:139], v[192:195], v[64:67]
	v_mfma_f32_16x16x32_bf16 v[60:63], v[144:147], v[192:195], v[60:63]
	v_mfma_f32_16x16x32_bf16 v[56:59], v[136:139], v[208:211], v[56:59]
	v_mfma_f32_16x16x32_bf16 v[52:55], v[144:147], v[208:211], v[52:55]
	v_mfma_f32_16x16x32_bf16 v[48:51], v[136:139], v[216:219], v[48:51]
	v_mfma_f32_16x16x32_bf16 v[44:47], v[144:147], v[216:219], v[44:47]
	v_mfma_f32_16x16x32_bf16 v[40:43], v[136:139], v[224:227], v[40:43]
	v_mfma_f32_16x16x32_bf16 v[36:39], v[144:147], v[224:227], v[36:39]
	v_mfma_f32_16x16x32_bf16 v[32:35], v[148:151], v[188:191], 0
	v_mfma_f32_16x16x32_bf16 v[28:31], v[156:159], v[188:191], 0
	v_mfma_f32_16x16x32_bf16 v[24:27], v[148:151], v[196:199], 0
	v_mfma_f32_16x16x32_bf16 v[20:23], v[156:159], v[196:199], 0
	v_mfma_f32_16x16x32_bf16 v[16:19], v[148:151], v[212:215], 0
	v_mfma_f32_16x16x32_bf16 v[12:15], v[156:159], v[212:215], 0
	v_mfma_f32_16x16x32_bf16 v[8:11], v[148:151], v[220:223], 0
	v_mfma_f32_16x16x32_bf16 v[2:5], v[156:159], v[220:223], 0
	v_mfma_f32_16x16x32_bf16 v[32:35], v[152:155], v[192:195], v[32:35]
	v_mfma_f32_16x16x32_bf16 v[28:31], v[184:187], v[192:195], v[28:31]
	v_mfma_f32_16x16x32_bf16 v[24:27], v[152:155], v[208:211], v[24:27]
	v_mfma_f32_16x16x32_bf16 v[20:23], v[184:187], v[208:211], v[20:23]
	v_mfma_f32_16x16x32_bf16 v[16:19], v[152:155], v[216:219], v[16:19]
	v_mfma_f32_16x16x32_bf16 v[12:15], v[184:187], v[216:219], v[12:15]
	v_mfma_f32_16x16x32_bf16 v[8:11], v[152:155], v[224:227], v[8:11]
	v_mfma_f32_16x16x32_bf16 v[2:5], v[184:187], v[224:227], v[2:5]
	s_barrier
	s_setprio 0
	s_add_i32 s75, 0, 0x18000
	v_add_u32_e32 v0, s75, v205
	s_add_i32 s76, 0, 0x1c000
	ds_read_b128 v[132:135], v0
	ds_read_b128 v[136:139], v0 offset:1024
	ds_read_b128 v[140:143], v0 offset:2048
	ds_read_b128 v[144:147], v0 offset:3072
	v_add_u32_e32 v0, s76, v205
	ds_read_b128 v[148:151], v0
	ds_read_b128 v[152:155], v0 offset:1024
	ds_read_b128 v[156:159], v0 offset:2048
	ds_read_b128 v[184:187], v0 offset:3072
	s_add_u32 s72, s72, 0x40000
	s_addc_u32 s73, s73, 0
	s_mov_b32 m0, s23
	ds_read_b128 v[188:191], v207 offset:32768
	ds_read_b128 v[192:195], v207 offset:33792
	ds_read_b128 v[196:199], v207 offset:34816
	ds_read_b128 v[208:211], v207 offset:35840
	ds_read_b128 v[212:215], v207 offset:36864
	ds_read_b128 v[216:219], v207 offset:37888
	ds_read_b128 v[220:223], v207 offset:38912
	ds_read_b128 v[224:227], v207 offset:39936
	global_load_lds_dwordx4 v178, s[72:73]
	s_mov_b32 m0, s31
	s_nop 0
	global_load_lds_dwordx4 v174, s[72:73]
	s_waitcnt vmcnt(8)
	s_waitcnt lgkmcnt(0)
	s_setprio 1
	s_barrier
	v_mfma_f32_16x16x32_bf16 v[128:131], v[132:135], v[188:191], v[128:131]
	v_mfma_f32_16x16x32_bf16 v[124:127], v[140:143], v[188:191], v[124:127]
	v_mfma_f32_16x16x32_bf16 v[120:123], v[132:135], v[196:199], v[120:123]
	v_mfma_f32_16x16x32_bf16 v[116:119], v[140:143], v[196:199], v[116:119]
	v_mfma_f32_16x16x32_bf16 v[112:115], v[132:135], v[212:215], v[112:115]
	v_mfma_f32_16x16x32_bf16 v[108:111], v[140:143], v[212:215], v[108:111]
	v_mfma_f32_16x16x32_bf16 v[104:107], v[132:135], v[220:223], v[104:107]
	v_mfma_f32_16x16x32_bf16 v[100:103], v[140:143], v[220:223], v[100:103]
	v_mfma_f32_16x16x32_bf16 v[128:131], v[136:139], v[192:195], v[128:131]
	v_mfma_f32_16x16x32_bf16 v[124:127], v[144:147], v[192:195], v[124:127]
	v_mfma_f32_16x16x32_bf16 v[120:123], v[136:139], v[208:211], v[120:123]
	v_mfma_f32_16x16x32_bf16 v[116:119], v[144:147], v[208:211], v[116:119]
	v_mfma_f32_16x16x32_bf16 v[112:115], v[136:139], v[216:219], v[112:115]
	v_mfma_f32_16x16x32_bf16 v[108:111], v[144:147], v[216:219], v[108:111]
	v_mfma_f32_16x16x32_bf16 v[104:107], v[136:139], v[224:227], v[104:107]
	v_mfma_f32_16x16x32_bf16 v[100:103], v[144:147], v[224:227], v[100:103]
	v_mfma_f32_16x16x32_bf16 v[96:99], v[148:151], v[188:191], v[96:99]
	v_mfma_f32_16x16x32_bf16 v[92:95], v[156:159], v[188:191], v[92:95]
	v_mfma_f32_16x16x32_bf16 v[88:91], v[148:151], v[196:199], v[88:91]
	v_mfma_f32_16x16x32_bf16 v[84:87], v[156:159], v[196:199], v[84:87]
	v_mfma_f32_16x16x32_bf16 v[80:83], v[148:151], v[212:215], v[80:83]
	v_mfma_f32_16x16x32_bf16 v[76:79], v[156:159], v[212:215], v[76:79]
	v_mfma_f32_16x16x32_bf16 v[72:75], v[148:151], v[220:223], v[72:75]
	v_mfma_f32_16x16x32_bf16 v[68:71], v[156:159], v[220:223], v[68:71]
	v_mfma_f32_16x16x32_bf16 v[96:99], v[152:155], v[192:195], v[96:99]
	v_mfma_f32_16x16x32_bf16 v[92:95], v[184:187], v[192:195], v[92:95]
	v_mfma_f32_16x16x32_bf16 v[88:91], v[152:155], v[208:211], v[88:91]
	v_mfma_f32_16x16x32_bf16 v[84:87], v[184:187], v[208:211], v[84:87]
	v_mfma_f32_16x16x32_bf16 v[80:83], v[152:155], v[216:219], v[80:83]
	v_mfma_f32_16x16x32_bf16 v[76:79], v[184:187], v[216:219], v[76:79]
	v_mfma_f32_16x16x32_bf16 v[72:75], v[152:155], v[224:227], v[72:75]
	v_mfma_f32_16x16x32_bf16 v[68:71], v[184:187], v[224:227], v[68:71]
	s_barrier
	s_setprio 0
	s_add_i32 s72, s75, s4
	v_lshl_add_u64 v[6:7], v[170:171], 0, s[24:25]
	s_mov_b32 m0, s72
	ds_read_b128 v[188:191], v207 offset:49152
	ds_read_b128 v[192:195], v207 offset:50176
	ds_read_b128 v[196:199], v207 offset:51200
	ds_read_b128 v[208:211], v207 offset:52224
	ds_read_b128 v[212:215], v207 offset:53248
	ds_read_b128 v[216:219], v207 offset:54272
	ds_read_b128 v[220:223], v207 offset:55296
	ds_read_b128 v[224:227], v207 offset:56320
	global_load_lds_dwordx4 v[6:7], off
	s_add_i32 m0, s72, 0x2000
	s_add_u32 s72, s84, 0x40080
	v_lshl_add_u64 v[6:7], v[172:173], 0, s[24:25]
	s_addc_u32 s73, s85, 0
	s_add_i32 s75, s76, s4
	global_load_lds_dwordx4 v[6:7], off
	s_mov_b32 m0, s75
	s_nop 0
	global_load_lds_dwordx4 v176, s[72:73]
	s_add_i32 m0, s75, 0x2000
	s_nop 0
	global_load_lds_dwordx4 v160, s[72:73]
	v_lshl_add_u64 v[6:7], v[228:229], 0, s[24:25]
	s_mov_b32 m0, s33
	s_nop 0
	global_load_lds_dwordx4 v[6:7], off
	v_lshl_add_u64 v[6:7], v[230:231], 0, s[24:25]
	s_mov_b32 m0, s38
	s_nop 0
	global_load_lds_dwordx4 v[6:7], off
	s_waitcnt vmcnt(8)
	s_waitcnt lgkmcnt(0)
	s_setprio 1
	s_barrier
	v_mfma_f32_16x16x32_bf16 v[64:67], v[132:135], v[188:191], v[64:67]
	v_mfma_f32_16x16x32_bf16 v[60:63], v[140:143], v[188:191], v[60:63]
	v_mfma_f32_16x16x32_bf16 v[56:59], v[132:135], v[196:199], v[56:59]
	v_mfma_f32_16x16x32_bf16 v[52:55], v[140:143], v[196:199], v[52:55]
	v_mfma_f32_16x16x32_bf16 v[48:51], v[132:135], v[212:215], v[48:51]
	v_mfma_f32_16x16x32_bf16 v[44:47], v[140:143], v[212:215], v[44:47]
	v_mfma_f32_16x16x32_bf16 v[40:43], v[132:135], v[220:223], v[40:43]
	v_mfma_f32_16x16x32_bf16 v[36:39], v[140:143], v[220:223], v[36:39]
	v_mfma_f32_16x16x32_bf16 v[64:67], v[136:139], v[192:195], v[64:67]
	v_mfma_f32_16x16x32_bf16 v[60:63], v[144:147], v[192:195], v[60:63]
	v_mfma_f32_16x16x32_bf16 v[56:59], v[136:139], v[208:211], v[56:59]
	v_mfma_f32_16x16x32_bf16 v[52:55], v[144:147], v[208:211], v[52:55]
	v_mfma_f32_16x16x32_bf16 v[48:51], v[136:139], v[216:219], v[48:51]
	v_mfma_f32_16x16x32_bf16 v[44:47], v[144:147], v[216:219], v[44:47]
	v_mfma_f32_16x16x32_bf16 v[40:43], v[136:139], v[224:227], v[40:43]
	v_mfma_f32_16x16x32_bf16 v[36:39], v[144:147], v[224:227], v[36:39]
	v_mfma_f32_16x16x32_bf16 v[32:35], v[148:151], v[188:191], v[32:35]
	v_mfma_f32_16x16x32_bf16 v[28:31], v[156:159], v[188:191], v[28:31]
	v_mfma_f32_16x16x32_bf16 v[24:27], v[148:151], v[196:199], v[24:27]
	v_mfma_f32_16x16x32_bf16 v[20:23], v[156:159], v[196:199], v[20:23]
	v_mfma_f32_16x16x32_bf16 v[16:19], v[148:151], v[212:215], v[16:19]
	v_mfma_f32_16x16x32_bf16 v[12:15], v[156:159], v[212:215], v[12:15]
	v_mfma_f32_16x16x32_bf16 v[6:9], v[148:151], v[220:223], v[8:11]
	v_mfma_f32_16x16x32_bf16 v[2:5], v[156:159], v[220:223], v[2:5]
	v_mfma_f32_16x16x32_bf16 v[32:35], v[152:155], v[192:195], v[32:35]
	v_mfma_f32_16x16x32_bf16 v[28:31], v[184:187], v[192:195], v[28:31]
	v_mfma_f32_16x16x32_bf16 v[24:27], v[152:155], v[208:211], v[24:27]
	v_mfma_f32_16x16x32_bf16 v[20:23], v[184:187], v[208:211], v[20:23]
	v_mfma_f32_16x16x32_bf16 v[16:19], v[152:155], v[216:219], v[16:19]
	v_mfma_f32_16x16x32_bf16 v[12:15], v[184:187], v[216:219], v[12:15]
	v_mfma_f32_16x16x32_bf16 v[8:11], v[152:155], v[224:227], v[6:9]
	v_mfma_f32_16x16x32_bf16 v[4:7], v[184:187], v[224:227], v[2:5]
	s_barrier
	s_setprio 0
	s_add_u32 s37, s37, 0x100
	s_addc_u32 s49, s49, 0
	s_add_u32 vcc_lo, vcc_lo, 0x100
	s_addc_u32 vcc_hi, vcc_hi, 0
	s_cmp_ge_i32 s74, s3
	s_mov_b32 s72, s74
	s_cbranch_scc0 .LBB7_1104
	s_branch .Lpeelx_1104
	.p2align	6

.Lpeel_1196:
	s_add_i32 s72, s42, 2
	s_add_u32 s29, s16, 0xfffc0080
	s_addc_u32 s37, s17, -1
	s_add_i32 s73, 0, 0x10000
	s_cmp_eq_u32 s55, s42
	s_cselect_b32 s53, s13, s37
	s_cselect_b32 s52, s15, s29
	v_add_u32_e32 v146, s73, v153
	s_cselect_b32 s43, s28, s57
	s_cselect_b32 s42, s39, s56
	s_add_i32 s29, 0, 0x14000
	ds_read_b128 v[130:133], v146
	ds_read_b128 v[156:159], v146 offset:1024
	ds_read_b128 v[174:177], v146 offset:2048
	ds_read_b128 v[178:181], v146 offset:3072
	v_add_u32_e32 v146, s29, v153
	ds_read_b128 v[182:185], v146
	ds_read_b128 v[186:189], v146 offset:1024
	ds_read_b128 v[190:193], v146 offset:2048
	ds_read_b128 v[194:197], v146 offset:3072
	s_add_i32 m0, s5, 0xc000
	ds_read_b128 v[204:207], v161
	ds_read_b128 v[208:211], v161 offset:1024
	ds_read_b128 v[212:215], v161 offset:2048
	ds_read_b128 v[216:219], v161 offset:3072
	ds_read_b128 v[220:223], v161 offset:4096
	ds_read_b128 v[224:227], v161 offset:5120
	ds_read_b128 v[228:231], v161 offset:6144
	ds_read_b128 v[232:235], v161 offset:7168
	global_load_lds_dwordx4 v142, s[16:17]
	s_add_i32 m0, s5, 0xe000
	s_nop 0
	global_load_lds_dwordx4 v144, s[16:17]
	s_waitcnt vmcnt(8)
	s_waitcnt lgkmcnt(0)
	s_setprio 1
	s_barrier
	v_mfma_f32_16x16x32_bf16 v[126:129], v[130:133], v[204:207], 0
	v_mfma_f32_16x16x32_bf16 v[122:125], v[174:177], v[204:207], 0
	v_mfma_f32_16x16x32_bf16 v[110:113], v[130:133], v[212:215], 0
	v_mfma_f32_16x16x32_bf16 v[106:109], v[174:177], v[212:215], 0
	v_mfma_f32_16x16x32_bf16 v[94:97], v[130:133], v[220:223], 0
	v_mfma_f32_16x16x32_bf16 v[90:93], v[174:177], v[220:223], 0
	v_mfma_f32_16x16x32_bf16 v[78:81], v[130:133], v[228:231], 0
	v_mfma_f32_16x16x32_bf16 v[74:77], v[174:177], v[228:231], 0
	v_mfma_f32_16x16x32_bf16 v[126:129], v[156:159], v[208:211], v[126:129]
	v_mfma_f32_16x16x32_bf16 v[122:125], v[178:181], v[208:211], v[122:125]
	v_mfma_f32_16x16x32_bf16 v[110:113], v[156:159], v[216:219], v[110:113]
	v_mfma_f32_16x16x32_bf16 v[106:109], v[178:181], v[216:219], v[106:109]
	v_mfma_f32_16x16x32_bf16 v[94:97], v[156:159], v[224:227], v[94:97]
	v_mfma_f32_16x16x32_bf16 v[90:93], v[178:181], v[224:227], v[90:93]
	v_mfma_f32_16x16x32_bf16 v[78:81], v[156:159], v[232:235], v[78:81]
	v_mfma_f32_16x16x32_bf16 v[74:77], v[178:181], v[232:235], v[74:77]
	v_mfma_f32_16x16x32_bf16 v[118:121], v[182:185], v[204:207], 0
	v_mfma_f32_16x16x32_bf16 v[114:117], v[190:193], v[204:207], 0
	v_mfma_f32_16x16x32_bf16 v[102:105], v[182:185], v[212:215], 0
	v_mfma_f32_16x16x32_bf16 v[98:101], v[190:193], v[212:215], 0
	v_mfma_f32_16x16x32_bf16 v[86:89], v[182:185], v[220:223], 0
	v_mfma_f32_16x16x32_bf16 v[82:85], v[190:193], v[220:223], 0
	v_mfma_f32_16x16x32_bf16 v[70:73], v[182:185], v[228:231], 0
	v_mfma_f32_16x16x32_bf16 v[66:69], v[190:193], v[228:231], 0
	v_mfma_f32_16x16x32_bf16 v[118:121], v[186:189], v[208:211], v[118:121]
	v_mfma_f32_16x16x32_bf16 v[114:117], v[194:197], v[208:211], v[114:117]
	v_mfma_f32_16x16x32_bf16 v[102:105], v[186:189], v[216:219], v[102:105]
	v_mfma_f32_16x16x32_bf16 v[98:101], v[194:197], v[216:219], v[98:101]
	v_mfma_f32_16x16x32_bf16 v[86:89], v[186:189], v[224:227], v[86:89]
	v_mfma_f32_16x16x32_bf16 v[82:85], v[194:197], v[224:227], v[82:85]
	v_mfma_f32_16x16x32_bf16 v[70:73], v[186:189], v[232:235], v[70:73]
	v_mfma_f32_16x16x32_bf16 v[66:69], v[194:197], v[232:235], v[66:69]
	s_barrier
	s_setprio 0
	s_add_i32 s37, s73, s4
	v_lshl_add_u64 v[146:147], s[42:43], 0, v[0:1]
	s_mov_b32 m0, s37
	ds_read_b128 v[204:207], v161 offset:16384
	ds_read_b128 v[208:211], v161 offset:17408
	ds_read_b128 v[212:215], v161 offset:18432
	ds_read_b128 v[216:219], v161 offset:19456
	ds_read_b128 v[220:223], v161 offset:20480
	ds_read_b128 v[224:227], v161 offset:21504
	ds_read_b128 v[228:231], v161 offset:22528
	ds_read_b128 v[232:235], v161 offset:23552
	global_load_lds_dwordx4 v[146:147], off
	s_add_i32 m0, s37, 0x2000
	s_add_u32 s74, s42, 0x40000
	v_lshl_add_u64 v[150:151], s[42:43], 0, v[134:135]
	s_addc_u32 s75, s43, 0
	s_add_i32 s29, s29, s4
	global_load_lds_dwordx4 v[150:151], off
	s_mov_b32 m0, s29
	v_lshl_add_u64 v[172:173], s[52:53], 0, v[136:137]
	global_load_lds_dwordx4 v0, s[74:75]
	s_add_i32 m0, s29, 0x2000
	s_nop 0
	global_load_lds_dwordx4 v134, s[74:75]
	v_lshl_add_u64 v[170:171], s[52:53], 0, v[138:139]
	s_mov_b32 m0, s5
	s_nop 0
	global_load_lds_dwordx4 v[170:171], off
	s_mov_b32 m0, s20
	s_nop 0
	global_load_lds_dwordx4 v[172:173], off
	s_lshl_b32 s101, s10, 14
	s_add_i32 s101, s101, s5
	s_add_u32 s100, s66, s101
	s_addc_u32 s101, s67, 0
	v_lshlrev_b32_e32 v2, 4, v163
	v_add_u32_e32 v3, 0x2000, v2
	s_add_i32 m0, s5, 0x20000
	s_nop 0
	global_load_lds_dwordx4 v2, s[100:101]
	s_add_i32 m0, s5, 0x22000
	s_nop 0
	global_load_lds_dwordx4 v3, s[100:101]
	s_waitcnt vmcnt(8)
	s_waitcnt lgkmcnt(0)
	s_setprio 1
	s_barrier
	v_mfma_f32_16x16x32_bf16 v[62:65], v[130:133], v[204:207], 0
	v_mfma_f32_16x16x32_bf16 v[58:61], v[174:177], v[204:207], 0
	v_mfma_f32_16x16x32_bf16 v[46:49], v[130:133], v[212:215], 0
	v_mfma_f32_16x16x32_bf16 v[42:45], v[174:177], v[212:215], 0
	v_mfma_f32_16x16x32_bf16 v[30:33], v[130:133], v[220:223], 0
	v_mfma_f32_16x16x32_bf16 v[26:29], v[174:177], v[220:223], 0
	v_mfma_f32_16x16x32_bf16 v[14:17], v[130:133], v[228:231], 0
	v_mfma_f32_16x16x32_bf16 v[10:13], v[174:177], v[228:231], 0
	v_mfma_f32_16x16x32_bf16 v[62:65], v[156:159], v[208:211], v[62:65]
	v_mfma_f32_16x16x32_bf16 v[58:61], v[178:181], v[208:211], v[58:61]
	v_mfma_f32_16x16x32_bf16 v[46:49], v[156:159], v[216:219], v[46:49]
	v_mfma_f32_16x16x32_bf16 v[42:45], v[178:181], v[216:219], v[42:45]
	v_mfma_f32_16x16x32_bf16 v[30:33], v[156:159], v[224:227], v[30:33]
	v_mfma_f32_16x16x32_bf16 v[26:29], v[178:181], v[224:227], v[26:29]
	v_mfma_f32_16x16x32_bf16 v[14:17], v[156:159], v[232:235], v[14:17]
	v_mfma_f32_16x16x32_bf16 v[10:13], v[178:181], v[232:235], v[10:13]
	v_mfma_f32_16x16x32_bf16 v[54:57], v[182:185], v[204:207], 0
	v_mfma_f32_16x16x32_bf16 v[50:53], v[190:193], v[204:207], 0
	v_mfma_f32_16x16x32_bf16 v[38:41], v[182:185], v[212:215], 0
	v_mfma_f32_16x16x32_bf16 v[34:37], v[190:193], v[212:215], 0
	v_mfma_f32_16x16x32_bf16 v[22:25], v[182:185], v[220:223], 0
	v_mfma_f32_16x16x32_bf16 v[18:21], v[190:193], v[220:223], 0
	v_mfma_f32_16x16x32_bf16 v[6:9], v[182:185], v[228:231], 0
	v_mfma_f32_16x16x32_bf16 v[2:5], v[190:193], v[228:231], 0
	v_mfma_f32_16x16x32_bf16 v[54:57], v[186:189], v[208:211], v[54:57]
	v_mfma_f32_16x16x32_bf16 v[50:53], v[194:197], v[208:211], v[50:53]
	v_mfma_f32_16x16x32_bf16 v[38:41], v[186:189], v[216:219], v[38:41]
	v_mfma_f32_16x16x32_bf16 v[34:37], v[194:197], v[216:219], v[34:37]
	v_mfma_f32_16x16x32_bf16 v[22:25], v[186:189], v[224:227], v[22:25]
	v_mfma_f32_16x16x32_bf16 v[18:21], v[194:197], v[224:227], v[18:21]
	v_mfma_f32_16x16x32_bf16 v[6:9], v[186:189], v[232:235], v[6:9]
	v_mfma_f32_16x16x32_bf16 v[2:5], v[194:197], v[232:235], v[2:5]
	s_barrier
	s_setprio 0
	s_add_i32 s29, 0, 0x18000
	v_add_u32_e32 v148, s29, v153
	s_add_i32 s37, 0, 0x1c000
	ds_read_b128 v[130:133], v148
	ds_read_b128 v[156:159], v148 offset:1024
	ds_read_b128 v[174:177], v148 offset:2048
	ds_read_b128 v[178:181], v148 offset:3072
	v_add_u32_e32 v148, s37, v153
	ds_read_b128 v[182:185], v148
	ds_read_b128 v[186:189], v148 offset:1024
	ds_read_b128 v[190:193], v148 offset:2048
	ds_read_b128 v[194:197], v148 offset:3072
	s_add_u32 s52, s52, 0x40000
	s_addc_u32 s53, s53, 0
	s_mov_b32 m0, s22
	ds_read_b128 v[204:207], v161 offset:32768
	ds_read_b128 v[208:211], v161 offset:33792
	ds_read_b128 v[212:215], v161 offset:34816
	ds_read_b128 v[216:219], v161 offset:35840
	ds_read_b128 v[220:223], v161 offset:36864
	ds_read_b128 v[224:227], v161 offset:37888
	ds_read_b128 v[228:231], v161 offset:38912
	ds_read_b128 v[232:235], v161 offset:39936
	global_load_lds_dwordx4 v138, s[52:53]
	s_mov_b32 m0, s23
	s_nop 0
	global_load_lds_dwordx4 v136, s[52:53]
	s_waitcnt vmcnt(8)
	s_waitcnt lgkmcnt(0)
	s_setprio 1
	s_barrier
	v_mfma_f32_16x16x32_bf16 v[126:129], v[130:133], v[204:207], v[126:129]
	v_mfma_f32_16x16x32_bf16 v[122:125], v[174:177], v[204:207], v[122:125]
	v_mfma_f32_16x16x32_bf16 v[110:113], v[130:133], v[212:215], v[110:113]
	v_mfma_f32_16x16x32_bf16 v[106:109], v[174:177], v[212:215], v[106:109]
	v_mfma_f32_16x16x32_bf16 v[94:97], v[130:133], v[220:223], v[94:97]
	v_mfma_f32_16x16x32_bf16 v[90:93], v[174:177], v[220:223], v[90:93]
	v_mfma_f32_16x16x32_bf16 v[78:81], v[130:133], v[228:231], v[78:81]
	v_mfma_f32_16x16x32_bf16 v[74:77], v[174:177], v[228:231], v[74:77]
	v_mfma_f32_16x16x32_bf16 v[126:129], v[156:159], v[208:211], v[126:129]
	v_mfma_f32_16x16x32_bf16 v[122:125], v[178:181], v[208:211], v[122:125]
	v_mfma_f32_16x16x32_bf16 v[110:113], v[156:159], v[216:219], v[110:113]
	v_mfma_f32_16x16x32_bf16 v[106:109], v[178:181], v[216:219], v[106:109]
	v_mfma_f32_16x16x32_bf16 v[94:97], v[156:159], v[224:227], v[94:97]
	v_mfma_f32_16x16x32_bf16 v[90:93], v[178:181], v[224:227], v[90:93]
	v_mfma_f32_16x16x32_bf16 v[78:81], v[156:159], v[232:235], v[78:81]
	v_mfma_f32_16x16x32_bf16 v[74:77], v[178:181], v[232:235], v[74:77]
	v_mfma_f32_16x16x32_bf16 v[118:121], v[182:185], v[204:207], v[118:121]
	v_mfma_f32_16x16x32_bf16 v[114:117], v[190:193], v[204:207], v[114:117]
	v_mfma_f32_16x16x32_bf16 v[102:105], v[182:185], v[212:215], v[102:105]
	v_mfma_f32_16x16x32_bf16 v[98:101], v[190:193], v[212:215], v[98:101]
	v_mfma_f32_16x16x32_bf16 v[86:89], v[182:185], v[220:223], v[86:89]
	v_mfma_f32_16x16x32_bf16 v[82:85], v[190:193], v[220:223], v[82:85]
	v_mfma_f32_16x16x32_bf16 v[70:73], v[182:185], v[228:231], v[70:73]
	v_mfma_f32_16x16x32_bf16 v[66:69], v[190:193], v[228:231], v[66:69]
	v_mfma_f32_16x16x32_bf16 v[118:121], v[186:189], v[208:211], v[118:121]
	v_mfma_f32_16x16x32_bf16 v[114:117], v[194:197], v[208:211], v[114:117]
	v_mfma_f32_16x16x32_bf16 v[102:105], v[186:189], v[216:219], v[102:105]
	v_mfma_f32_16x16x32_bf16 v[98:101], v[194:197], v[216:219], v[98:101]
	v_mfma_f32_16x16x32_bf16 v[86:89], v[186:189], v[224:227], v[86:89]
	v_mfma_f32_16x16x32_bf16 v[82:85], v[194:197], v[224:227], v[82:85]
	v_mfma_f32_16x16x32_bf16 v[70:73], v[186:189], v[232:235], v[70:73]
	v_mfma_f32_16x16x32_bf16 v[66:69], v[194:197], v[232:235], v[66:69]
	s_barrier
	s_setprio 0
	s_add_i32 s29, s29, s4
	v_lshl_add_u64 v[146:147], v[146:147], 0, s[24:25]
	s_mov_b32 m0, s29
	ds_read_b128 v[204:207], v161 offset:49152
	ds_read_b128 v[208:211], v161 offset:50176
	ds_read_b128 v[212:215], v161 offset:51200
	ds_read_b128 v[216:219], v161 offset:52224
	ds_read_b128 v[220:223], v161 offset:53248
	ds_read_b128 v[224:227], v161 offset:54272
	ds_read_b128 v[228:231], v161 offset:55296
	ds_read_b128 v[232:235], v161 offset:56320
	global_load_lds_dwordx4 v[146:147], off
	s_add_i32 m0, s29, 0x2000
	s_add_u32 s42, s42, 0x40080
	v_lshl_add_u64 v[146:147], v[150:151], 0, s[24:25]
	s_addc_u32 s43, s43, 0
	s_add_i32 s29, s37, s4
	global_load_lds_dwordx4 v[146:147], off
	s_mov_b32 m0, s29
	s_nop 0
	global_load_lds_dwordx4 v0, s[42:43]
	s_add_i32 m0, s29, 0x2000
	s_nop 0
	global_load_lds_dwordx4 v134, s[42:43]
	v_lshl_add_u64 v[146:147], v[170:171], 0, s[24:25]
	s_mov_b32 m0, s31
	s_nop 0
	global_load_lds_dwordx4 v[146:147], off
	v_lshl_add_u64 v[146:147], v[172:173], 0, s[24:25]
	s_mov_b32 m0, s33
	s_nop 0
	global_load_lds_dwordx4 v[146:147], off
	s_waitcnt vmcnt(8)
	s_waitcnt lgkmcnt(0)
	s_setprio 1
	s_barrier
	v_mfma_f32_16x16x32_bf16 v[62:65], v[130:133], v[204:207], v[62:65]
	v_mfma_f32_16x16x32_bf16 v[58:61], v[174:177], v[204:207], v[58:61]
	v_mfma_f32_16x16x32_bf16 v[46:49], v[130:133], v[212:215], v[46:49]
	v_mfma_f32_16x16x32_bf16 v[42:45], v[174:177], v[212:215], v[42:45]
	v_mfma_f32_16x16x32_bf16 v[30:33], v[130:133], v[220:223], v[30:33]
	v_mfma_f32_16x16x32_bf16 v[26:29], v[174:177], v[220:223], v[26:29]
	v_mfma_f32_16x16x32_bf16 v[14:17], v[130:133], v[228:231], v[14:17]
	v_mfma_f32_16x16x32_bf16 v[10:13], v[174:177], v[228:231], v[10:13]
	v_mfma_f32_16x16x32_bf16 v[62:65], v[156:159], v[208:211], v[62:65]
	v_mfma_f32_16x16x32_bf16 v[58:61], v[178:181], v[208:211], v[58:61]
	v_mfma_f32_16x16x32_bf16 v[46:49], v[156:159], v[216:219], v[46:49]
	v_mfma_f32_16x16x32_bf16 v[42:45], v[178:181], v[216:219], v[42:45]
	v_mfma_f32_16x16x32_bf16 v[30:33], v[156:159], v[224:227], v[30:33]
	v_mfma_f32_16x16x32_bf16 v[26:29], v[178:181], v[224:227], v[26:29]
	v_mfma_f32_16x16x32_bf16 v[14:17], v[156:159], v[232:235], v[14:17]
	v_mfma_f32_16x16x32_bf16 v[10:13], v[178:181], v[232:235], v[10:13]
	v_mfma_f32_16x16x32_bf16 v[54:57], v[182:185], v[204:207], v[54:57]
	v_mfma_f32_16x16x32_bf16 v[50:53], v[190:193], v[204:207], v[50:53]
	v_mfma_f32_16x16x32_bf16 v[38:41], v[182:185], v[212:215], v[38:41]
	v_mfma_f32_16x16x32_bf16 v[34:37], v[190:193], v[212:215], v[34:37]
	v_mfma_f32_16x16x32_bf16 v[22:25], v[182:185], v[220:223], v[22:25]
	v_mfma_f32_16x16x32_bf16 v[18:21], v[190:193], v[220:223], v[18:21]
	v_mfma_f32_16x16x32_bf16 v[6:9], v[182:185], v[228:231], v[6:9]
	v_mfma_f32_16x16x32_bf16 v[2:5], v[190:193], v[228:231], v[2:5]
	v_mfma_f32_16x16x32_bf16 v[54:57], v[186:189], v[208:211], v[54:57]
	v_mfma_f32_16x16x32_bf16 v[50:53], v[194:197], v[208:211], v[50:53]
	v_mfma_f32_16x16x32_bf16 v[38:41], v[186:189], v[216:219], v[38:41]
	v_mfma_f32_16x16x32_bf16 v[34:37], v[194:197], v[216:219], v[34:37]
	v_mfma_f32_16x16x32_bf16 v[22:25], v[186:189], v[224:227], v[22:25]
	v_mfma_f32_16x16x32_bf16 v[18:21], v[194:197], v[224:227], v[18:21]
	v_mfma_f32_16x16x32_bf16 v[6:9], v[186:189], v[232:235], v[6:9]
	v_mfma_f32_16x16x32_bf16 v[2:5], v[194:197], v[232:235], v[2:5]
	s_barrier
	s_setprio 0
	s_add_u32 s16, s16, 0x100
	s_addc_u32 s17, s17, 0
	s_add_u32 s56, s56, 0x100
	s_addc_u32 s57, s57, 0
	s_cmp_ge_i32 s72, s3
	s_mov_b32 s42, s72
	s_cbranch_scc0 .LBB7_1196
	s_branch .Lpeelx_1196
	.p2align	6

.Lpeel_1219:
	s_add_i32 s56, s52, 2
	s_add_u32 s29, s16, 0xfffc0080
	s_addc_u32 s37, s17, -1
	s_add_i32 s57, 0, 0x10000
	s_cmp_eq_u32 s84, s52
	s_cselect_b32 s55, s10, s37
	s_cselect_b32 s54, s13, s29
	s_cselect_b32 s53, s15, s39
	s_cselect_b32 s52, s28, s38
	s_add_i32 s29, 0, 0x14000
	v_add_u32_e32 v152, s57, v157
	v_add_u32_e32 v170, s29, v157
	ds_read_b128 v[140:143], v152
	ds_read_b128 v[144:147], v152 offset:1024
	ds_read_b128 v[148:151], v152 offset:2048
	ds_read_b128 v[152:155], v152 offset:3072
	ds_read_b128 v[184:187], v170
	ds_read_b128 v[188:191], v170 offset:1024
	ds_read_b128 v[192:195], v170 offset:2048
	ds_read_b128 v[196:199], v170 offset:3072
	s_add_i32 m0, s5, 0xc000
	ds_read_b128 v[204:207], v181
	ds_read_b128 v[208:211], v181 offset:1024
	ds_read_b128 v[212:215], v181 offset:2048
	ds_read_b128 v[216:219], v181 offset:3072
	ds_read_b128 v[220:223], v181 offset:4096
	ds_read_b128 v[224:227], v181 offset:5120
	ds_read_b128 v[228:231], v181 offset:6144
	ds_read_b128 v[232:235], v181 offset:7168
	global_load_lds_dwordx4 v136, s[16:17]
	s_add_i32 m0, s5, 0xe000
	s_nop 0
	global_load_lds_dwordx4 v138, s[16:17]
	s_waitcnt vmcnt(8)
	s_waitcnt lgkmcnt(0)
	s_setprio 1
	s_barrier
	v_mfma_f32_16x16x32_bf16 v[126:129], v[140:143], v[204:207], 0
	v_mfma_f32_16x16x32_bf16 v[122:125], v[148:151], v[204:207], 0
	v_mfma_f32_16x16x32_bf16 v[118:121], v[140:143], v[212:215], 0
	v_mfma_f32_16x16x32_bf16 v[114:117], v[148:151], v[212:215], 0
	v_mfma_f32_16x16x32_bf16 v[106:109], v[140:143], v[220:223], 0
	v_mfma_f32_16x16x32_bf16 v[98:101], v[148:151], v[220:223], 0
	v_mfma_f32_16x16x32_bf16 v[90:93], v[140:143], v[228:231], 0
	v_mfma_f32_16x16x32_bf16 v[82:85], v[148:151], v[228:231], 0
	v_mfma_f32_16x16x32_bf16 v[126:129], v[144:147], v[208:211], v[126:129]
	v_mfma_f32_16x16x32_bf16 v[122:125], v[152:155], v[208:211], v[122:125]
	v_mfma_f32_16x16x32_bf16 v[118:121], v[144:147], v[216:219], v[118:121]
	v_mfma_f32_16x16x32_bf16 v[114:117], v[152:155], v[216:219], v[114:117]
	v_mfma_f32_16x16x32_bf16 v[106:109], v[144:147], v[224:227], v[106:109]
	v_mfma_f32_16x16x32_bf16 v[98:101], v[152:155], v[224:227], v[98:101]
	v_mfma_f32_16x16x32_bf16 v[90:93], v[144:147], v[232:235], v[90:93]
	v_mfma_f32_16x16x32_bf16 v[82:85], v[152:155], v[232:235], v[82:85]
	v_mfma_f32_16x16x32_bf16 v[110:113], v[184:187], v[204:207], 0
	v_mfma_f32_16x16x32_bf16 v[102:105], v[192:195], v[204:207], 0
	v_mfma_f32_16x16x32_bf16 v[94:97], v[184:187], v[212:215], 0
	v_mfma_f32_16x16x32_bf16 v[86:89], v[192:195], v[212:215], 0
	v_mfma_f32_16x16x32_bf16 v[78:81], v[184:187], v[220:223], 0
	v_mfma_f32_16x16x32_bf16 v[74:77], v[192:195], v[220:223], 0
	v_mfma_f32_16x16x32_bf16 v[70:73], v[184:187], v[228:231], 0
	v_mfma_f32_16x16x32_bf16 v[66:69], v[192:195], v[228:231], 0
	v_mfma_f32_16x16x32_bf16 v[110:113], v[188:191], v[208:211], v[110:113]
	v_mfma_f32_16x16x32_bf16 v[102:105], v[196:199], v[208:211], v[102:105]
	v_mfma_f32_16x16x32_bf16 v[94:97], v[188:191], v[216:219], v[94:97]
	v_mfma_f32_16x16x32_bf16 v[86:89], v[196:199], v[216:219], v[86:89]
	v_mfma_f32_16x16x32_bf16 v[78:81], v[188:191], v[224:227], v[78:81]
	v_mfma_f32_16x16x32_bf16 v[74:77], v[196:199], v[224:227], v[74:77]
	v_mfma_f32_16x16x32_bf16 v[70:73], v[188:191], v[232:235], v[70:73]
	v_mfma_f32_16x16x32_bf16 v[66:69], v[196:199], v[232:235], v[66:69]
	s_barrier
	s_setprio 0
	s_add_i32 s37, s57, s4
	v_lshl_add_u64 v[170:171], s[52:53], 0, v[0:1]
	s_mov_b32 m0, s37
	ds_read_b128 v[204:207], v181 offset:16384
	ds_read_b128 v[208:211], v181 offset:17408
	ds_read_b128 v[212:215], v181 offset:18432
	ds_read_b128 v[216:219], v181 offset:19456
	ds_read_b128 v[220:223], v181 offset:20480
	ds_read_b128 v[224:227], v181 offset:21504
	ds_read_b128 v[228:231], v181 offset:22528
	ds_read_b128 v[232:235], v181 offset:23552
	global_load_lds_dwordx4 v[170:171], off
	s_add_i32 m0, s37, 0x2000
	s_add_u32 s74, s52, 0x40000
	v_lshl_add_u64 v[172:173], s[52:53], 0, v[130:131]
	s_addc_u32 s75, s53, 0
	s_add_i32 s29, s29, s4
	global_load_lds_dwordx4 v[172:173], off
	s_mov_b32 m0, s29
	v_lshl_add_u64 v[238:239], s[54:55], 0, v[132:133]
	global_load_lds_dwordx4 v0, s[74:75]
	s_add_i32 m0, s29, 0x2000
	s_nop 0
	global_load_lds_dwordx4 v130, s[74:75]
	v_lshl_add_u64 v[236:237], s[54:55], 0, v[134:135]
	s_mov_b32 m0, s5
	s_nop 0
	global_load_lds_dwordx4 v[236:237], off
	s_mov_b32 m0, s20
	s_nop 0
	global_load_lds_dwordx4 v[238:239], off
	s_waitcnt vmcnt(8)
	s_waitcnt lgkmcnt(0)
	s_setprio 1
	s_barrier
	v_mfma_f32_16x16x32_bf16 v[62:65], v[140:143], v[204:207], 0
	v_mfma_f32_16x16x32_bf16 v[58:61], v[148:151], v[204:207], 0
	v_mfma_f32_16x16x32_bf16 v[54:57], v[140:143], v[212:215], 0
	v_mfma_f32_16x16x32_bf16 v[50:53], v[148:151], v[212:215], 0
	v_mfma_f32_16x16x32_bf16 v[42:45], v[140:143], v[220:223], 0
	v_mfma_f32_16x16x32_bf16 v[34:37], v[148:151], v[220:223], 0
	v_mfma_f32_16x16x32_bf16 v[26:29], v[140:143], v[228:231], 0
	v_mfma_f32_16x16x32_bf16 v[18:21], v[148:151], v[228:231], 0
	v_mfma_f32_16x16x32_bf16 v[62:65], v[144:147], v[208:211], v[62:65]
	v_mfma_f32_16x16x32_bf16 v[58:61], v[152:155], v[208:211], v[58:61]
	v_mfma_f32_16x16x32_bf16 v[54:57], v[144:147], v[216:219], v[54:57]
	v_mfma_f32_16x16x32_bf16 v[50:53], v[152:155], v[216:219], v[50:53]
	v_mfma_f32_16x16x32_bf16 v[42:45], v[144:147], v[224:227], v[42:45]
	v_mfma_f32_16x16x32_bf16 v[34:37], v[152:155], v[224:227], v[34:37]
	v_mfma_f32_16x16x32_bf16 v[26:29], v[144:147], v[232:235], v[26:29]
	v_mfma_f32_16x16x32_bf16 v[18:21], v[152:155], v[232:235], v[18:21]
	v_mfma_f32_16x16x32_bf16 v[46:49], v[184:187], v[204:207], 0
	v_mfma_f32_16x16x32_bf16 v[38:41], v[192:195], v[204:207], 0
	v_mfma_f32_16x16x32_bf16 v[30:33], v[184:187], v[212:215], 0
	v_mfma_f32_16x16x32_bf16 v[22:25], v[192:195], v[212:215], 0
	v_mfma_f32_16x16x32_bf16 v[14:17], v[184:187], v[220:223], 0
	v_mfma_f32_16x16x32_bf16 v[10:13], v[192:195], v[220:223], 0
	v_mfma_f32_16x16x32_bf16 v[6:9], v[184:187], v[228:231], 0
	v_mfma_f32_16x16x32_bf16 v[2:5], v[192:195], v[228:231], 0
	v_mfma_f32_16x16x32_bf16 v[46:49], v[188:191], v[208:211], v[46:49]
	v_mfma_f32_16x16x32_bf16 v[38:41], v[196:199], v[208:211], v[38:41]
	v_mfma_f32_16x16x32_bf16 v[30:33], v[188:191], v[216:219], v[30:33]
	v_mfma_f32_16x16x32_bf16 v[22:25], v[196:199], v[216:219], v[22:25]
	v_mfma_f32_16x16x32_bf16 v[14:17], v[188:191], v[224:227], v[14:17]
	v_mfma_f32_16x16x32_bf16 v[10:13], v[196:199], v[224:227], v[10:13]
	v_mfma_f32_16x16x32_bf16 v[6:9], v[188:191], v[232:235], v[6:9]
	v_mfma_f32_16x16x32_bf16 v[2:5], v[196:199], v[232:235], v[2:5]
	s_barrier
	s_setprio 0
	s_add_i32 s29, 0, 0x18000
	s_add_i32 s37, 0, 0x1c000
	v_add_u32_e32 v152, s29, v157
	v_add_u32_e32 v183, s37, v157
	ds_read_b128 v[140:143], v152
	ds_read_b128 v[144:147], v152 offset:1024
	ds_read_b128 v[148:151], v152 offset:2048
	ds_read_b128 v[152:155], v152 offset:3072
	ds_read_b128 v[184:187], v183
	ds_read_b128 v[188:191], v183 offset:1024
	ds_read_b128 v[192:195], v183 offset:2048
	ds_read_b128 v[196:199], v183 offset:3072
	s_add_u32 s54, s54, 0x40000
	s_addc_u32 s55, s55, 0
	s_mov_b32 m0, s22
	ds_read_b128 v[204:207], v181 offset:32768
	ds_read_b128 v[208:211], v181 offset:33792
	ds_read_b128 v[212:215], v181 offset:34816
	ds_read_b128 v[216:219], v181 offset:35840
	ds_read_b128 v[220:223], v181 offset:36864
	ds_read_b128 v[224:227], v181 offset:37888
	ds_read_b128 v[228:231], v181 offset:38912
	ds_read_b128 v[232:235], v181 offset:39936
	global_load_lds_dwordx4 v134, s[54:55]
	s_mov_b32 m0, s23
	s_nop 0
	global_load_lds_dwordx4 v132, s[54:55]
	s_waitcnt vmcnt(8)
	s_waitcnt lgkmcnt(0)
	s_setprio 1
	s_barrier
	v_mfma_f32_16x16x32_bf16 v[126:129], v[140:143], v[204:207], v[126:129]
	v_mfma_f32_16x16x32_bf16 v[122:125], v[148:151], v[204:207], v[122:125]
	v_mfma_f32_16x16x32_bf16 v[118:121], v[140:143], v[212:215], v[118:121]
	v_mfma_f32_16x16x32_bf16 v[114:117], v[148:151], v[212:215], v[114:117]
	v_mfma_f32_16x16x32_bf16 v[106:109], v[140:143], v[220:223], v[106:109]
	v_mfma_f32_16x16x32_bf16 v[98:101], v[148:151], v[220:223], v[98:101]
	v_mfma_f32_16x16x32_bf16 v[90:93], v[140:143], v[228:231], v[90:93]
	v_mfma_f32_16x16x32_bf16 v[82:85], v[148:151], v[228:231], v[82:85]
	v_mfma_f32_16x16x32_bf16 v[126:129], v[144:147], v[208:211], v[126:129]
	v_mfma_f32_16x16x32_bf16 v[122:125], v[152:155], v[208:211], v[122:125]
	v_mfma_f32_16x16x32_bf16 v[118:121], v[144:147], v[216:219], v[118:121]
	v_mfma_f32_16x16x32_bf16 v[114:117], v[152:155], v[216:219], v[114:117]
	v_mfma_f32_16x16x32_bf16 v[106:109], v[144:147], v[224:227], v[106:109]
	v_mfma_f32_16x16x32_bf16 v[98:101], v[152:155], v[224:227], v[98:101]
	v_mfma_f32_16x16x32_bf16 v[90:93], v[144:147], v[232:235], v[90:93]
	v_mfma_f32_16x16x32_bf16 v[82:85], v[152:155], v[232:235], v[82:85]
	v_mfma_f32_16x16x32_bf16 v[110:113], v[184:187], v[204:207], v[110:113]
	v_mfma_f32_16x16x32_bf16 v[102:105], v[192:195], v[204:207], v[102:105]
	v_mfma_f32_16x16x32_bf16 v[94:97], v[184:187], v[212:215], v[94:97]
	v_mfma_f32_16x16x32_bf16 v[86:89], v[192:195], v[212:215], v[86:89]
	v_mfma_f32_16x16x32_bf16 v[78:81], v[184:187], v[220:223], v[78:81]
	v_mfma_f32_16x16x32_bf16 v[74:77], v[192:195], v[220:223], v[74:77]
	v_mfma_f32_16x16x32_bf16 v[70:73], v[184:187], v[228:231], v[70:73]
	v_mfma_f32_16x16x32_bf16 v[66:69], v[192:195], v[228:231], v[66:69]
	v_mfma_f32_16x16x32_bf16 v[110:113], v[188:191], v[208:211], v[110:113]
	v_mfma_f32_16x16x32_bf16 v[102:105], v[196:199], v[208:211], v[102:105]
	v_mfma_f32_16x16x32_bf16 v[94:97], v[188:191], v[216:219], v[94:97]
	v_mfma_f32_16x16x32_bf16 v[86:89], v[196:199], v[216:219], v[86:89]
	v_mfma_f32_16x16x32_bf16 v[78:81], v[188:191], v[224:227], v[78:81]
	v_mfma_f32_16x16x32_bf16 v[74:77], v[196:199], v[224:227], v[74:77]
	v_mfma_f32_16x16x32_bf16 v[70:73], v[188:191], v[232:235], v[70:73]
	v_mfma_f32_16x16x32_bf16 v[66:69], v[196:199], v[232:235], v[66:69]
	s_barrier
	s_setprio 0
	s_add_i32 s29, s29, s4
	v_lshl_add_u64 v[170:171], v[170:171], 0, s[24:25]
	s_mov_b32 m0, s29
	ds_read_b128 v[204:207], v181 offset:49152
	ds_read_b128 v[208:211], v181 offset:50176
	ds_read_b128 v[212:215], v181 offset:51200
	ds_read_b128 v[216:219], v181 offset:52224
	ds_read_b128 v[220:223], v181 offset:53248
	ds_read_b128 v[224:227], v181 offset:54272
	ds_read_b128 v[228:231], v181 offset:55296
	ds_read_b128 v[232:235], v181 offset:56320
	global_load_lds_dwordx4 v[170:171], off
	s_add_i32 m0, s29, 0x2000
	s_add_u32 s52, s52, 0x40080
	v_lshl_add_u64 v[170:171], v[172:173], 0, s[24:25]
	s_addc_u32 s53, s53, 0
	s_add_i32 s29, s37, s4
	global_load_lds_dwordx4 v[170:171], off
	s_mov_b32 m0, s29
	s_nop 0
	global_load_lds_dwordx4 v0, s[52:53]
	s_add_i32 m0, s29, 0x2000
	s_nop 0
	global_load_lds_dwordx4 v130, s[52:53]
	v_lshl_add_u64 v[170:171], v[236:237], 0, s[24:25]
	s_mov_b32 m0, s31
	s_nop 0
	global_load_lds_dwordx4 v[170:171], off
	v_lshl_add_u64 v[170:171], v[238:239], 0, s[24:25]
	s_mov_b32 m0, s33
	s_nop 0
	global_load_lds_dwordx4 v[170:171], off
	s_waitcnt vmcnt(8)
	s_waitcnt lgkmcnt(0)
	s_setprio 1
	s_barrier
	v_mfma_f32_16x16x32_bf16 v[62:65], v[140:143], v[204:207], v[62:65]
	v_mfma_f32_16x16x32_bf16 v[58:61], v[148:151], v[204:207], v[58:61]
	v_mfma_f32_16x16x32_bf16 v[54:57], v[140:143], v[212:215], v[54:57]
	v_mfma_f32_16x16x32_bf16 v[50:53], v[148:151], v[212:215], v[50:53]
	v_mfma_f32_16x16x32_bf16 v[42:45], v[140:143], v[220:223], v[42:45]
	v_mfma_f32_16x16x32_bf16 v[34:37], v[148:151], v[220:223], v[34:37]
	v_mfma_f32_16x16x32_bf16 v[26:29], v[140:143], v[228:231], v[26:29]
	v_mfma_f32_16x16x32_bf16 v[18:21], v[148:151], v[228:231], v[18:21]
	v_mfma_f32_16x16x32_bf16 v[62:65], v[144:147], v[208:211], v[62:65]
	v_mfma_f32_16x16x32_bf16 v[58:61], v[152:155], v[208:211], v[58:61]
	v_mfma_f32_16x16x32_bf16 v[54:57], v[144:147], v[216:219], v[54:57]
	v_mfma_f32_16x16x32_bf16 v[50:53], v[152:155], v[216:219], v[50:53]
	v_mfma_f32_16x16x32_bf16 v[42:45], v[144:147], v[224:227], v[42:45]
	v_mfma_f32_16x16x32_bf16 v[34:37], v[152:155], v[224:227], v[34:37]
	v_mfma_f32_16x16x32_bf16 v[26:29], v[144:147], v[232:235], v[26:29]
	v_mfma_f32_16x16x32_bf16 v[18:21], v[152:155], v[232:235], v[18:21]
	v_mfma_f32_16x16x32_bf16 v[46:49], v[184:187], v[204:207], v[46:49]
	v_mfma_f32_16x16x32_bf16 v[38:41], v[192:195], v[204:207], v[38:41]
	v_mfma_f32_16x16x32_bf16 v[30:33], v[184:187], v[212:215], v[30:33]
	v_mfma_f32_16x16x32_bf16 v[22:25], v[192:195], v[212:215], v[22:25]
	v_mfma_f32_16x16x32_bf16 v[14:17], v[184:187], v[220:223], v[14:17]
	v_mfma_f32_16x16x32_bf16 v[10:13], v[192:195], v[220:223], v[10:13]
	v_mfma_f32_16x16x32_bf16 v[6:9], v[184:187], v[228:231], v[6:9]
	v_mfma_f32_16x16x32_bf16 v[2:5], v[192:195], v[228:231], v[2:5]
	v_mfma_f32_16x16x32_bf16 v[46:49], v[188:191], v[208:211], v[46:49]
	v_mfma_f32_16x16x32_bf16 v[38:41], v[196:199], v[208:211], v[38:41]
	v_mfma_f32_16x16x32_bf16 v[30:33], v[188:191], v[216:219], v[30:33]
	v_mfma_f32_16x16x32_bf16 v[22:25], v[196:199], v[216:219], v[22:25]
	v_mfma_f32_16x16x32_bf16 v[14:17], v[188:191], v[224:227], v[14:17]
	v_mfma_f32_16x16x32_bf16 v[10:13], v[196:199], v[224:227], v[10:13]
	v_mfma_f32_16x16x32_bf16 v[6:9], v[188:191], v[232:235], v[6:9]
	v_mfma_f32_16x16x32_bf16 v[2:5], v[196:199], v[232:235], v[2:5]
	s_barrier
	s_setprio 0
	s_add_u32 s16, s16, 0x100
	s_addc_u32 s17, s17, 0
	s_add_u32 s38, s38, 0x100
	s_addc_u32 s39, s39, 0
	s_cmp_ge_i32 s56, s3
	s_mov_b32 s52, s56
	s_cbranch_scc0 .LBB7_1219
	s_branch .Lpeelx_1219
	.p2align	6

.Lpeel_1274:
	s_add_i32 s72, s50, 2
	s_add_u32 s29, s48, 0xfffc0080
	s_addc_u32 s37, s49, -1
	s_add_i32 s73, 0, 0x10000
	s_cmp_eq_u32 s33, s50
	s_cselect_b32 s53, s13, s37
	s_cselect_b32 s52, s15, s29
	s_cselect_b32 s51, s54, s57
	s_cselect_b32 s50, s55, s56
	s_add_i32 s29, 0, 0x14000
	v_add_u32_e32 v156, s73, v141
	v_add_u32_e32 v160, s29, v141
	ds_read_b128 v[144:147], v156
	ds_read_b128 v[148:151], v156 offset:1024
	ds_read_b128 v[152:155], v156 offset:2048
	ds_read_b128 v[156:159], v156 offset:3072
	ds_read_b128 v[174:177], v160
	ds_read_b128 v[178:181], v160 offset:1024
	ds_read_b128 v[182:185], v160 offset:2048
	ds_read_b128 v[186:189], v160 offset:3072
	s_add_i32 m0, s5, 0xc000
	ds_read_b128 v[190:193], v143
	ds_read_b128 v[194:197], v143 offset:1024
	ds_read_b128 v[204:207], v143 offset:2048
	ds_read_b128 v[208:211], v143 offset:3072
	ds_read_b128 v[212:215], v143 offset:4096
	ds_read_b128 v[216:219], v143 offset:5120
	ds_read_b128 v[220:223], v143 offset:6144
	ds_read_b128 v[224:227], v143 offset:7168
	global_load_lds_dwordx4 v136, s[48:49]
	s_add_i32 m0, s5, 0xe000
	s_nop 0
	global_load_lds_dwordx4 v138, s[48:49]
	s_waitcnt vmcnt(8)
	s_waitcnt lgkmcnt(0)
	s_setprio 1
	s_barrier
	v_mfma_f32_16x16x32_bf16 v[126:129], v[144:147], v[190:193], 0
	v_mfma_f32_16x16x32_bf16 v[122:125], v[152:155], v[190:193], 0
	v_mfma_f32_16x16x32_bf16 v[110:113], v[144:147], v[204:207], 0
	v_mfma_f32_16x16x32_bf16 v[106:109], v[152:155], v[204:207], 0
	v_mfma_f32_16x16x32_bf16 v[94:97], v[144:147], v[212:215], 0
	v_mfma_f32_16x16x32_bf16 v[90:93], v[152:155], v[212:215], 0
	v_mfma_f32_16x16x32_bf16 v[78:81], v[144:147], v[220:223], 0
	v_mfma_f32_16x16x32_bf16 v[74:77], v[152:155], v[220:223], 0
	v_mfma_f32_16x16x32_bf16 v[126:129], v[148:151], v[194:197], v[126:129]
	v_mfma_f32_16x16x32_bf16 v[122:125], v[156:159], v[194:197], v[122:125]
	v_mfma_f32_16x16x32_bf16 v[110:113], v[148:151], v[208:211], v[110:113]
	v_mfma_f32_16x16x32_bf16 v[106:109], v[156:159], v[208:211], v[106:109]
	v_mfma_f32_16x16x32_bf16 v[94:97], v[148:151], v[216:219], v[94:97]
	v_mfma_f32_16x16x32_bf16 v[90:93], v[156:159], v[216:219], v[90:93]
	v_mfma_f32_16x16x32_bf16 v[78:81], v[148:151], v[224:227], v[78:81]
	v_mfma_f32_16x16x32_bf16 v[74:77], v[156:159], v[224:227], v[74:77]
	v_mfma_f32_16x16x32_bf16 v[118:121], v[174:177], v[190:193], 0
	v_mfma_f32_16x16x32_bf16 v[114:117], v[182:185], v[190:193], 0
	v_mfma_f32_16x16x32_bf16 v[102:105], v[174:177], v[204:207], 0
	v_mfma_f32_16x16x32_bf16 v[98:101], v[182:185], v[204:207], 0
	v_mfma_f32_16x16x32_bf16 v[86:89], v[174:177], v[212:215], 0
	v_mfma_f32_16x16x32_bf16 v[82:85], v[182:185], v[212:215], 0
	v_mfma_f32_16x16x32_bf16 v[70:73], v[174:177], v[220:223], 0
	v_mfma_f32_16x16x32_bf16 v[66:69], v[182:185], v[220:223], 0
	v_mfma_f32_16x16x32_bf16 v[118:121], v[178:181], v[194:197], v[118:121]
	v_mfma_f32_16x16x32_bf16 v[114:117], v[186:189], v[194:197], v[114:117]
	v_mfma_f32_16x16x32_bf16 v[102:105], v[178:181], v[208:211], v[102:105]
	v_mfma_f32_16x16x32_bf16 v[98:101], v[186:189], v[208:211], v[98:101]
	v_mfma_f32_16x16x32_bf16 v[86:89], v[178:181], v[216:219], v[86:89]
	v_mfma_f32_16x16x32_bf16 v[82:85], v[186:189], v[216:219], v[82:85]
	v_mfma_f32_16x16x32_bf16 v[70:73], v[178:181], v[224:227], v[70:73]
	v_mfma_f32_16x16x32_bf16 v[66:69], v[186:189], v[224:227], v[66:69]
	s_barrier
	s_setprio 0
	s_add_i32 s37, s73, s4
	v_lshl_add_u64 v[160:161], s[50:51], 0, v[0:1]
	s_mov_b32 m0, s37
	ds_read_b128 v[190:193], v143 offset:16384
	ds_read_b128 v[194:197], v143 offset:17408
	ds_read_b128 v[204:207], v143 offset:18432
	ds_read_b128 v[208:211], v143 offset:19456
	ds_read_b128 v[212:215], v143 offset:20480
	ds_read_b128 v[216:219], v143 offset:21504
	ds_read_b128 v[220:223], v143 offset:22528
	ds_read_b128 v[224:227], v143 offset:23552
	global_load_lds_dwordx4 v[160:161], off
	s_add_i32 m0, s37, 0x2000
	s_add_u32 s74, s50, 0x100000
	v_lshl_add_u64 v[170:171], s[50:51], 0, v[130:131]
	s_addc_u32 s75, s51, 0
	s_add_i32 s29, s29, s4
	global_load_lds_dwordx4 v[170:171], off
	s_mov_b32 m0, s29
	v_lshl_add_u64 v[198:199], s[52:53], 0, v[132:133]
	global_load_lds_dwordx4 v0, s[74:75]
	s_add_i32 m0, s29, 0x2000
	s_nop 0
	global_load_lds_dwordx4 v130, s[74:75]
	v_lshl_add_u64 v[172:173], s[52:53], 0, v[134:135]
	s_mov_b32 m0, s5
	s_nop 0
	global_load_lds_dwordx4 v[172:173], off
	s_mov_b32 m0, s10
	s_nop 0
	global_load_lds_dwordx4 v[198:199], off
	s_waitcnt vmcnt(8)
	s_waitcnt lgkmcnt(0)
	s_setprio 1
	s_barrier
	v_mfma_f32_16x16x32_bf16 v[62:65], v[144:147], v[190:193], 0
	v_mfma_f32_16x16x32_bf16 v[58:61], v[152:155], v[190:193], 0
	v_mfma_f32_16x16x32_bf16 v[46:49], v[144:147], v[204:207], 0
	v_mfma_f32_16x16x32_bf16 v[42:45], v[152:155], v[204:207], 0
	v_mfma_f32_16x16x32_bf16 v[30:33], v[144:147], v[212:215], 0
	v_mfma_f32_16x16x32_bf16 v[26:29], v[152:155], v[212:215], 0
	v_mfma_f32_16x16x32_bf16 v[14:17], v[144:147], v[220:223], 0
	v_mfma_f32_16x16x32_bf16 v[10:13], v[152:155], v[220:223], 0
	v_mfma_f32_16x16x32_bf16 v[62:65], v[148:151], v[194:197], v[62:65]
	v_mfma_f32_16x16x32_bf16 v[58:61], v[156:159], v[194:197], v[58:61]
	v_mfma_f32_16x16x32_bf16 v[46:49], v[148:151], v[208:211], v[46:49]
	v_mfma_f32_16x16x32_bf16 v[42:45], v[156:159], v[208:211], v[42:45]
	v_mfma_f32_16x16x32_bf16 v[30:33], v[148:151], v[216:219], v[30:33]
	v_mfma_f32_16x16x32_bf16 v[26:29], v[156:159], v[216:219], v[26:29]
	v_mfma_f32_16x16x32_bf16 v[14:17], v[148:151], v[224:227], v[14:17]
	v_mfma_f32_16x16x32_bf16 v[10:13], v[156:159], v[224:227], v[10:13]
	v_mfma_f32_16x16x32_bf16 v[54:57], v[174:177], v[190:193], 0
	v_mfma_f32_16x16x32_bf16 v[50:53], v[182:185], v[190:193], 0
	v_mfma_f32_16x16x32_bf16 v[38:41], v[174:177], v[204:207], 0
	v_mfma_f32_16x16x32_bf16 v[34:37], v[182:185], v[204:207], 0
	v_mfma_f32_16x16x32_bf16 v[22:25], v[174:177], v[212:215], 0
	v_mfma_f32_16x16x32_bf16 v[18:21], v[182:185], v[212:215], 0
	v_mfma_f32_16x16x32_bf16 v[6:9], v[174:177], v[220:223], 0
	v_mfma_f32_16x16x32_bf16 v[2:5], v[182:185], v[220:223], 0
	v_mfma_f32_16x16x32_bf16 v[54:57], v[178:181], v[194:197], v[54:57]
	v_mfma_f32_16x16x32_bf16 v[50:53], v[186:189], v[194:197], v[50:53]
	v_mfma_f32_16x16x32_bf16 v[38:41], v[178:181], v[208:211], v[38:41]
	v_mfma_f32_16x16x32_bf16 v[34:37], v[186:189], v[208:211], v[34:37]
	v_mfma_f32_16x16x32_bf16 v[22:25], v[178:181], v[216:219], v[22:25]
	v_mfma_f32_16x16x32_bf16 v[18:21], v[186:189], v[216:219], v[18:21]
	v_mfma_f32_16x16x32_bf16 v[6:9], v[178:181], v[224:227], v[6:9]
	v_mfma_f32_16x16x32_bf16 v[2:5], v[186:189], v[224:227], v[2:5]
	s_barrier
	s_setprio 0
	s_add_i32 s29, 0, 0x18000
	s_add_i32 s37, 0, 0x1c000
	v_add_u32_e32 v156, s29, v141
	v_add_u32_e32 v186, s37, v141
	ds_read_b128 v[144:147], v156
	ds_read_b128 v[148:151], v156 offset:1024
	ds_read_b128 v[152:155], v156 offset:2048
	ds_read_b128 v[156:159], v156 offset:3072
	ds_read_b128 v[174:177], v186
	ds_read_b128 v[178:181], v186 offset:1024
	ds_read_b128 v[182:185], v186 offset:2048
	ds_read_b128 v[186:189], v186 offset:3072
	s_add_u32 s52, s52, 0x40000
	s_addc_u32 s53, s53, 0
	s_mov_b32 m0, s20
	ds_read_b128 v[190:193], v143 offset:32768
	ds_read_b128 v[194:197], v143 offset:33792
	ds_read_b128 v[204:207], v143 offset:34816
	ds_read_b128 v[208:211], v143 offset:35840
	ds_read_b128 v[212:215], v143 offset:36864
	ds_read_b128 v[216:219], v143 offset:37888
	ds_read_b128 v[220:223], v143 offset:38912
	ds_read_b128 v[224:227], v143 offset:39936
	global_load_lds_dwordx4 v134, s[52:53]
	s_mov_b32 m0, s22
	s_nop 0
	global_load_lds_dwordx4 v132, s[52:53]
	s_waitcnt vmcnt(8)
	s_waitcnt lgkmcnt(0)
	s_setprio 1
	s_barrier
	v_mfma_f32_16x16x32_bf16 v[126:129], v[144:147], v[190:193], v[126:129]
	v_mfma_f32_16x16x32_bf16 v[122:125], v[152:155], v[190:193], v[122:125]
	v_mfma_f32_16x16x32_bf16 v[110:113], v[144:147], v[204:207], v[110:113]
	v_mfma_f32_16x16x32_bf16 v[106:109], v[152:155], v[204:207], v[106:109]
	v_mfma_f32_16x16x32_bf16 v[94:97], v[144:147], v[212:215], v[94:97]
	v_mfma_f32_16x16x32_bf16 v[90:93], v[152:155], v[212:215], v[90:93]
	v_mfma_f32_16x16x32_bf16 v[78:81], v[144:147], v[220:223], v[78:81]
	v_mfma_f32_16x16x32_bf16 v[74:77], v[152:155], v[220:223], v[74:77]
	v_mfma_f32_16x16x32_bf16 v[126:129], v[148:151], v[194:197], v[126:129]
	v_mfma_f32_16x16x32_bf16 v[122:125], v[156:159], v[194:197], v[122:125]
	v_mfma_f32_16x16x32_bf16 v[110:113], v[148:151], v[208:211], v[110:113]
	v_mfma_f32_16x16x32_bf16 v[106:109], v[156:159], v[208:211], v[106:109]
	v_mfma_f32_16x16x32_bf16 v[94:97], v[148:151], v[216:219], v[94:97]
	v_mfma_f32_16x16x32_bf16 v[90:93], v[156:159], v[216:219], v[90:93]
	v_mfma_f32_16x16x32_bf16 v[78:81], v[148:151], v[224:227], v[78:81]
	v_mfma_f32_16x16x32_bf16 v[74:77], v[156:159], v[224:227], v[74:77]
	v_mfma_f32_16x16x32_bf16 v[118:121], v[174:177], v[190:193], v[118:121]
	v_mfma_f32_16x16x32_bf16 v[114:117], v[182:185], v[190:193], v[114:117]
	v_mfma_f32_16x16x32_bf16 v[102:105], v[174:177], v[204:207], v[102:105]
	v_mfma_f32_16x16x32_bf16 v[98:101], v[182:185], v[204:207], v[98:101]
	v_mfma_f32_16x16x32_bf16 v[86:89], v[174:177], v[212:215], v[86:89]
	v_mfma_f32_16x16x32_bf16 v[82:85], v[182:185], v[212:215], v[82:85]
	v_mfma_f32_16x16x32_bf16 v[70:73], v[174:177], v[220:223], v[70:73]
	v_mfma_f32_16x16x32_bf16 v[66:69], v[182:185], v[220:223], v[66:69]
	v_mfma_f32_16x16x32_bf16 v[118:121], v[178:181], v[194:197], v[118:121]
	v_mfma_f32_16x16x32_bf16 v[114:117], v[186:189], v[194:197], v[114:117]
	v_mfma_f32_16x16x32_bf16 v[102:105], v[178:181], v[208:211], v[102:105]
	v_mfma_f32_16x16x32_bf16 v[98:101], v[186:189], v[208:211], v[98:101]
	v_mfma_f32_16x16x32_bf16 v[86:89], v[178:181], v[216:219], v[86:89]
	v_mfma_f32_16x16x32_bf16 v[82:85], v[186:189], v[216:219], v[82:85]
	v_mfma_f32_16x16x32_bf16 v[70:73], v[178:181], v[224:227], v[70:73]
	v_mfma_f32_16x16x32_bf16 v[66:69], v[186:189], v[224:227], v[66:69]
	s_barrier
	s_setprio 0
	s_add_i32 s29, s29, s4
	v_lshl_add_u64 v[160:161], v[160:161], 0, s[24:25]
	s_mov_b32 m0, s29
	ds_read_b128 v[190:193], v143 offset:49152
	ds_read_b128 v[194:197], v143 offset:50176
	ds_read_b128 v[204:207], v143 offset:51200
	ds_read_b128 v[208:211], v143 offset:52224
	ds_read_b128 v[212:215], v143 offset:53248
	ds_read_b128 v[216:219], v143 offset:54272
	ds_read_b128 v[220:223], v143 offset:55296
	ds_read_b128 v[224:227], v143 offset:56320
	global_load_lds_dwordx4 v[160:161], off
	s_add_i32 m0, s29, 0x2000
	s_add_u32 s50, s50, 0x100080
	v_lshl_add_u64 v[160:161], v[170:171], 0, s[24:25]
	s_addc_u32 s51, s51, 0
	s_add_i32 s29, s37, s4
	global_load_lds_dwordx4 v[160:161], off
	s_mov_b32 m0, s29
	s_nop 0
	global_load_lds_dwordx4 v0, s[50:51]
	s_add_i32 m0, s29, 0x2000
	s_nop 0
	global_load_lds_dwordx4 v130, s[50:51]
	v_lshl_add_u64 v[160:161], v[172:173], 0, s[24:25]
	s_mov_b32 m0, s23
	s_nop 0
	global_load_lds_dwordx4 v[160:161], off
	v_lshl_add_u64 v[160:161], v[198:199], 0, s[24:25]
	s_mov_b32 m0, s28
	s_nop 0
	global_load_lds_dwordx4 v[160:161], off
	s_waitcnt vmcnt(8)
	s_waitcnt lgkmcnt(0)
	s_setprio 1
	s_barrier
	v_mfma_f32_16x16x32_bf16 v[62:65], v[144:147], v[190:193], v[62:65]
	v_mfma_f32_16x16x32_bf16 v[58:61], v[152:155], v[190:193], v[58:61]
	v_mfma_f32_16x16x32_bf16 v[46:49], v[144:147], v[204:207], v[46:49]
	v_mfma_f32_16x16x32_bf16 v[42:45], v[152:155], v[204:207], v[42:45]
	v_mfma_f32_16x16x32_bf16 v[30:33], v[144:147], v[212:215], v[30:33]
	v_mfma_f32_16x16x32_bf16 v[26:29], v[152:155], v[212:215], v[26:29]
	v_mfma_f32_16x16x32_bf16 v[14:17], v[144:147], v[220:223], v[14:17]
	v_mfma_f32_16x16x32_bf16 v[10:13], v[152:155], v[220:223], v[10:13]
	v_mfma_f32_16x16x32_bf16 v[62:65], v[148:151], v[194:197], v[62:65]
	v_mfma_f32_16x16x32_bf16 v[58:61], v[156:159], v[194:197], v[58:61]
	v_mfma_f32_16x16x32_bf16 v[46:49], v[148:151], v[208:211], v[46:49]
	v_mfma_f32_16x16x32_bf16 v[42:45], v[156:159], v[208:211], v[42:45]
	v_mfma_f32_16x16x32_bf16 v[30:33], v[148:151], v[216:219], v[30:33]
	v_mfma_f32_16x16x32_bf16 v[26:29], v[156:159], v[216:219], v[26:29]
	v_mfma_f32_16x16x32_bf16 v[14:17], v[148:151], v[224:227], v[14:17]
	v_mfma_f32_16x16x32_bf16 v[10:13], v[156:159], v[224:227], v[10:13]
	v_mfma_f32_16x16x32_bf16 v[54:57], v[174:177], v[190:193], v[54:57]
	v_mfma_f32_16x16x32_bf16 v[50:53], v[182:185], v[190:193], v[50:53]
	v_mfma_f32_16x16x32_bf16 v[38:41], v[174:177], v[204:207], v[38:41]
	v_mfma_f32_16x16x32_bf16 v[34:37], v[182:185], v[204:207], v[34:37]
	v_mfma_f32_16x16x32_bf16 v[22:25], v[174:177], v[212:215], v[22:25]
	v_mfma_f32_16x16x32_bf16 v[18:21], v[182:185], v[212:215], v[18:21]
	v_mfma_f32_16x16x32_bf16 v[6:9], v[174:177], v[220:223], v[6:9]
	v_mfma_f32_16x16x32_bf16 v[2:5], v[182:185], v[220:223], v[2:5]
	v_mfma_f32_16x16x32_bf16 v[54:57], v[178:181], v[194:197], v[54:57]
	v_mfma_f32_16x16x32_bf16 v[50:53], v[186:189], v[194:197], v[50:53]
	v_mfma_f32_16x16x32_bf16 v[38:41], v[178:181], v[208:211], v[38:41]
	v_mfma_f32_16x16x32_bf16 v[34:37], v[186:189], v[208:211], v[34:37]
	v_mfma_f32_16x16x32_bf16 v[22:25], v[178:181], v[216:219], v[22:25]
	v_mfma_f32_16x16x32_bf16 v[18:21], v[186:189], v[216:219], v[18:21]
	v_mfma_f32_16x16x32_bf16 v[6:9], v[178:181], v[224:227], v[6:9]
	v_mfma_f32_16x16x32_bf16 v[2:5], v[186:189], v[224:227], v[2:5]
	s_barrier
	s_setprio 0
	s_add_u32 s48, s48, 0x100
	s_addc_u32 s49, s49, 0
	s_add_u32 s56, s56, 0x100
	s_addc_u32 s57, s57, 0
	s_cmp_ge_i32 s72, s3
	s_mov_b32 s50, s72
	s_cbranch_scc0 .LBB7_1274
	s_branch .Lpeelx_1274
	.p2align	6
